# plus phase 12 (E5B) epilogue: o^T loads issued 3 groups ahead with counted waits; silu division via v_rcp_f32
# speedup vs baseline: 1.0418x; 1.0092x over previous
; DI bf16_t f2bf(float x) { return (bf16_t)(cvt_pk(x, 0.f) & 0xffffu); }
; DI float ex2(float x) { return __builtin_amdgcn_exp2f(x); }
; DI size_t vf_off(int item, int dvh, int j) { return ((size_t)((item * 16 + (dvh >> 5)) * 4 + (j >> 4)) * 64 + ((j >> 3) & 1) * 32 + (dvh & 31)) * 8 + (j & 7); }
;     ...
;     } else if (EPI == EPI_E5B) {
;         const u32x2 ov = *(const u32x2*)((const bf16_t*)(p.ws + OFF_VT1) + vf_off((((pos + 48) >> 6) * 4 + b) * 4 + (col >> 9), col & 511, (pos + 48) & 63));
;         bf16_t* d = (bf16_t*)(p.ws + OFF_YB) + (size_t)row0 * 2048 + col;
; #pragma unroll
;         for (int e = 0; e < 4; ++e) {
;             const unsigned ob = (e & 1) ? (ov[e >> 1] & 0xffff0000u) : (ov[e >> 1] << 16);
;             const float o = __uint_as_float(ob);
;             const float gte = v[e] / (1.f + __expf(-v[e]));
;             d[(size_t)e * 2048] = f2bf(gte * o * s_aux[lrow0 + e]);
;         }
; template <int EPI, int K, int LNI = -1>
; DI void ph_gemm(const Params& p, const bf16_t* __restrict__ A, const bf16_t* __restrict__ Bt, int N, float* s_aux) {
;     ...
; #pragma unroll
;             for (int ai = 0; ai < 2; ++ai)
; #pragma unroll
;                 for (int m = 0; m < 4; ++m) {
;                     const int lrow0 = ai * 128 + wr * 64 + m * 16 + fq * 4, row0 = brow + lrow0 + oz;
;                     f32x2 rs[4];
;                     if (EPI == EPI_RESID && LNI >= 0) {
;                         const f32x2* st_ = (const f32x2*)((unsigned char*)p.out + OFFO_STATS) + row0;
; #pragma unroll
;                         for (int e = 0; e < 4; ++e) rs[e] = st_[e];
;                     }
;                     if (EPI == EPI_E5) {
;                         const int idx_ = ((row0 % LT) + 48) & 63; const float lgh = lg_[0][0];
; #pragma unroll
;                         for (int e = 0; e < 4; ++e) rs[e] = (f32x2){ex2(lgh * (float)(idx_ + e + 1)), 0.0625f * ex2(lgh * (float)(63 - idx_ - e))};
;                     }
; #pragma unroll
;                     for (int bj = 0; bj < 2; ++bj)
; #pragma unroll
;                         for (int n = 0; n < 2; ++n) {
;                             float v[4];
; #pragma unroll
;                             for (int e = 0; e < 4; ++e) v[e] = acc[ai][bj][m][n][e];
;                             epi_store<EPI, LNI>(p, row0, bcol + bj * 128 + wc * 32 + n * 16 + fr + oz, lrow0, v, sa, rs, lg_[bj][n], lb_[bj][n]);
.LBB0_1639:
	s_or_b64 exec, exec, s[12:13]
	v_mov_b32_e32 v128, 0
	v_lshl_or_b32 v129, s10, 8, v181
	v_add_u32_e32 v192, s42, v128
	v_add_u32_e32 v148, v129, v128
	v_add_u32_e32 v128, v128, v172
	v_add_u32_e32 v154, v192, v173
	v_and_b32_e32 v191, 31, v128
	v_mul_hi_i32 v128, v154, s68
	v_lshrrev_b32_e32 v129, 31, v128
	v_ashrrev_i32_e32 v128, 12, v128
	v_add_u32_e32 v128, v128, v129
	v_mul_i32_i24_e32 v129, 0xffffdff0, v128
	v_add3_u32 v129, v154, v129, 48
	v_lshrrev_b32_e32 v130, 4, v129
	v_and_b32_e32 v130, 0xfffffc, v130
	v_add_lshl_u32 v198, v130, v128, 8
	v_lshlrev_b32_e32 v128, 2, v129
	v_and_b32_e32 v196, 32, v128
	v_and_b32_e32 v128, 7, v154
	v_lshlrev_b32_e32 v140, 1, v128
	v_ashrrev_i32_e32 v128, 3, v148
	v_bfe_u32 v197, v129, 4, 2
	v_and_b32_e32 v193, 0xffffffc0, v128
	v_lshrrev_b32_e32 v129, 3, v148
	v_add_u32_e32 v128, v198, v193
	v_and_b32_e32 v194, 60, v129
	v_or3_b32 v128, v128, v194, v197
	v_ashrrev_i32_e32 v129, 31, v128
	v_lshlrev_b64 v[128:129], 6, v[128:129]
	v_lshl_add_u64 v[150:151], s[20:21], 0, v[140:141]
	v_or3_b32 v128, v128, v196, v191
	v_lshl_add_u64 v[128:129], v[128:129], 4, v[150:151]
	global_load_dwordx2 v[152:153], v[128:129], off
	v_mul_f32_e32 v128, 0xbfb8aa3b, v124
	v_mul_f32_e32 v129, 0xbfb8aa3b, v125
	v_exp_f32_e32 v140, v128
	v_exp_f32_e32 v156, v129
	v_ashrrev_i32_e32 v149, 31, v148
	v_lshl_add_u32 v195, v173, 2, s11
	v_add_f32_e32 v140, 1.0, v140
	v_lshlrev_b64 v[146:147], 1, v[148:149]
	v_add_f32_e32 v149, 1.0, v156
	v_mul_f32_e32 v130, 0xbfb8aa3b, v126
	v_exp_f32_e32 v157, v130
	s_nop 0
	v_add_f32_e32 v199, 1.0, v157
	ds_read_b128 v[132:135], v195
	ds_read_b128 v[128:131], v195 offset:64
	s_mov_b64 vcc, s[10:11]
	v_ashrrev_i32_e32 v155, 31, v154
	v_rcp_f32_e32 v200, v140
	s_nop 0
	v_mul_f32_e32 v124, v124, v200
	v_lshlrev_b64 v[154:155], 12, v[154:155]
	v_rcp_f32_e32 v140, v149
	s_nop 0
	v_mul_f32_e32 v125, v125, v140
	v_lshl_add_u64 v[154:155], s[36:37], 0, v[154:155]
	v_lshl_add_u64 v[156:157], v[154:155], 0, v[146:147]
	v_add_co_u32_e64 v154, s[14:15], s3, v156
	s_nop 1
	v_addc_co_u32_e64 v155, s[14:15], 0, v157, s[14:15]
	s_mov_b64 vcc, s[12:13]
	s_waitcnt vmcnt(0)
	v_add_u32_e32 v224, 16, v148
	v_ashrrev_i32_e32 v225, 3, v224
	v_and_b32_e32 v225, 0xffffffc0, v225
	v_lshrrev_b32_e32 v226, 3, v224
	v_add_u32_e32 v227, v198, v225
	v_and_b32_e32 v226, 60, v226
	v_or3_b32 v228, v227, v226, v197
	v_ashrrev_i32_e32 v229, 31, v228
	v_lshlrev_b64 v[228:229], 6, v[228:229]
	v_and_b32_e32 v224, 31, v224
	v_or3_b32 v228, v228, v196, v224
	v_lshl_add_u64 v[228:229], v[228:229], 4, v[150:151]
	global_load_dwordx2 v[218:219], v[228:229], off
	v_add_u32_e32 v224, 0x80, v148
	v_ashrrev_i32_e32 v225, 3, v224
	v_and_b32_e32 v225, 0xffffffc0, v225
	v_lshrrev_b32_e32 v224, 3, v224
	v_add_u32_e32 v226, v198, v225
	v_and_b32_e32 v227, 60, v224
	v_or3_b32 v228, v226, v227, v197
	v_ashrrev_i32_e32 v229, 31, v228
	v_lshlrev_b64 v[228:229], 6, v[228:229]
	v_or3_b32 v228, v228, v196, v191
	v_lshl_add_u64 v[228:229], v[228:229], 4, v[150:151]
	global_load_dwordx2 v[220:221], v[228:229], off
	v_add_u32_e32 v224, 0x90, v148
	v_ashrrev_i32_e32 v226, 3, v224
	v_and_b32_e32 v225, 0xffffffc0, v226
	v_lshrrev_b32_e32 v227, 3, v224
	v_add_u32_e32 v226, v198, v225
	v_and_b32_e32 v228, 60, v227
	v_or3_b32 v226, v226, v228, v197
	v_ashrrev_i32_e32 v227, 31, v226
	v_lshlrev_b64 v[226:227], 6, v[226:227]
	v_and_b32_e32 v224, 31, v224
	v_or3_b32 v226, v226, v196, v224
	v_lshl_add_u64 v[226:227], v[226:227], 4, v[150:151]
	global_load_dwordx2 v[222:223], v[226:227], off
	v_lshlrev_b32_e32 v140, 16, v152
	v_and_b32_e32 v149, 0xffff0000, v152
	v_mul_f32_e32 v124, v124, v140
	v_mul_f32_e32 v125, v125, v149
	s_waitcnt lgkmcnt(1)
	v_mul_f32_e32 v124, v132, v124
	v_mul_f32_e32 v125, v133, v125
	v_cvt_pk_bf16_f32 v124, v124, s0
	v_cvt_pk_bf16_f32 v125, v125, s0
	global_store_short v[156:157], v124, off
	global_store_short v[154:155], v125, off offset:-4096
	v_mul_f32_e32 v125, 0xbfb8aa3b, v127
	v_exp_f32_e32 v125, v125
	s_nop 0
	v_add_f32_e32 v125, 1.0, v125
	v_rcp_f32_e32 v124, v199
	s_nop 0
	v_mul_f32_e32 v124, v126, v124
	v_lshlrev_b32_e32 v152, 16, v153
	v_mul_f32_e32 v124, v124, v152
	v_mul_f32_e32 v124, v134, v124
	v_cvt_pk_bf16_f32 v124, v124, s0
	global_store_short v[154:155], v124, off
	v_and_b32_e32 v124, 0xffff0000, v153
	v_rcp_f32_e32 v126, v125
	s_nop 0
	v_mul_f32_e32 v125, v127, v126
	v_mul_f32_e32 v124, v125, v124
	v_mul_f32_e32 v124, v135, v124
	v_cvt_pk_bf16_f32 v126, v124, s0
	v_add_co_u32_e32 v124, vcc, s69, v156
	v_add_u32_e32 v127, 16, v148
	s_nop 0
	v_addc_co_u32_e32 v125, vcc, 0, v157, vcc
	global_store_short v[124:125], v126, off
	v_ashrrev_i32_e32 v126, 3, v127
	v_and_b32_e32 v126, 0xffffffc0, v126
	v_lshrrev_b32_e32 v149, 3, v127
	v_add_u32_e32 v140, v198, v126
	v_and_b32_e32 v149, 60, v149
	v_or3_b32 v152, v140, v149, v197
	v_ashrrev_i32_e32 v153, 31, v152
	v_lshlrev_b64 v[152:153], 6, v[152:153]
	v_and_b32_e32 v127, 31, v127
	v_or3_b32 v152, v152, v196, v127
	v_lshl_add_u64 v[152:153], v[152:153], 4, v[150:151]
	v_mul_f32_e32 v140, 0xbfb8aa3b, v120
	v_exp_f32_e32 v140, v140
	v_mul_f32_e32 v199, 0xbfb8aa3b, v121
	v_exp_f32_e32 v199, v199
	v_add_f32_e32 v140, 1.0, v140
	v_add_f32_e32 v199, 1.0, v199
	v_rcp_f32_e32 v202, v140
	s_nop 0
	v_mul_f32_e32 v120, v120, v202
	v_add_co_u32_e64 v200, s[10:11], s61, v156
	s_waitcnt vmcnt(6)
; DI bf16_t f2bf(float x) { return (bf16_t)(cvt_pk(x, 0.f) & 0xffffu); }
; DI size_t vf_off(int item, int dvh, int j) { return ((size_t)((item * 16 + (dvh >> 5)) * 4 + (j >> 4)) * 64 + ((j >> 3) & 1) * 32 + (dvh & 31)) * 8 + (j & 7); }
;     ...
;     } else if (EPI == EPI_E5B) {
;         const u32x2 ov = *(const u32x2*)((const bf16_t*)(p.ws + OFF_VT1) + vf_off((((pos + 48) >> 6) * 4 + b) * 4 + (col >> 9), col & 511, (pos + 48) & 63));
;         bf16_t* d = (bf16_t*)(p.ws + OFF_YB) + (size_t)row0 * 2048 + col;
; #pragma unroll
;         for (int e = 0; e < 4; ++e) {
;             const unsigned ob = (e & 1) ? (ov[e >> 1] & 0xffff0000u) : (ov[e >> 1] << 16);
;             const float o = __uint_as_float(ob);
;             const float gte = v[e] / (1.f + __expf(-v[e]));
;             d[(size_t)e * 2048] = f2bf(gte * o * s_aux[lrow0 + e]);
;         }
; template <int EPI, int K, int LNI = -1>
; DI void ph_gemm(const Params& p, const bf16_t* __restrict__ A, const bf16_t* __restrict__ Bt, int N, float* s_aux) {
;     ...
; #pragma unroll
;                     for (int bj = 0; bj < 2; ++bj)
; #pragma unroll
;                         for (int n = 0; n < 2; ++n) {
;                             float v[4];
; #pragma unroll
;                             for (int e = 0; e < 4; ++e) v[e] = acc[ai][bj][m][n][e];
;                             epi_store<EPI, LNI>(p, row0, bcol + bj * 128 + wc * 32 + n * 16 + fr + oz, lrow0, v, sa, rs, lg_[bj][n], lb_[bj][n]);
	v_mov_b32_e32 v233, v141
	v_add_u32_e32 v224, v192, v174
	v_mul_hi_i32 v225, v224, s68
	v_lshrrev_b32_e32 v226, 31, v225
	v_ashrrev_i32_e32 v225, 12, v225
	v_add_u32_e32 v225, v225, v226
	v_mul_i32_i24_e32 v226, 0xffffdff0, v225
	v_add3_u32 v226, v224, v226, 48
	v_lshrrev_b32_e32 v227, 4, v226
	v_and_b32_e32 v227, 0xfffffc, v227
	v_add_lshl_u32 v228, v227, v225, 8
	v_lshlrev_b32_e32 v225, 2, v226
	v_and_b32_e32 v229, 32, v225
	v_and_b32_e32 v225, 7, v224
	v_bfe_u32 v230, v226, 4, 2
	v_lshlrev_b32_e32 v232, 1, v225
	v_add_u32_e32 v225, v228, v193
	v_or3_b32 v234, v225, v194, v230
	v_ashrrev_i32_e32 v235, 31, v234
	v_lshlrev_b64 v[234:235], 6, v[234:235]
	v_lshl_add_u64 v[226:227], s[20:21], 0, v[232:233]
	v_or3_b32 v234, v234, v229, v191
	v_lshl_add_u64 v[234:235], v[234:235], 4, v[226:227]
	global_load_dwordx2 v[216:217], v[234:235], off
	v_lshlrev_b32_e32 v140, 16, v218
	v_mul_f32_e32 v120, v120, v140
	v_mul_f32_e32 v120, v132, v120
	v_cvt_pk_bf16_f32 v120, v120, s0
	global_store_short v[156:157], v120, off offset:32
	v_mul_f32_e32 v140, 0xbfb8aa3b, v122
	v_exp_f32_e32 v140, v140
	v_rcp_f32_e32 v120, v199
	s_nop 0
	v_mul_f32_e32 v120, v121, v120
	v_addc_co_u32_e64 v201, s[10:11], 0, v157, s[10:11]
	v_add_f32_e32 v121, 1.0, v140
	v_and_b32_e32 v152, 0xffff0000, v218
	v_mul_f32_e32 v120, v120, v152
	v_mul_f32_e32 v120, v133, v120
	v_cvt_pk_bf16_f32 v120, v120, s0
	global_store_short v[200:201], v120, off offset:32
	v_mul_f32_e32 v152, 0xbfb8aa3b, v123
	v_exp_f32_e32 v152, v152
	v_lshlrev_b32_e32 v120, 16, v219
	v_rcp_f32_e32 v140, v121
	s_nop 0
	v_mul_f32_e32 v121, v122, v140
	v_mul_f32_e32 v120, v121, v120
	v_add_f32_e32 v121, 1.0, v152
	v_mul_f32_e32 v120, v134, v120
	v_cvt_pk_bf16_f32 v120, v120, s0
	global_store_short v[154:155], v120, off offset:32
	v_and_b32_e32 v120, 0xffff0000, v219
	v_rcp_f32_e32 v122, v121
	s_nop 0
	v_mul_f32_e32 v121, v123, v122
	v_mul_f32_e32 v120, v121, v120
	v_mul_f32_e32 v120, v135, v120
	v_cvt_pk_bf16_f32 v120, v120, s0
	global_store_short v[124:125], v120, off offset:32
	v_add_u32_e32 v120, 0x80, v148
	v_ashrrev_i32_e32 v121, 3, v120
	v_and_b32_e32 v121, 0xffffffc0, v121
	v_lshrrev_b32_e32 v120, 3, v120
	v_add_u32_e32 v123, v198, v121
	v_and_b32_e32 v122, 60, v120
	v_or3_b32 v152, v123, v122, v197
	v_ashrrev_i32_e32 v153, 31, v152
	v_lshlrev_b64 v[152:153], 6, v[152:153]
	v_or3_b32 v152, v152, v196, v191
	v_lshl_add_u64 v[152:153], v[152:153], 4, v[150:151]
	v_mul_f32_e32 v120, 0xbfb8aa3b, v116
	v_exp_f32_e32 v120, v120
	s_waitcnt vmcnt(10)
	v_mov_b32_e32 v233, v141
	v_add_u32_e32 v224, v192, v174
	v_mul_hi_i32 v225, v224, s68
	v_lshrrev_b32_e32 v226, 31, v225
	v_ashrrev_i32_e32 v225, 12, v225
	v_add_u32_e32 v225, v225, v226
	v_mul_i32_i24_e32 v226, 0xffffdff0, v225
	v_add3_u32 v226, v224, v226, 48
	v_lshrrev_b32_e32 v227, 4, v226
	v_and_b32_e32 v227, 0xfffffc, v227
	v_add_lshl_u32 v228, v227, v225, 8
	v_lshlrev_b32_e32 v225, 2, v226
	v_and_b32_e32 v229, 32, v225
	v_and_b32_e32 v225, 7, v224
	v_bfe_u32 v230, v226, 4, 2
	v_lshlrev_b32_e32 v232, 1, v225
	v_lshl_add_u64 v[226:227], s[20:21], 0, v[232:233]
	v_add_u32_e32 v234, v228, v126
	v_or3_b32 v234, v234, v149, v230
	v_ashrrev_i32_e32 v235, 31, v234
	v_lshlrev_b64 v[234:235], 6, v[234:235]
	v_or3_b32 v234, v234, v229, v127
	v_lshl_add_u64 v[234:235], v[234:235], 4, v[226:227]
	global_load_dwordx2 v[218:219], v[234:235], off
	v_lshlrev_b32_e32 v204, 16, v220
	v_add_f32_e32 v120, 1.0, v120
	v_mul_f32_e32 v140, 0xbfb8aa3b, v117
	v_exp_f32_e32 v140, v140
	v_rcp_f32_e32 v123, v120
	s_nop 0
	v_mul_f32_e32 v116, v116, v123
	v_mul_f32_e32 v116, v116, v204
	v_mul_f32_e32 v116, v132, v116
	v_add_f32_e32 v120, 1.0, v140
	v_cvt_pk_bf16_f32 v116, v116, s0
	global_store_short v[156:157], v116, off offset:256
	v_and_b32_e32 v116, 0xffff0000, v220
	v_mul_f32_e32 v140, 0xbfb8aa3b, v118
	v_exp_f32_e32 v140, v140
	v_rcp_f32_e32 v123, v120
	s_nop 0
	v_mul_f32_e32 v117, v117, v123
	v_mul_f32_e32 v116, v117, v116
	v_mul_f32_e32 v116, v133, v116
	v_add_f32_e32 v117, 1.0, v140
	v_cvt_pk_bf16_f32 v116, v116, s0
	global_store_short v[200:201], v116, off offset:256
	v_lshlrev_b32_e32 v116, 16, v221
	v_mul_f32_e32 v123, 0xbfb8aa3b, v119
	v_exp_f32_e32 v123, v123
	v_rcp_f32_e32 v120, v117
	s_nop 0
	v_mul_f32_e32 v117, v118, v120
	v_mul_f32_e32 v116, v117, v116
	v_mul_f32_e32 v116, v134, v116
	v_add_f32_e32 v117, 1.0, v123
	v_cvt_pk_bf16_f32 v116, v116, s0
	global_store_short v[154:155], v116, off offset:256
	v_and_b32_e32 v116, 0xffff0000, v221
	v_rcp_f32_e32 v118, v117
	s_nop 0
	v_mul_f32_e32 v117, v119, v118
	v_mul_f32_e32 v116, v117, v116
	v_mul_f32_e32 v116, v135, v116
	v_cvt_pk_bf16_f32 v116, v116, s0
	v_add_u32_e32 v119, 0x90, v148
	global_store_short v[124:125], v116, off offset:256
	v_ashrrev_i32_e32 v116, 3, v119
	v_and_b32_e32 v118, 0xffffffc0, v116
	v_lshrrev_b32_e32 v117, 3, v119
	v_add_u32_e32 v116, v198, v118
	v_and_b32_e32 v120, 60, v117
	v_or3_b32 v116, v116, v120, v197
	v_ashrrev_i32_e32 v117, 31, v116
	v_lshlrev_b64 v[116:117], 6, v[116:117]
	v_and_b32_e32 v119, 31, v119
	v_or3_b32 v116, v116, v196, v119
	v_lshl_add_u64 v[116:117], v[116:117], 4, v[150:151]
	v_mul_f32_e32 v123, 0xbfb8aa3b, v112
	v_exp_f32_e32 v123, v123
	s_waitcnt vmcnt(14)
; DI bf16_t f2bf(float x) { return (bf16_t)(cvt_pk(x, 0.f) & 0xffffu); }
; DI float ex2(float x) { return __builtin_amdgcn_exp2f(x); }
; DI size_t vf_off(int item, int dvh, int j) { return ((size_t)((item * 16 + (dvh >> 5)) * 4 + (j >> 4)) * 64 + ((j >> 3) & 1) * 32 + (dvh & 31)) * 8 + (j & 7); }
;     ...
;     } else if (EPI == EPI_E5B) {
;         const u32x2 ov = *(const u32x2*)((const bf16_t*)(p.ws + OFF_VT1) + vf_off((((pos + 48) >> 6) * 4 + b) * 4 + (col >> 9), col & 511, (pos + 48) & 63));
;         bf16_t* d = (bf16_t*)(p.ws + OFF_YB) + (size_t)row0 * 2048 + col;
; #pragma unroll
;         for (int e = 0; e < 4; ++e) {
;             const unsigned ob = (e & 1) ? (ov[e >> 1] & 0xffff0000u) : (ov[e >> 1] << 16);
;             const float o = __uint_as_float(ob);
;             const float gte = v[e] / (1.f + __expf(-v[e]));
;             d[(size_t)e * 2048] = f2bf(gte * o * s_aux[lrow0 + e]);
;         }
; template <int EPI, int K, int LNI = -1>
; DI void ph_gemm(const Params& p, const bf16_t* __restrict__ A, const bf16_t* __restrict__ Bt, int N, float* s_aux) {
;     ...
; #pragma unroll
;             for (int ai = 0; ai < 2; ++ai)
; #pragma unroll
;                 for (int m = 0; m < 4; ++m) {
;                     const int lrow0 = ai * 128 + wr * 64 + m * 16 + fq * 4, row0 = brow + lrow0 + oz;
;                     f32x2 rs[4];
;                     if (EPI == EPI_RESID && LNI >= 0) {
;                         const f32x2* st_ = (const f32x2*)((unsigned char*)p.out + OFFO_STATS) + row0;
; #pragma unroll
;                         for (int e = 0; e < 4; ++e) rs[e] = st_[e];
;                     }
;                     if (EPI == EPI_E5) {
;                         const int idx_ = ((row0 % LT) + 48) & 63; const float lgh = lg_[0][0];
; #pragma unroll
;                         for (int e = 0; e < 4; ++e) rs[e] = (f32x2){ex2(lgh * (float)(idx_ + e + 1)), 0.0625f * ex2(lgh * (float)(63 - idx_ - e))};
;                     }
; #pragma unroll
;                     for (int bj = 0; bj < 2; ++bj)
; #pragma unroll
;                         for (int n = 0; n < 2; ++n) {
;                             float v[4];
; #pragma unroll
;                             for (int e = 0; e < 4; ++e) v[e] = acc[ai][bj][m][n][e];
;                             epi_store<EPI, LNI>(p, row0, bcol + bj * 128 + wc * 32 + n * 16 + fr + oz, lrow0, v, sa, rs, lg_[bj][n], lb_[bj][n]);
	v_mov_b32_e32 v233, v141
	v_add_u32_e32 v224, v192, v174
	v_mul_hi_i32 v225, v224, s68
	v_lshrrev_b32_e32 v226, 31, v225
	v_ashrrev_i32_e32 v225, 12, v225
	v_add_u32_e32 v225, v225, v226
	v_mul_i32_i24_e32 v226, 0xffffdff0, v225
	v_add3_u32 v226, v224, v226, 48
	v_lshrrev_b32_e32 v227, 4, v226
	v_and_b32_e32 v227, 0xfffffc, v227
	v_add_lshl_u32 v228, v227, v225, 8
	v_lshlrev_b32_e32 v225, 2, v226
	v_and_b32_e32 v229, 32, v225
	v_and_b32_e32 v225, 7, v224
	v_bfe_u32 v230, v226, 4, 2
	v_lshlrev_b32_e32 v232, 1, v225
	v_lshl_add_u64 v[226:227], s[20:21], 0, v[232:233]
	v_add_u32_e32 v234, v228, v121
	v_or3_b32 v234, v234, v122, v230
	v_ashrrev_i32_e32 v235, 31, v234
	v_lshlrev_b64 v[234:235], 6, v[234:235]
	v_or3_b32 v234, v234, v229, v191
	v_lshl_add_u64 v[234:235], v[234:235], 4, v[226:227]
	global_load_dwordx2 v[220:221], v[234:235], off
	v_lshlrev_b32_e32 v150, 16, v222
	v_add_f32_e32 v123, 1.0, v123
	s_nop 0
	v_mul_f32_e32 v148, 0xbfb8aa3b, v113
	v_exp_f32_e32 v148, v148
	v_rcp_f32_e32 v140, v123
	s_nop 0
	v_mul_f32_e32 v112, v112, v140
	v_mul_f32_e32 v112, v112, v150
	v_mul_f32_e32 v112, v132, v112
	v_add_f32_e32 v123, 1.0, v148
	v_cvt_pk_bf16_f32 v112, v112, s0
	global_store_short v[156:157], v112, off offset:288
	v_and_b32_e32 v112, 0xffff0000, v222
	v_mul_f32_e32 v132, 0xbfb8aa3b, v114
	v_exp_f32_e32 v132, v132
	v_rcp_f32_e32 v116, v123
	s_nop 0
	v_mul_f32_e32 v113, v113, v116
	v_mul_f32_e32 v112, v113, v112
	v_add_f32_e32 v113, 1.0, v132
	v_mul_f32_e32 v112, v133, v112
	v_cvt_pk_bf16_f32 v112, v112, s0
	global_store_short v[200:201], v112, off offset:288
	v_mul_f32_e32 v123, 0xbfb8aa3b, v115
	v_exp_f32_e32 v123, v123
	v_lshlrev_b32_e32 v112, 16, v223
	v_rcp_f32_e32 v116, v113
	s_nop 0
	v_mul_f32_e32 v113, v114, v116
	v_mul_f32_e32 v112, v113, v112
	v_add_f32_e32 v113, 1.0, v123
	v_mul_f32_e32 v112, v134, v112
	v_cvt_pk_bf16_f32 v112, v112, s0
	global_store_short v[154:155], v112, off offset:288
	v_and_b32_e32 v112, 0xffff0000, v223
	v_rcp_f32_e32 v114, v113
	s_nop 0
	v_mul_f32_e32 v113, v115, v114
	v_mul_f32_e32 v112, v113, v112
	v_mul_f32_e32 v112, v135, v112
	v_cvt_pk_bf16_f32 v112, v112, s0
	global_store_short v[124:125], v112, off offset:288
	v_add_u32_e32 v112, v192, v174
	v_mul_hi_i32 v113, v112, s68
	v_lshrrev_b32_e32 v114, 31, v113
	v_ashrrev_i32_e32 v113, 12, v113
	v_add_u32_e32 v113, v113, v114
	v_mul_i32_i24_e32 v114, 0xffffdff0, v113
	v_add3_u32 v114, v112, v114, 48
	v_lshrrev_b32_e32 v115, 4, v114
	v_and_b32_e32 v115, 0xfffffc, v115
	v_add_lshl_u32 v123, v115, v113, 8
	v_lshlrev_b32_e32 v113, 2, v114
	v_and_b32_e32 v133, 32, v113
	v_and_b32_e32 v113, 7, v112
	v_bfe_u32 v132, v114, 4, 2
	v_lshlrev_b32_e32 v140, 1, v113
	v_add_u32_e32 v113, v123, v193
	v_or3_b32 v116, v113, v194, v132
	v_ashrrev_i32_e32 v117, 31, v116
	v_lshlrev_b64 v[116:117], 6, v[116:117]
	v_lshl_add_u64 v[114:115], s[20:21], 0, v[140:141]
	v_or3_b32 v116, v116, v133, v191
	v_lshl_add_u64 v[116:117], v[116:117], 4, v[114:115]
	v_mul_f32_e32 v113, 0xbfb8aa3b, v108
	v_exp_f32_e32 v124, v113
	v_ashrrev_i32_e32 v113, 31, v112
	v_lshlrev_b64 v[112:113], 12, v[112:113]
	v_lshl_add_u64 v[112:113], s[36:37], 0, v[112:113]
	v_add_f32_e32 v124, 1.0, v124
	v_lshl_add_u64 v[112:113], v[112:113], 0, v[146:147]
	v_mul_f32_e32 v134, 0xbfb8aa3b, v109
	v_exp_f32_e32 v134, v134
	v_rcp_f32_e32 v125, v124
	s_nop 0
	v_mul_f32_e32 v108, v108, v125
	v_add_f32_e32 v124, 1.0, v134
	s_waitcnt vmcnt(14)
	v_add_u32_e32 v224, v123, v118
	v_or3_b32 v224, v224, v120, v132
	v_ashrrev_i32_e32 v225, 31, v224
	v_lshlrev_b64 v[224:225], 6, v[224:225]
	v_or3_b32 v224, v224, v133, v119
	v_lshl_add_u64 v[224:225], v[224:225], 4, v[114:115]
	global_load_dwordx2 v[222:223], v[224:225], off
	v_lshlrev_b32_e32 v135, 16, v216
	v_mul_f32_e32 v108, v108, v135
	s_waitcnt lgkmcnt(0)
	v_mul_f32_e32 v108, v128, v108
	v_cvt_pk_bf16_f32 v108, v108, s0
	global_store_short v[112:113], v108, off
	v_and_b32_e32 v108, 0xffff0000, v216
	v_rcp_f32_e32 v116, v124
	s_nop 0
	v_mul_f32_e32 v109, v109, v116
	v_mul_f32_e32 v116, 0xbfb8aa3b, v110
	v_exp_f32_e32 v116, v116
	v_mul_f32_e32 v108, v109, v108
	v_mul_f32_e32 v108, v129, v108
	v_cvt_pk_bf16_f32 v124, v108, s0
	v_add_f32_e32 v116, 1.0, v116
	v_add_co_u32_e32 v108, vcc, s3, v112
	s_nop 0
	s_nop 0
	v_addc_co_u32_e32 v109, vcc, 0, v113, vcc
	v_mul_f32_e32 v134, 0xbfb8aa3b, v111
	v_exp_f32_e32 v134, v134
	global_store_short v[108:109], v124, off offset:-4096
	v_lshlrev_b32_e32 v124, 16, v217
	v_rcp_f32_e32 v125, v116
	s_nop 0
	v_mul_f32_e32 v110, v110, v125
	v_add_f32_e32 v116, 1.0, v134
	v_mul_f32_e32 v110, v110, v124
	v_mul_f32_e32 v110, v130, v110
	v_cvt_pk_bf16_f32 v110, v110, s0
	global_store_short v[108:109], v110, off
	v_and_b32_e32 v110, 0xffff0000, v217
	v_rcp_f32_e32 v117, v116
	s_nop 0
	v_mul_f32_e32 v111, v111, v117
	v_mul_f32_e32 v110, v111, v110
	v_mul_f32_e32 v110, v131, v110
	v_cvt_pk_bf16_f32 v116, v110, s0
	v_add_co_u32_e32 v110, vcc, s69, v112
	s_nop 1
	v_addc_co_u32_e32 v111, vcc, 0, v113, vcc
	global_store_short v[110:111], v116, off
	v_add_u32_e32 v116, v123, v126
	v_or3_b32 v116, v116, v149, v132
	v_ashrrev_i32_e32 v117, 31, v116
	v_lshlrev_b64 v[116:117], 6, v[116:117]
	v_or3_b32 v116, v116, v133, v127
	v_lshl_add_u64 v[116:117], v[116:117], 4, v[114:115]
	v_mul_f32_e32 v116, 0xbfb8aa3b, v104
	v_exp_f32_e32 v116, v116
	s_waitcnt vmcnt(14)
; DI bf16_t f2bf(float x) { return (bf16_t)(cvt_pk(x, 0.f) & 0xffffu); }
; DI size_t vf_off(int item, int dvh, int j) { return ((size_t)((item * 16 + (dvh >> 5)) * 4 + (j >> 4)) * 64 + ((j >> 3) & 1) * 32 + (dvh & 31)) * 8 + (j & 7); }
;     ...
;     } else if (EPI == EPI_E5B) {
;         const u32x2 ov = *(const u32x2*)((const bf16_t*)(p.ws + OFF_VT1) + vf_off((((pos + 48) >> 6) * 4 + b) * 4 + (col >> 9), col & 511, (pos + 48) & 63));
;         bf16_t* d = (bf16_t*)(p.ws + OFF_YB) + (size_t)row0 * 2048 + col;
; #pragma unroll
;         for (int e = 0; e < 4; ++e) {
;             const unsigned ob = (e & 1) ? (ov[e >> 1] & 0xffff0000u) : (ov[e >> 1] << 16);
;             const float o = __uint_as_float(ob);
;             const float gte = v[e] / (1.f + __expf(-v[e]));
;             d[(size_t)e * 2048] = f2bf(gte * o * s_aux[lrow0 + e]);
;         }
; template <int EPI, int K, int LNI = -1>
; DI void ph_gemm(const Params& p, const bf16_t* __restrict__ A, const bf16_t* __restrict__ Bt, int N, float* s_aux) {
;     ...
; #pragma unroll
;                     for (int bj = 0; bj < 2; ++bj)
; #pragma unroll
;                         for (int n = 0; n < 2; ++n) {
;                             float v[4];
; #pragma unroll
;                             for (int e = 0; e < 4; ++e) v[e] = acc[ai][bj][m][n][e];
;                             epi_store<EPI, LNI>(p, row0, bcol + bj * 128 + wc * 32 + n * 16 + fr + oz, lrow0, v, sa, rs, lg_[bj][n], lb_[bj][n]);
	v_mov_b32_e32 v233, v141
	v_add_u32_e32 v224, v192, v175
	v_mul_hi_i32 v225, v224, s68
	v_lshrrev_b32_e32 v226, 31, v225
	v_ashrrev_i32_e32 v225, 12, v225
	v_add_u32_e32 v225, v225, v226
	v_mul_i32_i24_e32 v226, 0xffffdff0, v225
	v_add3_u32 v226, v224, v226, 48
	v_lshrrev_b32_e32 v227, 4, v226
	v_and_b32_e32 v227, 0xfffffc, v227
	v_add_lshl_u32 v228, v227, v225, 8
	v_lshlrev_b32_e32 v225, 2, v226
	v_and_b32_e32 v229, 32, v225
	v_and_b32_e32 v225, 7, v224
	v_bfe_u32 v230, v226, 4, 2
	v_lshlrev_b32_e32 v232, 1, v225
	v_add_u32_e32 v225, v228, v193
	v_or3_b32 v226, v225, v194, v230
	v_ashrrev_i32_e32 v227, 31, v226
	v_lshlrev_b64 v[226:227], 6, v[226:227]
	v_lshl_add_u64 v[234:235], s[20:21], 0, v[232:233]
	v_or3_b32 v226, v226, v229, v191
	v_lshl_add_u64 v[226:227], v[226:227], 4, v[234:235]
	global_load_dwordx2 v[216:217], v[226:227], off
	v_lshlrev_b32_e32 v148, 16, v218
	v_add_f32_e32 v134, 1.0, v116
	v_add_co_u32_e32 v116, vcc, s61, v112
	s_nop 0
	s_nop 0
	v_addc_co_u32_e32 v117, vcc, 0, v113, vcc
	v_mul_f32_e32 v140, 0xbfb8aa3b, v105
	v_exp_f32_e32 v140, v140
	v_rcp_f32_e32 v135, v134
	s_nop 0
	v_mul_f32_e32 v104, v104, v135
	v_mul_f32_e32 v104, v104, v148
	v_mul_f32_e32 v104, v128, v104
	v_add_f32_e32 v134, 1.0, v140
	v_cvt_pk_bf16_f32 v104, v104, s0
	global_store_short v[112:113], v104, off offset:32
	v_and_b32_e32 v104, 0xffff0000, v218
	v_mul_f32_e32 v135, 0xbfb8aa3b, v106
	v_exp_f32_e32 v135, v135
	v_rcp_f32_e32 v124, v134
	s_nop 0
	v_mul_f32_e32 v105, v105, v124
	v_mul_f32_e32 v104, v105, v104
	v_add_f32_e32 v105, 1.0, v135
	v_mul_f32_e32 v104, v129, v104
	v_cvt_pk_bf16_f32 v104, v104, s0
	global_store_short v[116:117], v104, off offset:32
	v_mul_f32_e32 v134, 0xbfb8aa3b, v107
	v_exp_f32_e32 v134, v134
	v_lshlrev_b32_e32 v104, 16, v219
	v_rcp_f32_e32 v124, v105
	s_nop 0
	v_mul_f32_e32 v105, v106, v124
	v_mul_f32_e32 v104, v105, v104
	v_add_f32_e32 v105, 1.0, v134
	v_mul_f32_e32 v104, v130, v104
	v_cvt_pk_bf16_f32 v104, v104, s0
	global_store_short v[108:109], v104, off offset:32
	v_and_b32_e32 v104, 0xffff0000, v219
	v_rcp_f32_e32 v106, v105
	s_nop 0
	v_mul_f32_e32 v105, v107, v106
	v_mul_f32_e32 v104, v105, v104
	v_mul_f32_e32 v104, v131, v104
	v_cvt_pk_bf16_f32 v104, v104, s0
	global_store_short v[110:111], v104, off offset:32
	v_add_u32_e32 v104, v123, v121
	v_or3_b32 v104, v104, v122, v132
	v_ashrrev_i32_e32 v105, 31, v104
	v_lshlrev_b64 v[104:105], 6, v[104:105]
	v_or3_b32 v104, v104, v133, v191
	v_lshl_add_u64 v[104:105], v[104:105], 4, v[114:115]
	v_mul_f32_e32 v106, 0xbfb8aa3b, v100
	v_exp_f32_e32 v106, v106
	s_waitcnt vmcnt(14)
	v_mov_b32_e32 v233, v141
	v_add_u32_e32 v224, v192, v175
	v_mul_hi_i32 v225, v224, s68
	v_lshrrev_b32_e32 v226, 31, v225
	v_ashrrev_i32_e32 v225, 12, v225
	v_add_u32_e32 v225, v225, v226
	v_mul_i32_i24_e32 v226, 0xffffdff0, v225
	v_add3_u32 v226, v224, v226, 48
	v_lshrrev_b32_e32 v227, 4, v226
	v_and_b32_e32 v227, 0xfffffc, v227
	v_add_lshl_u32 v228, v227, v225, 8
	v_lshlrev_b32_e32 v225, 2, v226
	v_and_b32_e32 v229, 32, v225
	v_and_b32_e32 v225, 7, v224
	v_bfe_u32 v230, v226, 4, 2
	v_lshlrev_b32_e32 v232, 1, v225
	v_lshl_add_u64 v[234:235], s[20:21], 0, v[232:233]
	v_add_u32_e32 v236, v228, v126
	v_or3_b32 v236, v236, v149, v230
	v_ashrrev_i32_e32 v237, 31, v236
	v_lshlrev_b64 v[236:237], 6, v[236:237]
	v_or3_b32 v236, v236, v229, v127
	v_lshl_add_u64 v[236:237], v[236:237], 4, v[234:235]
	global_load_dwordx2 v[218:219], v[236:237], off
	v_lshlrev_b32_e32 v125, 16, v220
	v_add_f32_e32 v106, 1.0, v106
	s_nop 0
	v_mul_f32_e32 v124, 0xbfb8aa3b, v101
	v_exp_f32_e32 v124, v124
	v_rcp_f32_e32 v107, v106
	s_nop 0
	v_mul_f32_e32 v100, v100, v107
	v_mul_f32_e32 v100, v100, v125
	v_mul_f32_e32 v100, v128, v100
	v_add_f32_e32 v106, 1.0, v124
	v_cvt_pk_bf16_f32 v100, v100, s0
	global_store_short v[112:113], v100, off offset:256
	v_and_b32_e32 v100, 0xffff0000, v220
	v_mul_f32_e32 v107, 0xbfb8aa3b, v102
	v_exp_f32_e32 v107, v107
	v_rcp_f32_e32 v104, v106
	s_nop 0
	v_mul_f32_e32 v101, v101, v104
	v_mul_f32_e32 v100, v101, v100
	v_add_f32_e32 v101, 1.0, v107
	v_mul_f32_e32 v100, v129, v100
	v_cvt_pk_bf16_f32 v100, v100, s0
	global_store_short v[116:117], v100, off offset:256
	v_mul_f32_e32 v106, 0xbfb8aa3b, v103
	v_exp_f32_e32 v106, v106
	v_lshlrev_b32_e32 v100, 16, v221
	v_rcp_f32_e32 v104, v101
	s_nop 0
	v_mul_f32_e32 v101, v102, v104
	v_mul_f32_e32 v100, v101, v100
	v_add_f32_e32 v101, 1.0, v106
	v_mul_f32_e32 v100, v130, v100
	v_cvt_pk_bf16_f32 v100, v100, s0
	global_store_short v[108:109], v100, off offset:256
	v_and_b32_e32 v100, 0xffff0000, v221
	v_rcp_f32_e32 v102, v101
	s_nop 0
	v_mul_f32_e32 v101, v103, v102
	v_mul_f32_e32 v100, v101, v100
	v_mul_f32_e32 v100, v131, v100
	v_cvt_pk_bf16_f32 v100, v100, s0
	global_store_short v[110:111], v100, off offset:256
	v_add_u32_e32 v100, v123, v118
	v_or3_b32 v100, v100, v120, v132
	v_ashrrev_i32_e32 v101, 31, v100
	v_lshlrev_b64 v[100:101], 6, v[100:101]
	v_or3_b32 v100, v100, v133, v119
	v_lshl_add_u64 v[100:101], v[100:101], 4, v[114:115]
	v_mul_f32_e32 v102, 0xbfb8aa3b, v96
	v_exp_f32_e32 v102, v102
	s_waitcnt vmcnt(14)
; DI bf16_t f2bf(float x) { return (bf16_t)(cvt_pk(x, 0.f) & 0xffffu); }
; DI float ex2(float x) { return __builtin_amdgcn_exp2f(x); }
; DI size_t vf_off(int item, int dvh, int j) { return ((size_t)((item * 16 + (dvh >> 5)) * 4 + (j >> 4)) * 64 + ((j >> 3) & 1) * 32 + (dvh & 31)) * 8 + (j & 7); }
;     ...
;     } else if (EPI == EPI_E5B) {
;         const u32x2 ov = *(const u32x2*)((const bf16_t*)(p.ws + OFF_VT1) + vf_off((((pos + 48) >> 6) * 4 + b) * 4 + (col >> 9), col & 511, (pos + 48) & 63));
;         bf16_t* d = (bf16_t*)(p.ws + OFF_YB) + (size_t)row0 * 2048 + col;
; #pragma unroll
;         for (int e = 0; e < 4; ++e) {
;             const unsigned ob = (e & 1) ? (ov[e >> 1] & 0xffff0000u) : (ov[e >> 1] << 16);
;             const float o = __uint_as_float(ob);
;             const float gte = v[e] / (1.f + __expf(-v[e]));
;             d[(size_t)e * 2048] = f2bf(gte * o * s_aux[lrow0 + e]);
;         }
; template <int EPI, int K, int LNI = -1>
; DI void ph_gemm(const Params& p, const bf16_t* __restrict__ A, const bf16_t* __restrict__ Bt, int N, float* s_aux) {
;     ...
; #pragma unroll
;             for (int ai = 0; ai < 2; ++ai)
; #pragma unroll
;                 for (int m = 0; m < 4; ++m) {
;                     const int lrow0 = ai * 128 + wr * 64 + m * 16 + fq * 4, row0 = brow + lrow0 + oz;
;                     f32x2 rs[4];
;                     if (EPI == EPI_RESID && LNI >= 0) {
;                         const f32x2* st_ = (const f32x2*)((unsigned char*)p.out + OFFO_STATS) + row0;
; #pragma unroll
;                         for (int e = 0; e < 4; ++e) rs[e] = st_[e];
;                     }
;                     if (EPI == EPI_E5) {
;                         const int idx_ = ((row0 % LT) + 48) & 63; const float lgh = lg_[0][0];
; #pragma unroll
;                         for (int e = 0; e < 4; ++e) rs[e] = (f32x2){ex2(lgh * (float)(idx_ + e + 1)), 0.0625f * ex2(lgh * (float)(63 - idx_ - e))};
;                     }
; #pragma unroll
;                     for (int bj = 0; bj < 2; ++bj)
; #pragma unroll
;                         for (int n = 0; n < 2; ++n) {
;                             float v[4];
; #pragma unroll
;                             for (int e = 0; e < 4; ++e) v[e] = acc[ai][bj][m][n][e];
;                             epi_store<EPI, LNI>(p, row0, bcol + bj * 128 + wc * 32 + n * 16 + fr + oz, lrow0, v, sa, rs, lg_[bj][n], lb_[bj][n]);
	v_mov_b32_e32 v233, v141
	v_add_u32_e32 v224, v192, v175
	v_mul_hi_i32 v225, v224, s68
	v_lshrrev_b32_e32 v226, 31, v225
	v_ashrrev_i32_e32 v225, 12, v225
	v_add_u32_e32 v225, v225, v226
	v_mul_i32_i24_e32 v226, 0xffffdff0, v225
	v_add3_u32 v226, v224, v226, 48
	v_lshrrev_b32_e32 v227, 4, v226
	v_and_b32_e32 v227, 0xfffffc, v227
	v_add_lshl_u32 v228, v227, v225, 8
	v_lshlrev_b32_e32 v225, 2, v226
	v_and_b32_e32 v229, 32, v225
	v_and_b32_e32 v225, 7, v224
	v_bfe_u32 v230, v226, 4, 2
	v_lshlrev_b32_e32 v232, 1, v225
	v_lshl_add_u64 v[234:235], s[20:21], 0, v[232:233]
	v_add_u32_e32 v236, v228, v121
	v_or3_b32 v236, v236, v122, v230
	v_ashrrev_i32_e32 v237, 31, v236
	v_lshlrev_b64 v[236:237], 6, v[236:237]
	v_or3_b32 v236, v236, v229, v191
	v_lshl_add_u64 v[236:237], v[236:237], 4, v[234:235]
	global_load_dwordx2 v[220:221], v[236:237], off
	v_lshlrev_b32_e32 v105, 16, v222
	v_add_f32_e32 v102, 1.0, v102
	s_nop 0
	v_mul_f32_e32 v104, 0xbfb8aa3b, v97
	v_exp_f32_e32 v104, v104
	v_rcp_f32_e32 v103, v102
	s_nop 0
	v_mul_f32_e32 v96, v96, v103
	v_mul_f32_e32 v96, v96, v105
	v_mul_f32_e32 v96, v128, v96
	v_add_f32_e32 v102, 1.0, v104
	v_cvt_pk_bf16_f32 v96, v96, s0
	global_store_short v[112:113], v96, off offset:288
	v_and_b32_e32 v96, 0xffff0000, v222
	v_mul_f32_e32 v103, 0xbfb8aa3b, v98
	v_exp_f32_e32 v103, v103
	v_rcp_f32_e32 v100, v102
	s_nop 0
	v_mul_f32_e32 v97, v97, v100
	v_mul_f32_e32 v96, v97, v96
	v_add_f32_e32 v97, 1.0, v103
	v_mul_f32_e32 v96, v129, v96
	v_cvt_pk_bf16_f32 v96, v96, s0
	global_store_short v[116:117], v96, off offset:288
	v_mul_f32_e32 v102, 0xbfb8aa3b, v99
	v_exp_f32_e32 v102, v102
	v_lshlrev_b32_e32 v96, 16, v223
	v_rcp_f32_e32 v100, v97
	s_nop 0
	v_mul_f32_e32 v97, v98, v100
	v_mul_f32_e32 v96, v97, v96
	v_add_f32_e32 v97, 1.0, v102
	v_mul_f32_e32 v96, v130, v96
	v_cvt_pk_bf16_f32 v96, v96, s0
	global_store_short v[108:109], v96, off offset:288
	v_and_b32_e32 v96, 0xffff0000, v223
	v_rcp_f32_e32 v98, v97
	s_nop 0
	v_mul_f32_e32 v97, v99, v98
	v_mul_f32_e32 v96, v97, v96
	v_mul_f32_e32 v96, v131, v96
	v_cvt_pk_bf16_f32 v96, v96, s0
	global_store_short v[110:111], v96, off offset:288
	v_add_u32_e32 v96, v192, v175
	v_mul_hi_i32 v97, v96, s68
	v_lshrrev_b32_e32 v98, 31, v97
	v_ashrrev_i32_e32 v97, 12, v97
	v_add_u32_e32 v97, v97, v98
	v_mul_i32_i24_e32 v98, 0xffffdff0, v97
	v_add3_u32 v98, v96, v98, 48
	v_lshrrev_b32_e32 v99, 4, v98
	v_and_b32_e32 v99, 0xfffffc, v99
	v_add_lshl_u32 v111, v99, v97, 8
	v_lshlrev_b32_e32 v97, 2, v98
	v_and_b32_e32 v110, 32, v97
	v_and_b32_e32 v97, 7, v96
	v_bfe_u32 v112, v98, 4, 2
	v_lshlrev_b32_e32 v140, 1, v97
	v_add_u32_e32 v97, v111, v193
	v_or3_b32 v98, v97, v194, v112
	v_ashrrev_i32_e32 v99, 31, v98
	v_lshlrev_b64 v[98:99], 6, v[98:99]
	v_lshl_add_u64 v[104:105], s[20:21], 0, v[140:141]
	v_or3_b32 v98, v98, v110, v191
	v_lshl_add_u64 v[98:99], v[98:99], 4, v[104:105]
	v_mul_f32_e32 v97, 0xbfb8aa3b, v92
	v_exp_f32_e32 v98, v97
	v_ashrrev_i32_e32 v97, 31, v96
	v_lshlrev_b64 v[96:97], 12, v[96:97]
	v_lshl_add_u64 v[96:97], s[36:37], 0, v[96:97]
	v_add_f32_e32 v98, 1.0, v98
	v_lshl_add_u64 v[106:107], v[96:97], 0, v[146:147]
	ds_read_b128 v[100:103], v195 offset:128
	v_rcp_f32_e32 v97, v98
	s_nop 0
	v_mul_f32_e32 v92, v92, v97
	v_mul_f32_e32 v97, 0xbfb8aa3b, v93
	v_exp_f32_e32 v113, v97
	s_waitcnt vmcnt(14)
	v_add_u32_e32 v224, v111, v118
	v_or3_b32 v224, v224, v120, v112
	v_ashrrev_i32_e32 v225, 31, v224
	v_lshlrev_b64 v[224:225], 6, v[224:225]
	v_or3_b32 v224, v224, v110, v119
	v_lshl_add_u64 v[224:225], v[224:225], 4, v[104:105]
	global_load_dwordx2 v[222:223], v[224:225], off
	v_lshlrev_b32_e32 v96, 16, v216
	v_add_f32_e32 v113, 1.0, v113
	v_mul_f32_e32 v92, v92, v96
	ds_read_b128 v[96:99], v195 offset:192
	s_waitcnt lgkmcnt(1)
	v_mul_f32_e32 v92, v100, v92
	v_cvt_pk_bf16_f32 v92, v92, s0
	global_store_short v[106:107], v92, off
	v_and_b32_e32 v92, 0xffff0000, v216
	v_rcp_f32_e32 v108, v113
	s_nop 0
	v_mul_f32_e32 v93, v93, v108
	v_mul_f32_e32 v108, 0xbfb8aa3b, v94
	v_exp_f32_e32 v108, v108
	v_mul_f32_e32 v92, v93, v92
	v_mul_f32_e32 v92, v101, v92
	v_cvt_pk_bf16_f32 v113, v92, s0
	v_add_f32_e32 v108, 1.0, v108
	v_add_co_u32_e32 v92, vcc, s3, v106
	s_nop 0
	s_nop 0
	v_addc_co_u32_e32 v93, vcc, 0, v107, vcc
	v_mul_f32_e32 v115, 0xbfb8aa3b, v95
	v_exp_f32_e32 v115, v115
	global_store_short v[92:93], v113, off offset:-4096
	v_lshlrev_b32_e32 v113, 16, v217
	v_rcp_f32_e32 v114, v108
	s_nop 0
	v_mul_f32_e32 v94, v94, v114
	v_add_f32_e32 v108, 1.0, v115
	v_mul_f32_e32 v94, v94, v113
	v_mul_f32_e32 v94, v102, v94
	v_cvt_pk_bf16_f32 v94, v94, s0
	global_store_short v[92:93], v94, off
	v_and_b32_e32 v94, 0xffff0000, v217
	v_rcp_f32_e32 v109, v108
	s_nop 0
	v_mul_f32_e32 v95, v95, v109
	v_mul_f32_e32 v94, v95, v94
	v_mul_f32_e32 v94, v103, v94
	v_cvt_pk_bf16_f32 v108, v94, s0
	v_add_co_u32_e32 v94, vcc, s69, v106
	v_mul_f32_e32 v113, 0xbfb8aa3b, v88
	s_nop 0
	v_addc_co_u32_e32 v95, vcc, 0, v107, vcc
	global_store_short v[94:95], v108, off
	v_add_u32_e32 v108, v111, v126
	v_or3_b32 v108, v108, v149, v112
	v_ashrrev_i32_e32 v109, 31, v108
	v_lshlrev_b64 v[108:109], 6, v[108:109]
	v_or3_b32 v108, v108, v110, v127
	v_lshl_add_u64 v[108:109], v[108:109], 4, v[104:105]
	v_exp_f32_e32 v113, v113
	v_add_co_u32_e32 v114, vcc, s61, v106
	v_add_f32_e32 v113, 1.0, v113
	s_nop 0
	v_addc_co_u32_e32 v115, vcc, 0, v107, vcc
	v_mul_f32_e32 v117, 0xbfb8aa3b, v89
	v_exp_f32_e32 v117, v117
	v_rcp_f32_e32 v116, v113
	s_nop 0
	v_mul_f32_e32 v88, v88, v116
	v_add_f32_e32 v113, 1.0, v117
	s_waitcnt vmcnt(14)
; DI bf16_t f2bf(float x) { return (bf16_t)(cvt_pk(x, 0.f) & 0xffffu); }
; DI size_t vf_off(int item, int dvh, int j) { return ((size_t)((item * 16 + (dvh >> 5)) * 4 + (j >> 4)) * 64 + ((j >> 3) & 1) * 32 + (dvh & 31)) * 8 + (j & 7); }
;     ...
;     } else if (EPI == EPI_E5B) {
;         const u32x2 ov = *(const u32x2*)((const bf16_t*)(p.ws + OFF_VT1) + vf_off((((pos + 48) >> 6) * 4 + b) * 4 + (col >> 9), col & 511, (pos + 48) & 63));
;         bf16_t* d = (bf16_t*)(p.ws + OFF_YB) + (size_t)row0 * 2048 + col;
; #pragma unroll
;         for (int e = 0; e < 4; ++e) {
;             const unsigned ob = (e & 1) ? (ov[e >> 1] & 0xffff0000u) : (ov[e >> 1] << 16);
;             const float o = __uint_as_float(ob);
;             const float gte = v[e] / (1.f + __expf(-v[e]));
;             d[(size_t)e * 2048] = f2bf(gte * o * s_aux[lrow0 + e]);
;         }
; template <int EPI, int K, int LNI = -1>
; DI void ph_gemm(const Params& p, const bf16_t* __restrict__ A, const bf16_t* __restrict__ Bt, int N, float* s_aux) {
;     ...
; #pragma unroll
;                     for (int bj = 0; bj < 2; ++bj)
; #pragma unroll
;                         for (int n = 0; n < 2; ++n) {
;                             float v[4];
; #pragma unroll
;                             for (int e = 0; e < 4; ++e) v[e] = acc[ai][bj][m][n][e];
;                             epi_store<EPI, LNI>(p, row0, bcol + bj * 128 + wc * 32 + n * 16 + fr + oz, lrow0, v, sa, rs, lg_[bj][n], lb_[bj][n]);
	v_mov_b32_e32 v233, v141
	v_add_u32_e32 v224, v192, v176
	v_mul_hi_i32 v225, v224, s68
	v_lshrrev_b32_e32 v226, 31, v225
	v_ashrrev_i32_e32 v225, 12, v225
	v_add_u32_e32 v225, v225, v226
	v_mul_i32_i24_e32 v226, 0xffffdff0, v225
	v_add3_u32 v226, v224, v226, 48
	v_lshrrev_b32_e32 v227, 4, v226
	v_and_b32_e32 v227, 0xfffffc, v227
	v_add_lshl_u32 v228, v227, v225, 8
	v_lshlrev_b32_e32 v225, 2, v226
	v_and_b32_e32 v229, 32, v225
	v_and_b32_e32 v225, 7, v224
	v_bfe_u32 v230, v226, 4, 2
	v_lshlrev_b32_e32 v232, 1, v225
	v_add_u32_e32 v225, v228, v193
	v_or3_b32 v234, v225, v194, v230
	v_ashrrev_i32_e32 v235, 31, v234
	v_lshlrev_b64 v[234:235], 6, v[234:235]
	v_lshl_add_u64 v[226:227], s[20:21], 0, v[232:233]
	v_or3_b32 v234, v234, v229, v191
	v_lshl_add_u64 v[234:235], v[234:235], 4, v[226:227]
	global_load_dwordx2 v[216:217], v[234:235], off
	v_lshlrev_b32_e32 v123, 16, v218
	v_mul_f32_e32 v88, v88, v123
	v_mul_f32_e32 v88, v100, v88
	v_cvt_pk_bf16_f32 v88, v88, s0
	global_store_short v[106:107], v88, off offset:32
	v_and_b32_e32 v88, 0xffff0000, v218
	v_mul_f32_e32 v116, 0xbfb8aa3b, v90
	v_exp_f32_e32 v116, v116
	v_rcp_f32_e32 v108, v113
	s_nop 0
	v_mul_f32_e32 v89, v89, v108
	v_mul_f32_e32 v88, v89, v88
	v_add_f32_e32 v89, 1.0, v116
	v_mul_f32_e32 v88, v101, v88
	v_cvt_pk_bf16_f32 v88, v88, s0
	global_store_short v[114:115], v88, off offset:32
	v_mul_f32_e32 v113, 0xbfb8aa3b, v91
	v_exp_f32_e32 v113, v113
	v_lshlrev_b32_e32 v88, 16, v219
	v_rcp_f32_e32 v108, v89
	s_nop 0
	v_mul_f32_e32 v89, v90, v108
	v_mul_f32_e32 v88, v89, v88
	v_add_f32_e32 v89, 1.0, v113
	v_mul_f32_e32 v88, v102, v88
	v_cvt_pk_bf16_f32 v88, v88, s0
	global_store_short v[92:93], v88, off offset:32
	v_and_b32_e32 v88, 0xffff0000, v219
	v_rcp_f32_e32 v90, v89
	s_nop 0
	v_mul_f32_e32 v89, v91, v90
	v_mul_f32_e32 v88, v89, v88
	v_mul_f32_e32 v88, v103, v88
	v_cvt_pk_bf16_f32 v88, v88, s0
	global_store_short v[94:95], v88, off offset:32
	v_add_u32_e32 v88, v111, v121
	v_or3_b32 v88, v88, v122, v112
	v_ashrrev_i32_e32 v89, 31, v88
	v_lshlrev_b64 v[88:89], 6, v[88:89]
	v_or3_b32 v88, v88, v110, v191
	v_lshl_add_u64 v[88:89], v[88:89], 4, v[104:105]
	v_mul_f32_e32 v90, 0xbfb8aa3b, v84
	v_exp_f32_e32 v90, v90
	s_waitcnt vmcnt(14)
	v_mov_b32_e32 v233, v141
	v_add_u32_e32 v224, v192, v176
	v_mul_hi_i32 v225, v224, s68
	v_lshrrev_b32_e32 v226, 31, v225
	v_ashrrev_i32_e32 v225, 12, v225
	v_add_u32_e32 v225, v225, v226
	v_mul_i32_i24_e32 v226, 0xffffdff0, v225
	v_add3_u32 v226, v224, v226, 48
	v_lshrrev_b32_e32 v227, 4, v226
	v_and_b32_e32 v227, 0xfffffc, v227
	v_add_lshl_u32 v228, v227, v225, 8
	v_lshlrev_b32_e32 v225, 2, v226
	v_and_b32_e32 v229, 32, v225
	v_and_b32_e32 v225, 7, v224
	v_bfe_u32 v230, v226, 4, 2
	v_lshlrev_b32_e32 v232, 1, v225
	v_lshl_add_u64 v[226:227], s[20:21], 0, v[232:233]
	v_add_u32_e32 v234, v228, v126
	v_or3_b32 v234, v234, v149, v230
	v_ashrrev_i32_e32 v235, 31, v234
	v_lshlrev_b64 v[234:235], 6, v[234:235]
	v_or3_b32 v234, v234, v229, v127
	v_lshl_add_u64 v[234:235], v[234:235], 4, v[226:227]
	global_load_dwordx2 v[218:219], v[234:235], off
	v_lshlrev_b32_e32 v109, 16, v220
	v_add_f32_e32 v90, 1.0, v90
	s_nop 0
	v_mul_f32_e32 v108, 0xbfb8aa3b, v85
	v_exp_f32_e32 v108, v108
	v_rcp_f32_e32 v91, v90
	s_nop 0
	v_mul_f32_e32 v84, v84, v91
	v_mul_f32_e32 v84, v84, v109
	v_mul_f32_e32 v84, v100, v84
	v_add_f32_e32 v90, 1.0, v108
	v_cvt_pk_bf16_f32 v84, v84, s0
	global_store_short v[106:107], v84, off offset:256
	v_and_b32_e32 v84, 0xffff0000, v220
	v_mul_f32_e32 v91, 0xbfb8aa3b, v86
	v_exp_f32_e32 v91, v91
	v_rcp_f32_e32 v88, v90
	s_nop 0
	v_mul_f32_e32 v85, v85, v88
	v_mul_f32_e32 v84, v85, v84
	v_add_f32_e32 v85, 1.0, v91
	v_mul_f32_e32 v84, v101, v84
	v_cvt_pk_bf16_f32 v84, v84, s0
	global_store_short v[114:115], v84, off offset:256
	v_mul_f32_e32 v90, 0xbfb8aa3b, v87
	v_exp_f32_e32 v90, v90
	v_lshlrev_b32_e32 v84, 16, v221
	v_rcp_f32_e32 v88, v85
	s_nop 0
	v_mul_f32_e32 v85, v86, v88
	v_mul_f32_e32 v84, v85, v84
	v_add_f32_e32 v85, 1.0, v90
	v_mul_f32_e32 v84, v102, v84
	v_cvt_pk_bf16_f32 v84, v84, s0
	global_store_short v[92:93], v84, off offset:256
	v_and_b32_e32 v84, 0xffff0000, v221
	v_rcp_f32_e32 v86, v85
	s_nop 0
	v_mul_f32_e32 v85, v87, v86
	v_mul_f32_e32 v84, v85, v84
	v_mul_f32_e32 v84, v103, v84
	v_cvt_pk_bf16_f32 v84, v84, s0
	global_store_short v[94:95], v84, off offset:256
	v_add_u32_e32 v84, v111, v118
	v_or3_b32 v84, v84, v120, v112
	v_ashrrev_i32_e32 v85, 31, v84
	v_lshlrev_b64 v[84:85], 6, v[84:85]
	v_or3_b32 v84, v84, v110, v119
	v_lshl_add_u64 v[84:85], v[84:85], 4, v[104:105]
	v_mul_f32_e32 v86, 0xbfb8aa3b, v80
	v_exp_f32_e32 v86, v86
	s_waitcnt vmcnt(14)
; DI bf16_t f2bf(float x) { return (bf16_t)(cvt_pk(x, 0.f) & 0xffffu); }
; DI float ex2(float x) { return __builtin_amdgcn_exp2f(x); }
; DI size_t vf_off(int item, int dvh, int j) { return ((size_t)((item * 16 + (dvh >> 5)) * 4 + (j >> 4)) * 64 + ((j >> 3) & 1) * 32 + (dvh & 31)) * 8 + (j & 7); }
;     ...
;     } else if (EPI == EPI_E5B) {
;         const u32x2 ov = *(const u32x2*)((const bf16_t*)(p.ws + OFF_VT1) + vf_off((((pos + 48) >> 6) * 4 + b) * 4 + (col >> 9), col & 511, (pos + 48) & 63));
;         bf16_t* d = (bf16_t*)(p.ws + OFF_YB) + (size_t)row0 * 2048 + col;
; #pragma unroll
;         for (int e = 0; e < 4; ++e) {
;             const unsigned ob = (e & 1) ? (ov[e >> 1] & 0xffff0000u) : (ov[e >> 1] << 16);
;             const float o = __uint_as_float(ob);
;             const float gte = v[e] / (1.f + __expf(-v[e]));
;             d[(size_t)e * 2048] = f2bf(gte * o * s_aux[lrow0 + e]);
;         }
; template <int EPI, int K, int LNI = -1>
; DI void ph_gemm(const Params& p, const bf16_t* __restrict__ A, const bf16_t* __restrict__ Bt, int N, float* s_aux) {
;     ...
; #pragma unroll
;             for (int ai = 0; ai < 2; ++ai)
; #pragma unroll
;                 for (int m = 0; m < 4; ++m) {
;                     const int lrow0 = ai * 128 + wr * 64 + m * 16 + fq * 4, row0 = brow + lrow0 + oz;
;                     f32x2 rs[4];
;                     if (EPI == EPI_RESID && LNI >= 0) {
;                         const f32x2* st_ = (const f32x2*)((unsigned char*)p.out + OFFO_STATS) + row0;
; #pragma unroll
;                         for (int e = 0; e < 4; ++e) rs[e] = st_[e];
;                     }
;                     if (EPI == EPI_E5) {
;                         const int idx_ = ((row0 % LT) + 48) & 63; const float lgh = lg_[0][0];
; #pragma unroll
;                         for (int e = 0; e < 4; ++e) rs[e] = (f32x2){ex2(lgh * (float)(idx_ + e + 1)), 0.0625f * ex2(lgh * (float)(63 - idx_ - e))};
;                     }
; #pragma unroll
;                     for (int bj = 0; bj < 2; ++bj)
; #pragma unroll
;                         for (int n = 0; n < 2; ++n) {
;                             float v[4];
; #pragma unroll
;                             for (int e = 0; e < 4; ++e) v[e] = acc[ai][bj][m][n][e];
;                             epi_store<EPI, LNI>(p, row0, bcol + bj * 128 + wc * 32 + n * 16 + fr + oz, lrow0, v, sa, rs, lg_[bj][n], lb_[bj][n]);
	v_mov_b32_e32 v233, v141
	v_add_u32_e32 v224, v192, v176
	v_mul_hi_i32 v225, v224, s68
	v_lshrrev_b32_e32 v226, 31, v225
	v_ashrrev_i32_e32 v225, 12, v225
	v_add_u32_e32 v225, v225, v226
	v_mul_i32_i24_e32 v226, 0xffffdff0, v225
	v_add3_u32 v226, v224, v226, 48
	v_lshrrev_b32_e32 v227, 4, v226
	v_and_b32_e32 v227, 0xfffffc, v227
	v_add_lshl_u32 v228, v227, v225, 8
	v_lshlrev_b32_e32 v225, 2, v226
	v_and_b32_e32 v229, 32, v225
	v_and_b32_e32 v225, 7, v224
	v_bfe_u32 v230, v226, 4, 2
	v_lshlrev_b32_e32 v232, 1, v225
	v_lshl_add_u64 v[226:227], s[20:21], 0, v[232:233]
	v_add_u32_e32 v234, v228, v121
	v_or3_b32 v234, v234, v122, v230
	v_ashrrev_i32_e32 v235, 31, v234
	v_lshlrev_b64 v[234:235], 6, v[234:235]
	v_or3_b32 v234, v234, v229, v191
	v_lshl_add_u64 v[234:235], v[234:235], 4, v[226:227]
	global_load_dwordx2 v[220:221], v[234:235], off
	v_lshlrev_b32_e32 v89, 16, v222
	v_add_f32_e32 v86, 1.0, v86
	s_nop 0
	v_mul_f32_e32 v88, 0xbfb8aa3b, v81
	v_exp_f32_e32 v88, v88
	v_rcp_f32_e32 v87, v86
	s_nop 0
	v_mul_f32_e32 v80, v80, v87
	v_mul_f32_e32 v80, v80, v89
	v_mul_f32_e32 v80, v100, v80
	v_add_f32_e32 v86, 1.0, v88
	v_cvt_pk_bf16_f32 v80, v80, s0
	global_store_short v[106:107], v80, off offset:288
	v_and_b32_e32 v80, 0xffff0000, v222
	v_mul_f32_e32 v87, 0xbfb8aa3b, v82
	v_exp_f32_e32 v87, v87
	v_rcp_f32_e32 v84, v86
	s_nop 0
	v_mul_f32_e32 v81, v81, v84
	v_mul_f32_e32 v80, v81, v80
	v_add_f32_e32 v81, 1.0, v87
	v_mul_f32_e32 v80, v101, v80
	v_cvt_pk_bf16_f32 v80, v80, s0
	global_store_short v[114:115], v80, off offset:288
	v_mul_f32_e32 v86, 0xbfb8aa3b, v83
	v_exp_f32_e32 v86, v86
	v_lshlrev_b32_e32 v80, 16, v223
	v_rcp_f32_e32 v84, v81
	s_nop 0
	v_mul_f32_e32 v81, v82, v84
	v_mul_f32_e32 v80, v81, v80
	v_add_f32_e32 v81, 1.0, v86
	v_mul_f32_e32 v80, v102, v80
	v_cvt_pk_bf16_f32 v80, v80, s0
	global_store_short v[92:93], v80, off offset:288
	v_and_b32_e32 v80, 0xffff0000, v223
	v_rcp_f32_e32 v82, v81
	s_nop 0
	v_mul_f32_e32 v81, v83, v82
	v_mul_f32_e32 v80, v81, v80
	v_mul_f32_e32 v80, v103, v80
	v_cvt_pk_bf16_f32 v80, v80, s0
	global_store_short v[94:95], v80, off offset:288
	v_add_u32_e32 v80, v192, v176
	v_mul_hi_i32 v81, v80, s68
	v_lshrrev_b32_e32 v82, 31, v81
	v_ashrrev_i32_e32 v81, 12, v81
	v_add_u32_e32 v81, v81, v82
	v_mul_i32_i24_e32 v82, 0xffffdff0, v81
	v_add3_u32 v82, v80, v82, 48
	v_lshrrev_b32_e32 v83, 4, v82
	v_and_b32_e32 v83, 0xfffffc, v83
	v_add_lshl_u32 v88, v83, v81, 8
	v_lshlrev_b32_e32 v81, 2, v82
	v_and_b32_e32 v90, 32, v81
	v_and_b32_e32 v81, 7, v80
	v_bfe_u32 v89, v82, 4, 2
	v_lshlrev_b32_e32 v140, 1, v81
	v_add_u32_e32 v81, v88, v193
	v_or3_b32 v84, v81, v194, v89
	v_ashrrev_i32_e32 v85, 31, v84
	v_lshlrev_b64 v[84:85], 6, v[84:85]
	v_lshl_add_u64 v[82:83], s[20:21], 0, v[140:141]
	v_or3_b32 v84, v84, v90, v191
	v_lshl_add_u64 v[84:85], v[84:85], 4, v[82:83]
	v_mul_f32_e32 v81, 0xbfb8aa3b, v76
	v_exp_f32_e32 v86, v81
	v_ashrrev_i32_e32 v81, 31, v80
	v_lshlrev_b64 v[80:81], 12, v[80:81]
	v_lshl_add_u64 v[80:81], s[36:37], 0, v[80:81]
	v_add_f32_e32 v86, 1.0, v86
	v_lshl_add_u64 v[80:81], v[80:81], 0, v[146:147]
	v_mul_f32_e32 v91, 0xbfb8aa3b, v77
	v_exp_f32_e32 v91, v91
	v_rcp_f32_e32 v87, v86
	s_nop 0
	v_mul_f32_e32 v76, v76, v87
	v_add_f32_e32 v86, 1.0, v91
	s_waitcnt vmcnt(14)
	v_add_u32_e32 v224, v88, v118
	v_or3_b32 v224, v224, v120, v89
	v_ashrrev_i32_e32 v225, 31, v224
	v_lshlrev_b64 v[224:225], 6, v[224:225]
	v_or3_b32 v224, v224, v90, v119
	v_lshl_add_u64 v[224:225], v[224:225], 4, v[82:83]
	global_load_dwordx2 v[222:223], v[224:225], off
	v_lshlrev_b32_e32 v92, 16, v216
	v_mul_f32_e32 v76, v76, v92
	s_waitcnt lgkmcnt(0)
	v_mul_f32_e32 v76, v96, v76
	v_cvt_pk_bf16_f32 v76, v76, s0
	global_store_short v[80:81], v76, off
	v_and_b32_e32 v76, 0xffff0000, v216
	v_rcp_f32_e32 v84, v86
	s_nop 0
	v_mul_f32_e32 v77, v77, v84
	v_mul_f32_e32 v84, 0xbfb8aa3b, v78
	v_exp_f32_e32 v84, v84
	v_mul_f32_e32 v76, v77, v76
	v_mul_f32_e32 v76, v97, v76
	v_cvt_pk_bf16_f32 v86, v76, s0
	v_add_f32_e32 v84, 1.0, v84
	v_add_co_u32_e32 v76, vcc, s3, v80
	s_nop 0
	s_nop 0
	v_addc_co_u32_e32 v77, vcc, 0, v81, vcc
	v_mul_f32_e32 v91, 0xbfb8aa3b, v79
	v_exp_f32_e32 v91, v91
	global_store_short v[76:77], v86, off offset:-4096
	v_lshlrev_b32_e32 v86, 16, v217
	v_rcp_f32_e32 v87, v84
	s_nop 0
	v_mul_f32_e32 v78, v78, v87
	v_add_f32_e32 v84, 1.0, v91
	v_mul_f32_e32 v78, v78, v86
	v_mul_f32_e32 v78, v98, v78
	v_cvt_pk_bf16_f32 v78, v78, s0
	global_store_short v[76:77], v78, off
	v_and_b32_e32 v78, 0xffff0000, v217
	v_rcp_f32_e32 v85, v84
	s_nop 0
	v_mul_f32_e32 v79, v79, v85
	v_mul_f32_e32 v78, v79, v78
	v_mul_f32_e32 v78, v99, v78
	v_cvt_pk_bf16_f32 v84, v78, s0
	v_add_co_u32_e32 v78, vcc, s69, v80
	s_nop 1
	v_addc_co_u32_e32 v79, vcc, 0, v81, vcc
	global_store_short v[78:79], v84, off
	v_add_u32_e32 v84, v88, v126
	v_or3_b32 v84, v84, v149, v89
	v_ashrrev_i32_e32 v85, 31, v84
	v_lshlrev_b64 v[84:85], 6, v[84:85]
	v_or3_b32 v84, v84, v90, v127
	v_lshl_add_u64 v[84:85], v[84:85], 4, v[82:83]
	v_mul_f32_e32 v84, 0xbfb8aa3b, v72
	v_exp_f32_e32 v84, v84
	s_waitcnt vmcnt(14)
; DI bf16_t f2bf(float x) { return (bf16_t)(cvt_pk(x, 0.f) & 0xffffu); }
; DI size_t vf_off(int item, int dvh, int j) { return ((size_t)((item * 16 + (dvh >> 5)) * 4 + (j >> 4)) * 64 + ((j >> 3) & 1) * 32 + (dvh & 31)) * 8 + (j & 7); }
;     ...
;     } else if (EPI == EPI_E5B) {
;         const u32x2 ov = *(const u32x2*)((const bf16_t*)(p.ws + OFF_VT1) + vf_off((((pos + 48) >> 6) * 4 + b) * 4 + (col >> 9), col & 511, (pos + 48) & 63));
;         bf16_t* d = (bf16_t*)(p.ws + OFF_YB) + (size_t)row0 * 2048 + col;
; #pragma unroll
;         for (int e = 0; e < 4; ++e) {
;             const unsigned ob = (e & 1) ? (ov[e >> 1] & 0xffff0000u) : (ov[e >> 1] << 16);
;             const float o = __uint_as_float(ob);
;             const float gte = v[e] / (1.f + __expf(-v[e]));
;             d[(size_t)e * 2048] = f2bf(gte * o * s_aux[lrow0 + e]);
;         }
; template <int EPI, int K, int LNI = -1>
; DI void ph_gemm(const Params& p, const bf16_t* __restrict__ A, const bf16_t* __restrict__ Bt, int N, float* s_aux) {
;     ...
; #pragma unroll
;                     for (int bj = 0; bj < 2; ++bj)
; #pragma unroll
;                         for (int n = 0; n < 2; ++n) {
;                             float v[4];
; #pragma unroll
;                             for (int e = 0; e < 4; ++e) v[e] = acc[ai][bj][m][n][e];
;                             epi_store<EPI, LNI>(p, row0, bcol + bj * 128 + wc * 32 + n * 16 + fr + oz, lrow0, v, sa, rs, lg_[bj][n], lb_[bj][n]);
	v_mov_b32_e32 v233, v141
	v_add_u32_e32 v224, v192, v177
	v_mul_hi_i32 v225, v224, s68
	v_lshrrev_b32_e32 v226, 31, v225
	v_ashrrev_i32_e32 v225, 12, v225
	v_add_u32_e32 v225, v225, v226
	v_mul_i32_i24_e32 v226, 0xffffdff0, v225
	v_add3_u32 v226, v224, v226, 48
	v_lshrrev_b32_e32 v227, 4, v226
	v_and_b32_e32 v227, 0xfffffc, v227
	v_add_lshl_u32 v228, v227, v225, 8
	v_lshlrev_b32_e32 v225, 2, v226
	v_and_b32_e32 v229, 32, v225
	v_and_b32_e32 v225, 7, v224
	v_bfe_u32 v230, v226, 4, 2
	v_lshlrev_b32_e32 v232, 1, v225
	v_add_u32_e32 v225, v228, v193
	v_or3_b32 v226, v225, v194, v230
	v_ashrrev_i32_e32 v227, 31, v226
	v_lshlrev_b64 v[226:227], 6, v[226:227]
	v_lshl_add_u64 v[234:235], s[20:21], 0, v[232:233]
	v_or3_b32 v226, v226, v229, v191
	v_lshl_add_u64 v[226:227], v[226:227], 4, v[234:235]
	global_load_dwordx2 v[216:217], v[226:227], off
	v_lshlrev_b32_e32 v94, 16, v218
	v_add_f32_e32 v91, 1.0, v84
	v_add_co_u32_e32 v84, vcc, s61, v80
	s_nop 0
	s_nop 0
	v_addc_co_u32_e32 v85, vcc, 0, v81, vcc
	v_mul_f32_e32 v93, 0xbfb8aa3b, v73
	v_exp_f32_e32 v93, v93
	v_rcp_f32_e32 v92, v91
	s_nop 0
	v_mul_f32_e32 v72, v72, v92
	v_mul_f32_e32 v72, v72, v94
	v_mul_f32_e32 v72, v96, v72
	v_add_f32_e32 v91, 1.0, v93
	v_cvt_pk_bf16_f32 v72, v72, s0
	global_store_short v[80:81], v72, off offset:32
	v_and_b32_e32 v72, 0xffff0000, v218
	v_mul_f32_e32 v92, 0xbfb8aa3b, v74
	v_exp_f32_e32 v92, v92
	v_rcp_f32_e32 v86, v91
	s_nop 0
	v_mul_f32_e32 v73, v73, v86
	v_mul_f32_e32 v72, v73, v72
	v_add_f32_e32 v73, 1.0, v92
	v_mul_f32_e32 v72, v97, v72
	v_cvt_pk_bf16_f32 v72, v72, s0
	global_store_short v[84:85], v72, off offset:32
	v_mul_f32_e32 v91, 0xbfb8aa3b, v75
	v_exp_f32_e32 v91, v91
	v_lshlrev_b32_e32 v72, 16, v219
	v_rcp_f32_e32 v86, v73
	s_nop 0
	v_mul_f32_e32 v73, v74, v86
	v_mul_f32_e32 v72, v73, v72
	v_add_f32_e32 v73, 1.0, v91
	v_mul_f32_e32 v72, v98, v72
	v_cvt_pk_bf16_f32 v72, v72, s0
	global_store_short v[76:77], v72, off offset:32
	v_and_b32_e32 v72, 0xffff0000, v219
	v_rcp_f32_e32 v74, v73
	s_nop 0
	v_mul_f32_e32 v73, v75, v74
	v_mul_f32_e32 v72, v73, v72
	v_mul_f32_e32 v72, v99, v72
	v_cvt_pk_bf16_f32 v72, v72, s0
	global_store_short v[78:79], v72, off offset:32
	v_add_u32_e32 v72, v88, v121
	v_or3_b32 v72, v72, v122, v89
	v_ashrrev_i32_e32 v73, 31, v72
	v_lshlrev_b64 v[72:73], 6, v[72:73]
	v_or3_b32 v72, v72, v90, v191
	v_lshl_add_u64 v[72:73], v[72:73], 4, v[82:83]
	v_mul_f32_e32 v74, 0xbfb8aa3b, v68
	v_exp_f32_e32 v74, v74
	s_waitcnt vmcnt(14)
	v_mov_b32_e32 v233, v141
	v_add_u32_e32 v224, v192, v177
	v_mul_hi_i32 v225, v224, s68
	v_lshrrev_b32_e32 v226, 31, v225
	v_ashrrev_i32_e32 v225, 12, v225
	v_add_u32_e32 v225, v225, v226
	v_mul_i32_i24_e32 v226, 0xffffdff0, v225
	v_add3_u32 v226, v224, v226, 48
	v_lshrrev_b32_e32 v227, 4, v226
	v_and_b32_e32 v227, 0xfffffc, v227
	v_add_lshl_u32 v228, v227, v225, 8
	v_lshlrev_b32_e32 v225, 2, v226
	v_and_b32_e32 v229, 32, v225
	v_and_b32_e32 v225, 7, v224
	v_bfe_u32 v230, v226, 4, 2
	v_lshlrev_b32_e32 v232, 1, v225
	v_lshl_add_u64 v[234:235], s[20:21], 0, v[232:233]
	v_add_u32_e32 v236, v228, v126
	v_or3_b32 v236, v236, v149, v230
	v_ashrrev_i32_e32 v237, 31, v236
	v_lshlrev_b64 v[236:237], 6, v[236:237]
	v_or3_b32 v236, v236, v229, v127
	v_lshl_add_u64 v[236:237], v[236:237], 4, v[234:235]
	global_load_dwordx2 v[218:219], v[236:237], off
	v_lshlrev_b32_e32 v87, 16, v220
	v_add_f32_e32 v74, 1.0, v74
	s_nop 0
	v_mul_f32_e32 v86, 0xbfb8aa3b, v69
	v_exp_f32_e32 v86, v86
	v_rcp_f32_e32 v75, v74
	s_nop 0
	v_mul_f32_e32 v68, v68, v75
	v_mul_f32_e32 v68, v68, v87
	v_mul_f32_e32 v68, v96, v68
	v_add_f32_e32 v74, 1.0, v86
	v_cvt_pk_bf16_f32 v68, v68, s0
	global_store_short v[80:81], v68, off offset:256
	v_and_b32_e32 v68, 0xffff0000, v220
	v_mul_f32_e32 v75, 0xbfb8aa3b, v70
	v_exp_f32_e32 v75, v75
	v_rcp_f32_e32 v72, v74
	s_nop 0
	v_mul_f32_e32 v69, v69, v72
	v_mul_f32_e32 v68, v69, v68
	v_add_f32_e32 v69, 1.0, v75
	v_mul_f32_e32 v68, v97, v68
	v_cvt_pk_bf16_f32 v68, v68, s0
	global_store_short v[84:85], v68, off offset:256
	v_mul_f32_e32 v74, 0xbfb8aa3b, v71
	v_exp_f32_e32 v74, v74
	v_lshlrev_b32_e32 v68, 16, v221
	v_rcp_f32_e32 v72, v69
	s_nop 0
	v_mul_f32_e32 v69, v70, v72
	v_mul_f32_e32 v68, v69, v68
	v_add_f32_e32 v69, 1.0, v74
	v_mul_f32_e32 v68, v98, v68
	v_cvt_pk_bf16_f32 v68, v68, s0
	global_store_short v[76:77], v68, off offset:256
	v_and_b32_e32 v68, 0xffff0000, v221
	v_rcp_f32_e32 v70, v69
	s_nop 0
	v_mul_f32_e32 v69, v71, v70
	v_mul_f32_e32 v68, v69, v68
	v_mul_f32_e32 v68, v99, v68
	v_cvt_pk_bf16_f32 v68, v68, s0
	global_store_short v[78:79], v68, off offset:256
	v_add_u32_e32 v68, v88, v118
	v_or3_b32 v68, v68, v120, v89
	v_ashrrev_i32_e32 v69, 31, v68
	v_lshlrev_b64 v[68:69], 6, v[68:69]
	v_or3_b32 v68, v68, v90, v119
	v_lshl_add_u64 v[68:69], v[68:69], 4, v[82:83]
	v_mul_f32_e32 v70, 0xbfb8aa3b, v64
	v_exp_f32_e32 v70, v70
	s_waitcnt vmcnt(14)
; DI bf16_t f2bf(float x) { return (bf16_t)(cvt_pk(x, 0.f) & 0xffffu); }
; DI float ex2(float x) { return __builtin_amdgcn_exp2f(x); }
; DI size_t vf_off(int item, int dvh, int j) { return ((size_t)((item * 16 + (dvh >> 5)) * 4 + (j >> 4)) * 64 + ((j >> 3) & 1) * 32 + (dvh & 31)) * 8 + (j & 7); }
;     ...
;     } else if (EPI == EPI_E5B) {
;         const u32x2 ov = *(const u32x2*)((const bf16_t*)(p.ws + OFF_VT1) + vf_off((((pos + 48) >> 6) * 4 + b) * 4 + (col >> 9), col & 511, (pos + 48) & 63));
;         bf16_t* d = (bf16_t*)(p.ws + OFF_YB) + (size_t)row0 * 2048 + col;
; #pragma unroll
;         for (int e = 0; e < 4; ++e) {
;             const unsigned ob = (e & 1) ? (ov[e >> 1] & 0xffff0000u) : (ov[e >> 1] << 16);
;             const float o = __uint_as_float(ob);
;             const float gte = v[e] / (1.f + __expf(-v[e]));
;             d[(size_t)e * 2048] = f2bf(gte * o * s_aux[lrow0 + e]);
;         }
; template <int EPI, int K, int LNI = -1>
; DI void ph_gemm(const Params& p, const bf16_t* __restrict__ A, const bf16_t* __restrict__ Bt, int N, float* s_aux) {
;     ...
; #pragma unroll
;             for (int ai = 0; ai < 2; ++ai)
; #pragma unroll
;                 for (int m = 0; m < 4; ++m) {
;                     const int lrow0 = ai * 128 + wr * 64 + m * 16 + fq * 4, row0 = brow + lrow0 + oz;
;                     f32x2 rs[4];
;                     if (EPI == EPI_RESID && LNI >= 0) {
;                         const f32x2* st_ = (const f32x2*)((unsigned char*)p.out + OFFO_STATS) + row0;
; #pragma unroll
;                         for (int e = 0; e < 4; ++e) rs[e] = st_[e];
;                     }
;                     if (EPI == EPI_E5) {
;                         const int idx_ = ((row0 % LT) + 48) & 63; const float lgh = lg_[0][0];
; #pragma unroll
;                         for (int e = 0; e < 4; ++e) rs[e] = (f32x2){ex2(lgh * (float)(idx_ + e + 1)), 0.0625f * ex2(lgh * (float)(63 - idx_ - e))};
;                     }
; #pragma unroll
;                     for (int bj = 0; bj < 2; ++bj)
; #pragma unroll
;                         for (int n = 0; n < 2; ++n) {
;                             float v[4];
; #pragma unroll
;                             for (int e = 0; e < 4; ++e) v[e] = acc[ai][bj][m][n][e];
;                             epi_store<EPI, LNI>(p, row0, bcol + bj * 128 + wc * 32 + n * 16 + fr + oz, lrow0, v, sa, rs, lg_[bj][n], lb_[bj][n]);
	v_mov_b32_e32 v233, v141
	v_add_u32_e32 v224, v192, v177
	v_mul_hi_i32 v225, v224, s68
	v_lshrrev_b32_e32 v226, 31, v225
	v_ashrrev_i32_e32 v225, 12, v225
	v_add_u32_e32 v225, v225, v226
	v_mul_i32_i24_e32 v226, 0xffffdff0, v225
	v_add3_u32 v226, v224, v226, 48
	v_lshrrev_b32_e32 v227, 4, v226
	v_and_b32_e32 v227, 0xfffffc, v227
	v_add_lshl_u32 v228, v227, v225, 8
	v_lshlrev_b32_e32 v225, 2, v226
	v_and_b32_e32 v229, 32, v225
	v_and_b32_e32 v225, 7, v224
	v_bfe_u32 v230, v226, 4, 2
	v_lshlrev_b32_e32 v232, 1, v225
	v_lshl_add_u64 v[234:235], s[20:21], 0, v[232:233]
	v_add_u32_e32 v236, v228, v121
	v_or3_b32 v236, v236, v122, v230
	v_ashrrev_i32_e32 v237, 31, v236
	v_lshlrev_b64 v[236:237], 6, v[236:237]
	v_or3_b32 v236, v236, v229, v191
	v_lshl_add_u64 v[236:237], v[236:237], 4, v[234:235]
	global_load_dwordx2 v[220:221], v[236:237], off
	v_lshlrev_b32_e32 v73, 16, v222
	v_add_f32_e32 v70, 1.0, v70
	s_nop 0
	v_mul_f32_e32 v72, 0xbfb8aa3b, v65
	v_exp_f32_e32 v72, v72
	v_rcp_f32_e32 v71, v70
	s_nop 0
	v_mul_f32_e32 v64, v64, v71
	v_mul_f32_e32 v64, v64, v73
	v_mul_f32_e32 v64, v96, v64
	v_add_f32_e32 v70, 1.0, v72
	v_cvt_pk_bf16_f32 v64, v64, s0
	global_store_short v[80:81], v64, off offset:288
	v_and_b32_e32 v64, 0xffff0000, v222
	v_mul_f32_e32 v71, 0xbfb8aa3b, v66
	v_exp_f32_e32 v71, v71
	v_rcp_f32_e32 v68, v70
	s_nop 0
	v_mul_f32_e32 v65, v65, v68
	v_mul_f32_e32 v64, v65, v64
	v_add_f32_e32 v65, 1.0, v71
	v_mul_f32_e32 v64, v97, v64
	v_cvt_pk_bf16_f32 v64, v64, s0
	global_store_short v[84:85], v64, off offset:288
	v_mul_f32_e32 v70, 0xbfb8aa3b, v67
	v_exp_f32_e32 v70, v70
	v_lshlrev_b32_e32 v64, 16, v223
	v_rcp_f32_e32 v68, v65
	s_nop 0
	v_mul_f32_e32 v65, v66, v68
	v_mul_f32_e32 v64, v65, v64
	v_add_f32_e32 v65, 1.0, v70
	v_mul_f32_e32 v64, v98, v64
	v_cvt_pk_bf16_f32 v64, v64, s0
	global_store_short v[76:77], v64, off offset:288
	v_and_b32_e32 v64, 0xffff0000, v223
	v_rcp_f32_e32 v66, v65
	s_nop 0
	v_mul_f32_e32 v65, v67, v66
	v_mul_f32_e32 v64, v65, v64
	v_mul_f32_e32 v64, v99, v64
	v_cvt_pk_bf16_f32 v64, v64, s0
	global_store_short v[78:79], v64, off offset:288
	v_add_u32_e32 v64, v192, v177
	v_mul_hi_i32 v65, v64, s68
	v_lshrrev_b32_e32 v66, 31, v65
	v_ashrrev_i32_e32 v65, 12, v65
	v_add_u32_e32 v65, v65, v66
	v_mul_i32_i24_e32 v66, 0xffffdff0, v65
	v_add3_u32 v66, v64, v66, 48
	v_lshrrev_b32_e32 v67, 4, v66
	v_and_b32_e32 v67, 0xfffffc, v67
	v_add_lshl_u32 v79, v67, v65, 8
	v_lshlrev_b32_e32 v65, 2, v66
	v_and_b32_e32 v78, 32, v65
	v_and_b32_e32 v65, 7, v64
	v_bfe_u32 v80, v66, 4, 2
	v_lshlrev_b32_e32 v140, 1, v65
	v_add_u32_e32 v65, v79, v193
	v_or3_b32 v66, v65, v194, v80
	v_ashrrev_i32_e32 v67, 31, v66
	v_lshlrev_b64 v[66:67], 6, v[66:67]
	v_lshl_add_u64 v[72:73], s[20:21], 0, v[140:141]
	v_or3_b32 v66, v66, v78, v191
	v_lshl_add_u64 v[66:67], v[66:67], 4, v[72:73]
	v_mul_f32_e32 v65, 0xbfb8aa3b, v60
	v_exp_f32_e32 v66, v65
	v_ashrrev_i32_e32 v65, 31, v64
	v_lshlrev_b64 v[64:65], 12, v[64:65]
	v_lshl_add_u64 v[64:65], s[36:37], 0, v[64:65]
	v_add_f32_e32 v66, 1.0, v66
	v_lshl_add_u64 v[74:75], v[64:65], 0, v[146:147]
	ds_read_b128 v[68:71], v195 offset:512
	v_rcp_f32_e32 v65, v66
	s_nop 0
	v_mul_f32_e32 v60, v60, v65
	v_mul_f32_e32 v65, 0xbfb8aa3b, v61
	v_exp_f32_e32 v81, v65
	s_waitcnt vmcnt(14)
	v_add_u32_e32 v224, v79, v118
	v_or3_b32 v224, v224, v120, v80
	v_ashrrev_i32_e32 v225, 31, v224
	v_lshlrev_b64 v[224:225], 6, v[224:225]
	v_or3_b32 v224, v224, v78, v119
	v_lshl_add_u64 v[224:225], v[224:225], 4, v[72:73]
	global_load_dwordx2 v[222:223], v[224:225], off
	v_lshlrev_b32_e32 v64, 16, v216
	v_add_f32_e32 v81, 1.0, v81
	v_mul_f32_e32 v60, v60, v64
	ds_read_b128 v[64:67], v195 offset:576
	s_waitcnt lgkmcnt(1)
	v_mul_f32_e32 v60, v68, v60
	v_cvt_pk_bf16_f32 v60, v60, s0
	global_store_short v[74:75], v60, off
	v_and_b32_e32 v60, 0xffff0000, v216
	v_rcp_f32_e32 v76, v81
	s_nop 0
	v_mul_f32_e32 v61, v61, v76
	v_mul_f32_e32 v76, 0xbfb8aa3b, v62
	v_exp_f32_e32 v76, v76
	v_mul_f32_e32 v60, v61, v60
	v_mul_f32_e32 v60, v69, v60
	v_cvt_pk_bf16_f32 v81, v60, s0
	v_add_f32_e32 v76, 1.0, v76
	v_add_co_u32_e32 v60, vcc, s3, v74
	s_nop 0
	s_nop 0
	v_addc_co_u32_e32 v61, vcc, 0, v75, vcc
	v_mul_f32_e32 v83, 0xbfb8aa3b, v63
	v_exp_f32_e32 v83, v83
	global_store_short v[60:61], v81, off offset:-4096
	v_lshlrev_b32_e32 v81, 16, v217
	v_rcp_f32_e32 v82, v76
	s_nop 0
	v_mul_f32_e32 v62, v62, v82
	v_add_f32_e32 v76, 1.0, v83
	v_mul_f32_e32 v62, v62, v81
	v_mul_f32_e32 v62, v70, v62
	v_cvt_pk_bf16_f32 v62, v62, s0
	global_store_short v[60:61], v62, off
	v_and_b32_e32 v62, 0xffff0000, v217
	v_rcp_f32_e32 v77, v76
	s_nop 0
	v_mul_f32_e32 v63, v63, v77
	v_mul_f32_e32 v62, v63, v62
	v_mul_f32_e32 v62, v71, v62
	v_cvt_pk_bf16_f32 v76, v62, s0
	v_add_co_u32_e32 v62, vcc, s69, v74
	v_mul_f32_e32 v81, 0xbfb8aa3b, v56
	s_nop 0
	v_addc_co_u32_e32 v63, vcc, 0, v75, vcc
	global_store_short v[62:63], v76, off
	v_add_u32_e32 v76, v79, v126
	v_or3_b32 v76, v76, v149, v80
	v_ashrrev_i32_e32 v77, 31, v76
	v_lshlrev_b64 v[76:77], 6, v[76:77]
	v_or3_b32 v76, v76, v78, v127
	v_lshl_add_u64 v[76:77], v[76:77], 4, v[72:73]
	v_exp_f32_e32 v81, v81
	v_add_co_u32_e32 v82, vcc, s61, v74
	v_add_f32_e32 v81, 1.0, v81
	s_nop 0
	v_addc_co_u32_e32 v83, vcc, 0, v75, vcc
	v_mul_f32_e32 v85, 0xbfb8aa3b, v57
	v_exp_f32_e32 v85, v85
	v_rcp_f32_e32 v84, v81
	s_nop 0
	v_mul_f32_e32 v56, v56, v84
	v_add_f32_e32 v81, 1.0, v85
	s_waitcnt vmcnt(14)
; DI bf16_t f2bf(float x) { return (bf16_t)(cvt_pk(x, 0.f) & 0xffffu); }
; DI size_t vf_off(int item, int dvh, int j) { return ((size_t)((item * 16 + (dvh >> 5)) * 4 + (j >> 4)) * 64 + ((j >> 3) & 1) * 32 + (dvh & 31)) * 8 + (j & 7); }
;     ...
;     } else if (EPI == EPI_E5B) {
;         const u32x2 ov = *(const u32x2*)((const bf16_t*)(p.ws + OFF_VT1) + vf_off((((pos + 48) >> 6) * 4 + b) * 4 + (col >> 9), col & 511, (pos + 48) & 63));
;         bf16_t* d = (bf16_t*)(p.ws + OFF_YB) + (size_t)row0 * 2048 + col;
; #pragma unroll
;         for (int e = 0; e < 4; ++e) {
;             const unsigned ob = (e & 1) ? (ov[e >> 1] & 0xffff0000u) : (ov[e >> 1] << 16);
;             const float o = __uint_as_float(ob);
;             const float gte = v[e] / (1.f + __expf(-v[e]));
;             d[(size_t)e * 2048] = f2bf(gte * o * s_aux[lrow0 + e]);
;         }
; template <int EPI, int K, int LNI = -1>
; DI void ph_gemm(const Params& p, const bf16_t* __restrict__ A, const bf16_t* __restrict__ Bt, int N, float* s_aux) {
;     ...
; #pragma unroll
;                     for (int bj = 0; bj < 2; ++bj)
; #pragma unroll
;                         for (int n = 0; n < 2; ++n) {
;                             float v[4];
; #pragma unroll
;                             for (int e = 0; e < 4; ++e) v[e] = acc[ai][bj][m][n][e];
;                             epi_store<EPI, LNI>(p, row0, bcol + bj * 128 + wc * 32 + n * 16 + fr + oz, lrow0, v, sa, rs, lg_[bj][n], lb_[bj][n]);
	v_mov_b32_e32 v233, v141
	v_add_u32_e32 v224, v192, v178
	v_mul_hi_i32 v225, v224, s68
	v_lshrrev_b32_e32 v226, 31, v225
	v_ashrrev_i32_e32 v225, 12, v225
	v_add_u32_e32 v225, v225, v226
	v_mul_i32_i24_e32 v226, 0xffffdff0, v225
	v_add3_u32 v226, v224, v226, 48
	v_lshrrev_b32_e32 v227, 4, v226
	v_and_b32_e32 v227, 0xfffffc, v227
	v_add_lshl_u32 v228, v227, v225, 8
	v_lshlrev_b32_e32 v225, 2, v226
	v_and_b32_e32 v229, 32, v225
	v_and_b32_e32 v225, 7, v224
	v_bfe_u32 v230, v226, 4, 2
	v_lshlrev_b32_e32 v232, 1, v225
	v_add_u32_e32 v225, v228, v193
	v_or3_b32 v234, v225, v194, v230
	v_ashrrev_i32_e32 v235, 31, v234
	v_lshlrev_b64 v[234:235], 6, v[234:235]
	v_lshl_add_u64 v[226:227], s[20:21], 0, v[232:233]
	v_or3_b32 v234, v234, v229, v191
	v_lshl_add_u64 v[234:235], v[234:235], 4, v[226:227]
	global_load_dwordx2 v[216:217], v[234:235], off
	v_lshlrev_b32_e32 v86, 16, v218
	v_mul_f32_e32 v56, v56, v86
	v_mul_f32_e32 v56, v68, v56
	v_cvt_pk_bf16_f32 v56, v56, s0
	global_store_short v[74:75], v56, off offset:32
	v_and_b32_e32 v56, 0xffff0000, v218
	v_mul_f32_e32 v84, 0xbfb8aa3b, v58
	v_exp_f32_e32 v84, v84
	v_rcp_f32_e32 v76, v81
	s_nop 0
	v_mul_f32_e32 v57, v57, v76
	v_mul_f32_e32 v56, v57, v56
	v_add_f32_e32 v57, 1.0, v84
	v_mul_f32_e32 v56, v69, v56
	v_cvt_pk_bf16_f32 v56, v56, s0
	global_store_short v[82:83], v56, off offset:32
	v_mul_f32_e32 v81, 0xbfb8aa3b, v59
	v_exp_f32_e32 v81, v81
	v_lshlrev_b32_e32 v56, 16, v219
	v_rcp_f32_e32 v76, v57
	s_nop 0
	v_mul_f32_e32 v57, v58, v76
	v_mul_f32_e32 v56, v57, v56
	v_add_f32_e32 v57, 1.0, v81
	v_mul_f32_e32 v56, v70, v56
	v_cvt_pk_bf16_f32 v56, v56, s0
	global_store_short v[60:61], v56, off offset:32
	v_and_b32_e32 v56, 0xffff0000, v219
	v_rcp_f32_e32 v58, v57
	s_nop 0
	v_mul_f32_e32 v57, v59, v58
	v_mul_f32_e32 v56, v57, v56
	v_mul_f32_e32 v56, v71, v56
	v_cvt_pk_bf16_f32 v56, v56, s0
	global_store_short v[62:63], v56, off offset:32
	v_add_u32_e32 v56, v79, v121
	v_or3_b32 v56, v56, v122, v80
	v_ashrrev_i32_e32 v57, 31, v56
	v_lshlrev_b64 v[56:57], 6, v[56:57]
	v_or3_b32 v56, v56, v78, v191
	v_lshl_add_u64 v[56:57], v[56:57], 4, v[72:73]
	v_mul_f32_e32 v58, 0xbfb8aa3b, v52
	v_exp_f32_e32 v58, v58
	s_waitcnt vmcnt(14)
	v_mov_b32_e32 v233, v141
	v_add_u32_e32 v224, v192, v178
	v_mul_hi_i32 v225, v224, s68
	v_lshrrev_b32_e32 v226, 31, v225
	v_ashrrev_i32_e32 v225, 12, v225
	v_add_u32_e32 v225, v225, v226
	v_mul_i32_i24_e32 v226, 0xffffdff0, v225
	v_add3_u32 v226, v224, v226, 48
	v_lshrrev_b32_e32 v227, 4, v226
	v_and_b32_e32 v227, 0xfffffc, v227
	v_add_lshl_u32 v228, v227, v225, 8
	v_lshlrev_b32_e32 v225, 2, v226
	v_and_b32_e32 v229, 32, v225
	v_and_b32_e32 v225, 7, v224
	v_bfe_u32 v230, v226, 4, 2
	v_lshlrev_b32_e32 v232, 1, v225
	v_lshl_add_u64 v[226:227], s[20:21], 0, v[232:233]
	v_add_u32_e32 v234, v228, v126
	v_or3_b32 v234, v234, v149, v230
	v_ashrrev_i32_e32 v235, 31, v234
	v_lshlrev_b64 v[234:235], 6, v[234:235]
	v_or3_b32 v234, v234, v229, v127
	v_lshl_add_u64 v[234:235], v[234:235], 4, v[226:227]
	global_load_dwordx2 v[218:219], v[234:235], off
	v_lshlrev_b32_e32 v77, 16, v220
	v_add_f32_e32 v58, 1.0, v58
	s_nop 0
	v_mul_f32_e32 v76, 0xbfb8aa3b, v53
	v_exp_f32_e32 v76, v76
	v_rcp_f32_e32 v59, v58
	s_nop 0
	v_mul_f32_e32 v52, v52, v59
	v_mul_f32_e32 v52, v52, v77
	v_mul_f32_e32 v52, v68, v52
	v_add_f32_e32 v58, 1.0, v76
	v_cvt_pk_bf16_f32 v52, v52, s0
	global_store_short v[74:75], v52, off offset:256
	v_and_b32_e32 v52, 0xffff0000, v220
	v_mul_f32_e32 v59, 0xbfb8aa3b, v54
	v_exp_f32_e32 v59, v59
	v_rcp_f32_e32 v56, v58
	s_nop 0
	v_mul_f32_e32 v53, v53, v56
	v_mul_f32_e32 v52, v53, v52
	v_add_f32_e32 v53, 1.0, v59
	v_mul_f32_e32 v52, v69, v52
	v_cvt_pk_bf16_f32 v52, v52, s0
	global_store_short v[82:83], v52, off offset:256
	v_mul_f32_e32 v58, 0xbfb8aa3b, v55
	v_exp_f32_e32 v58, v58
	v_lshlrev_b32_e32 v52, 16, v221
	v_rcp_f32_e32 v56, v53
	s_nop 0
	v_mul_f32_e32 v53, v54, v56
	v_mul_f32_e32 v52, v53, v52
	v_add_f32_e32 v53, 1.0, v58
	v_mul_f32_e32 v52, v70, v52
	v_cvt_pk_bf16_f32 v52, v52, s0
	global_store_short v[60:61], v52, off offset:256
	v_and_b32_e32 v52, 0xffff0000, v221
	v_rcp_f32_e32 v54, v53
	s_nop 0
	v_mul_f32_e32 v53, v55, v54
	v_mul_f32_e32 v52, v53, v52
	v_mul_f32_e32 v52, v71, v52
	v_cvt_pk_bf16_f32 v52, v52, s0
	global_store_short v[62:63], v52, off offset:256
	v_add_u32_e32 v52, v79, v118
	v_or3_b32 v52, v52, v120, v80
	v_ashrrev_i32_e32 v53, 31, v52
	v_lshlrev_b64 v[52:53], 6, v[52:53]
	v_or3_b32 v52, v52, v78, v119
	v_lshl_add_u64 v[52:53], v[52:53], 4, v[72:73]
	v_mul_f32_e32 v54, 0xbfb8aa3b, v48
	v_exp_f32_e32 v54, v54
	s_waitcnt vmcnt(14)
; DI bf16_t f2bf(float x) { return (bf16_t)(cvt_pk(x, 0.f) & 0xffffu); }
; DI float ex2(float x) { return __builtin_amdgcn_exp2f(x); }
; DI size_t vf_off(int item, int dvh, int j) { return ((size_t)((item * 16 + (dvh >> 5)) * 4 + (j >> 4)) * 64 + ((j >> 3) & 1) * 32 + (dvh & 31)) * 8 + (j & 7); }
;     ...
;     } else if (EPI == EPI_E5B) {
;         const u32x2 ov = *(const u32x2*)((const bf16_t*)(p.ws + OFF_VT1) + vf_off((((pos + 48) >> 6) * 4 + b) * 4 + (col >> 9), col & 511, (pos + 48) & 63));
;         bf16_t* d = (bf16_t*)(p.ws + OFF_YB) + (size_t)row0 * 2048 + col;
; #pragma unroll
;         for (int e = 0; e < 4; ++e) {
;             const unsigned ob = (e & 1) ? (ov[e >> 1] & 0xffff0000u) : (ov[e >> 1] << 16);
;             const float o = __uint_as_float(ob);
;             const float gte = v[e] / (1.f + __expf(-v[e]));
;             d[(size_t)e * 2048] = f2bf(gte * o * s_aux[lrow0 + e]);
;         }
; template <int EPI, int K, int LNI = -1>
; DI void ph_gemm(const Params& p, const bf16_t* __restrict__ A, const bf16_t* __restrict__ Bt, int N, float* s_aux) {
;     ...
; #pragma unroll
;             for (int ai = 0; ai < 2; ++ai)
; #pragma unroll
;                 for (int m = 0; m < 4; ++m) {
;                     const int lrow0 = ai * 128 + wr * 64 + m * 16 + fq * 4, row0 = brow + lrow0 + oz;
;                     f32x2 rs[4];
;                     if (EPI == EPI_RESID && LNI >= 0) {
;                         const f32x2* st_ = (const f32x2*)((unsigned char*)p.out + OFFO_STATS) + row0;
; #pragma unroll
;                         for (int e = 0; e < 4; ++e) rs[e] = st_[e];
;                     }
;                     if (EPI == EPI_E5) {
;                         const int idx_ = ((row0 % LT) + 48) & 63; const float lgh = lg_[0][0];
; #pragma unroll
;                         for (int e = 0; e < 4; ++e) rs[e] = (f32x2){ex2(lgh * (float)(idx_ + e + 1)), 0.0625f * ex2(lgh * (float)(63 - idx_ - e))};
;                     }
; #pragma unroll
;                     for (int bj = 0; bj < 2; ++bj)
; #pragma unroll
;                         for (int n = 0; n < 2; ++n) {
;                             float v[4];
; #pragma unroll
;                             for (int e = 0; e < 4; ++e) v[e] = acc[ai][bj][m][n][e];
;                             epi_store<EPI, LNI>(p, row0, bcol + bj * 128 + wc * 32 + n * 16 + fr + oz, lrow0, v, sa, rs, lg_[bj][n], lb_[bj][n]);
	v_mov_b32_e32 v233, v141
	v_add_u32_e32 v224, v192, v178
	v_mul_hi_i32 v225, v224, s68
	v_lshrrev_b32_e32 v226, 31, v225
	v_ashrrev_i32_e32 v225, 12, v225
	v_add_u32_e32 v225, v225, v226
	v_mul_i32_i24_e32 v226, 0xffffdff0, v225
	v_add3_u32 v226, v224, v226, 48
	v_lshrrev_b32_e32 v227, 4, v226
	v_and_b32_e32 v227, 0xfffffc, v227
	v_add_lshl_u32 v228, v227, v225, 8
	v_lshlrev_b32_e32 v225, 2, v226
	v_and_b32_e32 v229, 32, v225
	v_and_b32_e32 v225, 7, v224
	v_bfe_u32 v230, v226, 4, 2
	v_lshlrev_b32_e32 v232, 1, v225
	v_lshl_add_u64 v[226:227], s[20:21], 0, v[232:233]
	v_add_u32_e32 v234, v228, v121
	v_or3_b32 v234, v234, v122, v230
	v_ashrrev_i32_e32 v235, 31, v234
	v_lshlrev_b64 v[234:235], 6, v[234:235]
	v_or3_b32 v234, v234, v229, v191
	v_lshl_add_u64 v[234:235], v[234:235], 4, v[226:227]
	global_load_dwordx2 v[220:221], v[234:235], off
	v_lshlrev_b32_e32 v57, 16, v222
	v_add_f32_e32 v54, 1.0, v54
	s_nop 0
	v_mul_f32_e32 v56, 0xbfb8aa3b, v49
	v_exp_f32_e32 v56, v56
	v_rcp_f32_e32 v55, v54
	s_nop 0
	v_mul_f32_e32 v48, v48, v55
	v_mul_f32_e32 v48, v48, v57
	v_mul_f32_e32 v48, v68, v48
	v_add_f32_e32 v54, 1.0, v56
	v_cvt_pk_bf16_f32 v48, v48, s0
	global_store_short v[74:75], v48, off offset:288
	v_and_b32_e32 v48, 0xffff0000, v222
	v_mul_f32_e32 v55, 0xbfb8aa3b, v50
	v_exp_f32_e32 v55, v55
	v_rcp_f32_e32 v52, v54
	s_nop 0
	v_mul_f32_e32 v49, v49, v52
	v_mul_f32_e32 v48, v49, v48
	v_add_f32_e32 v49, 1.0, v55
	v_mul_f32_e32 v48, v69, v48
	v_cvt_pk_bf16_f32 v48, v48, s0
	global_store_short v[82:83], v48, off offset:288
	v_mul_f32_e32 v54, 0xbfb8aa3b, v51
	v_exp_f32_e32 v54, v54
	v_lshlrev_b32_e32 v48, 16, v223
	v_rcp_f32_e32 v52, v49
	s_nop 0
	v_mul_f32_e32 v49, v50, v52
	v_mul_f32_e32 v48, v49, v48
	v_add_f32_e32 v49, 1.0, v54
	v_mul_f32_e32 v48, v70, v48
	v_cvt_pk_bf16_f32 v48, v48, s0
	global_store_short v[60:61], v48, off offset:288
	v_and_b32_e32 v48, 0xffff0000, v223
	v_rcp_f32_e32 v50, v49
	s_nop 0
	v_mul_f32_e32 v49, v51, v50
	v_mul_f32_e32 v48, v49, v48
	v_mul_f32_e32 v48, v71, v48
	v_cvt_pk_bf16_f32 v48, v48, s0
	global_store_short v[62:63], v48, off offset:288
	v_add_u32_e32 v48, v192, v178
	v_mul_hi_i32 v49, v48, s68
	v_lshrrev_b32_e32 v50, 31, v49
	v_ashrrev_i32_e32 v49, 12, v49
	v_add_u32_e32 v49, v49, v50
	v_mul_i32_i24_e32 v50, 0xffffdff0, v49
	v_add3_u32 v50, v48, v50, 48
	v_lshrrev_b32_e32 v51, 4, v50
	v_and_b32_e32 v51, 0xfffffc, v51
	v_add_lshl_u32 v56, v51, v49, 8
	v_lshlrev_b32_e32 v49, 2, v50
	v_and_b32_e32 v58, 32, v49
	v_and_b32_e32 v49, 7, v48
	v_bfe_u32 v57, v50, 4, 2
	v_lshlrev_b32_e32 v140, 1, v49
	v_add_u32_e32 v49, v56, v193
	v_or3_b32 v52, v49, v194, v57
	v_ashrrev_i32_e32 v53, 31, v52
	v_lshlrev_b64 v[52:53], 6, v[52:53]
	v_lshl_add_u64 v[50:51], s[20:21], 0, v[140:141]
	v_or3_b32 v52, v52, v58, v191
	v_lshl_add_u64 v[52:53], v[52:53], 4, v[50:51]
	v_mul_f32_e32 v49, 0xbfb8aa3b, v44
	v_exp_f32_e32 v54, v49
	v_ashrrev_i32_e32 v49, 31, v48
	v_lshlrev_b64 v[48:49], 12, v[48:49]
	v_lshl_add_u64 v[48:49], s[36:37], 0, v[48:49]
	v_add_f32_e32 v54, 1.0, v54
	v_lshl_add_u64 v[48:49], v[48:49], 0, v[146:147]
	v_mul_f32_e32 v59, 0xbfb8aa3b, v45
	v_exp_f32_e32 v59, v59
	v_rcp_f32_e32 v55, v54
	s_nop 0
	v_mul_f32_e32 v44, v44, v55
	v_add_f32_e32 v54, 1.0, v59
	s_waitcnt vmcnt(14)
	v_add_u32_e32 v224, v56, v118
	v_or3_b32 v224, v224, v120, v57
	v_ashrrev_i32_e32 v225, 31, v224
	v_lshlrev_b64 v[224:225], 6, v[224:225]
	v_or3_b32 v224, v224, v58, v119
	v_lshl_add_u64 v[224:225], v[224:225], 4, v[50:51]
	global_load_dwordx2 v[222:223], v[224:225], off
	v_lshlrev_b32_e32 v60, 16, v216
	v_mul_f32_e32 v44, v44, v60
	s_waitcnt lgkmcnt(0)
	v_mul_f32_e32 v44, v64, v44
	v_cvt_pk_bf16_f32 v44, v44, s0
	global_store_short v[48:49], v44, off
	v_and_b32_e32 v44, 0xffff0000, v216
	v_rcp_f32_e32 v52, v54
	s_nop 0
	v_mul_f32_e32 v45, v45, v52
	v_mul_f32_e32 v52, 0xbfb8aa3b, v46
	v_exp_f32_e32 v52, v52
	v_mul_f32_e32 v44, v45, v44
	v_mul_f32_e32 v44, v65, v44
	v_cvt_pk_bf16_f32 v54, v44, s0
	v_add_f32_e32 v52, 1.0, v52
	v_add_co_u32_e32 v44, vcc, s3, v48
	s_nop 0
	s_nop 0
	v_addc_co_u32_e32 v45, vcc, 0, v49, vcc
	v_mul_f32_e32 v59, 0xbfb8aa3b, v47
	v_exp_f32_e32 v59, v59
	global_store_short v[44:45], v54, off offset:-4096
	v_lshlrev_b32_e32 v54, 16, v217
	v_rcp_f32_e32 v55, v52
	s_nop 0
	v_mul_f32_e32 v46, v46, v55
	v_add_f32_e32 v52, 1.0, v59
	v_mul_f32_e32 v46, v46, v54
	v_mul_f32_e32 v46, v66, v46
	v_cvt_pk_bf16_f32 v46, v46, s0
	global_store_short v[44:45], v46, off
	v_and_b32_e32 v46, 0xffff0000, v217
	v_rcp_f32_e32 v53, v52
	s_nop 0
	v_mul_f32_e32 v47, v47, v53
	v_mul_f32_e32 v46, v47, v46
	v_mul_f32_e32 v46, v67, v46
	v_cvt_pk_bf16_f32 v52, v46, s0
	v_add_co_u32_e32 v46, vcc, s69, v48
	s_nop 1
	v_addc_co_u32_e32 v47, vcc, 0, v49, vcc
	global_store_short v[46:47], v52, off
	v_add_u32_e32 v52, v56, v126
	v_or3_b32 v52, v52, v149, v57
	v_ashrrev_i32_e32 v53, 31, v52
	v_lshlrev_b64 v[52:53], 6, v[52:53]
	v_or3_b32 v52, v52, v58, v127
	v_lshl_add_u64 v[52:53], v[52:53], 4, v[50:51]
	v_mul_f32_e32 v52, 0xbfb8aa3b, v40
	v_exp_f32_e32 v52, v52
	s_waitcnt vmcnt(14)
; DI bf16_t f2bf(float x) { return (bf16_t)(cvt_pk(x, 0.f) & 0xffffu); }
; DI size_t vf_off(int item, int dvh, int j) { return ((size_t)((item * 16 + (dvh >> 5)) * 4 + (j >> 4)) * 64 + ((j >> 3) & 1) * 32 + (dvh & 31)) * 8 + (j & 7); }
;     ...
;     } else if (EPI == EPI_E5B) {
;         const u32x2 ov = *(const u32x2*)((const bf16_t*)(p.ws + OFF_VT1) + vf_off((((pos + 48) >> 6) * 4 + b) * 4 + (col >> 9), col & 511, (pos + 48) & 63));
;         bf16_t* d = (bf16_t*)(p.ws + OFF_YB) + (size_t)row0 * 2048 + col;
; #pragma unroll
;         for (int e = 0; e < 4; ++e) {
;             const unsigned ob = (e & 1) ? (ov[e >> 1] & 0xffff0000u) : (ov[e >> 1] << 16);
;             const float o = __uint_as_float(ob);
;             const float gte = v[e] / (1.f + __expf(-v[e]));
;             d[(size_t)e * 2048] = f2bf(gte * o * s_aux[lrow0 + e]);
;         }
; template <int EPI, int K, int LNI = -1>
; DI void ph_gemm(const Params& p, const bf16_t* __restrict__ A, const bf16_t* __restrict__ Bt, int N, float* s_aux) {
;     ...
; #pragma unroll
;                     for (int bj = 0; bj < 2; ++bj)
; #pragma unroll
;                         for (int n = 0; n < 2; ++n) {
;                             float v[4];
; #pragma unroll
;                             for (int e = 0; e < 4; ++e) v[e] = acc[ai][bj][m][n][e];
;                             epi_store<EPI, LNI>(p, row0, bcol + bj * 128 + wc * 32 + n * 16 + fr + oz, lrow0, v, sa, rs, lg_[bj][n], lb_[bj][n]);
	v_mov_b32_e32 v233, v141
	v_add_u32_e32 v224, v192, v179
	v_mul_hi_i32 v225, v224, s68
	v_lshrrev_b32_e32 v226, 31, v225
	v_ashrrev_i32_e32 v225, 12, v225
	v_add_u32_e32 v225, v225, v226
	v_mul_i32_i24_e32 v226, 0xffffdff0, v225
	v_add3_u32 v226, v224, v226, 48
	v_lshrrev_b32_e32 v227, 4, v226
	v_and_b32_e32 v227, 0xfffffc, v227
	v_add_lshl_u32 v228, v227, v225, 8
	v_lshlrev_b32_e32 v225, 2, v226
	v_and_b32_e32 v229, 32, v225
	v_and_b32_e32 v225, 7, v224
	v_bfe_u32 v230, v226, 4, 2
	v_lshlrev_b32_e32 v232, 1, v225
	v_add_u32_e32 v225, v228, v193
	v_or3_b32 v226, v225, v194, v230
	v_ashrrev_i32_e32 v227, 31, v226
	v_lshlrev_b64 v[226:227], 6, v[226:227]
	v_lshl_add_u64 v[234:235], s[20:21], 0, v[232:233]
	v_or3_b32 v226, v226, v229, v191
	v_lshl_add_u64 v[226:227], v[226:227], 4, v[234:235]
	global_load_dwordx2 v[216:217], v[226:227], off
	v_lshlrev_b32_e32 v62, 16, v218
	v_add_f32_e32 v59, 1.0, v52
	v_add_co_u32_e32 v52, vcc, s61, v48
	s_nop 0
	s_nop 0
	v_addc_co_u32_e32 v53, vcc, 0, v49, vcc
	v_mul_f32_e32 v61, 0xbfb8aa3b, v41
	v_exp_f32_e32 v61, v61
	v_rcp_f32_e32 v60, v59
	s_nop 0
	v_mul_f32_e32 v40, v40, v60
	v_mul_f32_e32 v40, v40, v62
	v_mul_f32_e32 v40, v64, v40
	v_add_f32_e32 v59, 1.0, v61
	v_cvt_pk_bf16_f32 v40, v40, s0
	global_store_short v[48:49], v40, off offset:32
	v_and_b32_e32 v40, 0xffff0000, v218
	v_mul_f32_e32 v60, 0xbfb8aa3b, v42
	v_exp_f32_e32 v60, v60
	v_rcp_f32_e32 v54, v59
	s_nop 0
	v_mul_f32_e32 v41, v41, v54
	v_mul_f32_e32 v40, v41, v40
	v_add_f32_e32 v41, 1.0, v60
	v_mul_f32_e32 v40, v65, v40
	v_cvt_pk_bf16_f32 v40, v40, s0
	global_store_short v[52:53], v40, off offset:32
	v_mul_f32_e32 v59, 0xbfb8aa3b, v43
	v_exp_f32_e32 v59, v59
	v_lshlrev_b32_e32 v40, 16, v219
	v_rcp_f32_e32 v54, v41
	s_nop 0
	v_mul_f32_e32 v41, v42, v54
	v_mul_f32_e32 v40, v41, v40
	v_add_f32_e32 v41, 1.0, v59
	v_mul_f32_e32 v40, v66, v40
	v_cvt_pk_bf16_f32 v40, v40, s0
	global_store_short v[44:45], v40, off offset:32
	v_and_b32_e32 v40, 0xffff0000, v219
	v_rcp_f32_e32 v42, v41
	s_nop 0
	v_mul_f32_e32 v41, v43, v42
	v_mul_f32_e32 v40, v41, v40
	v_mul_f32_e32 v40, v67, v40
	v_cvt_pk_bf16_f32 v40, v40, s0
	global_store_short v[46:47], v40, off offset:32
	v_add_u32_e32 v40, v56, v121
	v_or3_b32 v40, v40, v122, v57
	v_ashrrev_i32_e32 v41, 31, v40
	v_lshlrev_b64 v[40:41], 6, v[40:41]
	v_or3_b32 v40, v40, v58, v191
	v_lshl_add_u64 v[40:41], v[40:41], 4, v[50:51]
	v_mul_f32_e32 v42, 0xbfb8aa3b, v36
	v_exp_f32_e32 v42, v42
	s_waitcnt vmcnt(14)
	v_mov_b32_e32 v233, v141
	v_add_u32_e32 v224, v192, v179
	v_mul_hi_i32 v225, v224, s68
	v_lshrrev_b32_e32 v226, 31, v225
	v_ashrrev_i32_e32 v225, 12, v225
	v_add_u32_e32 v225, v225, v226
	v_mul_i32_i24_e32 v226, 0xffffdff0, v225
	v_add3_u32 v226, v224, v226, 48
	v_lshrrev_b32_e32 v227, 4, v226
	v_and_b32_e32 v227, 0xfffffc, v227
	v_add_lshl_u32 v228, v227, v225, 8
	v_lshlrev_b32_e32 v225, 2, v226
	v_and_b32_e32 v229, 32, v225
	v_and_b32_e32 v225, 7, v224
	v_bfe_u32 v230, v226, 4, 2
	v_lshlrev_b32_e32 v232, 1, v225
	v_lshl_add_u64 v[234:235], s[20:21], 0, v[232:233]
	v_add_u32_e32 v236, v228, v126
	v_or3_b32 v236, v236, v149, v230
	v_ashrrev_i32_e32 v237, 31, v236
	v_lshlrev_b64 v[236:237], 6, v[236:237]
	v_or3_b32 v236, v236, v229, v127
	v_lshl_add_u64 v[236:237], v[236:237], 4, v[234:235]
	global_load_dwordx2 v[218:219], v[236:237], off
	v_lshlrev_b32_e32 v55, 16, v220
	v_add_f32_e32 v42, 1.0, v42
	s_nop 0
	v_mul_f32_e32 v54, 0xbfb8aa3b, v37
	v_exp_f32_e32 v54, v54
	v_rcp_f32_e32 v43, v42
	s_nop 0
	v_mul_f32_e32 v36, v36, v43
	v_mul_f32_e32 v36, v36, v55
	v_mul_f32_e32 v36, v64, v36
	v_add_f32_e32 v42, 1.0, v54
	v_cvt_pk_bf16_f32 v36, v36, s0
	global_store_short v[48:49], v36, off offset:256
	v_and_b32_e32 v36, 0xffff0000, v220
	v_mul_f32_e32 v43, 0xbfb8aa3b, v38
	v_exp_f32_e32 v43, v43
	v_rcp_f32_e32 v40, v42
	s_nop 0
	v_mul_f32_e32 v37, v37, v40
	v_mul_f32_e32 v36, v37, v36
	v_add_f32_e32 v37, 1.0, v43
	v_mul_f32_e32 v36, v65, v36
	v_cvt_pk_bf16_f32 v36, v36, s0
	global_store_short v[52:53], v36, off offset:256
	v_mul_f32_e32 v42, 0xbfb8aa3b, v39
	v_exp_f32_e32 v42, v42
	v_lshlrev_b32_e32 v36, 16, v221
	v_rcp_f32_e32 v40, v37
	s_nop 0
	v_mul_f32_e32 v37, v38, v40
	v_mul_f32_e32 v36, v37, v36
	v_add_f32_e32 v37, 1.0, v42
	v_mul_f32_e32 v36, v66, v36
	v_cvt_pk_bf16_f32 v36, v36, s0
	global_store_short v[44:45], v36, off offset:256
	v_and_b32_e32 v36, 0xffff0000, v221
	v_rcp_f32_e32 v38, v37
	s_nop 0
	v_mul_f32_e32 v37, v39, v38
	v_mul_f32_e32 v36, v37, v36
	v_mul_f32_e32 v36, v67, v36
	v_cvt_pk_bf16_f32 v36, v36, s0
	global_store_short v[46:47], v36, off offset:256
	v_add_u32_e32 v36, v56, v118
	v_or3_b32 v36, v36, v120, v57
	v_ashrrev_i32_e32 v37, 31, v36
	v_lshlrev_b64 v[36:37], 6, v[36:37]
	v_or3_b32 v36, v36, v58, v119
	v_lshl_add_u64 v[36:37], v[36:37], 4, v[50:51]
	v_mul_f32_e32 v38, 0xbfb8aa3b, v32
	v_exp_f32_e32 v38, v38
	s_waitcnt vmcnt(14)
; DI bf16_t f2bf(float x) { return (bf16_t)(cvt_pk(x, 0.f) & 0xffffu); }
; DI float ex2(float x) { return __builtin_amdgcn_exp2f(x); }
; DI size_t vf_off(int item, int dvh, int j) { return ((size_t)((item * 16 + (dvh >> 5)) * 4 + (j >> 4)) * 64 + ((j >> 3) & 1) * 32 + (dvh & 31)) * 8 + (j & 7); }
;     ...
;     } else if (EPI == EPI_E5B) {
;         const u32x2 ov = *(const u32x2*)((const bf16_t*)(p.ws + OFF_VT1) + vf_off((((pos + 48) >> 6) * 4 + b) * 4 + (col >> 9), col & 511, (pos + 48) & 63));
;         bf16_t* d = (bf16_t*)(p.ws + OFF_YB) + (size_t)row0 * 2048 + col;
; #pragma unroll
;         for (int e = 0; e < 4; ++e) {
;             const unsigned ob = (e & 1) ? (ov[e >> 1] & 0xffff0000u) : (ov[e >> 1] << 16);
;             const float o = __uint_as_float(ob);
;             const float gte = v[e] / (1.f + __expf(-v[e]));
;             d[(size_t)e * 2048] = f2bf(gte * o * s_aux[lrow0 + e]);
;         }
; template <int EPI, int K, int LNI = -1>
; DI void ph_gemm(const Params& p, const bf16_t* __restrict__ A, const bf16_t* __restrict__ Bt, int N, float* s_aux) {
;     ...
; #pragma unroll
;             for (int ai = 0; ai < 2; ++ai)
; #pragma unroll
;                 for (int m = 0; m < 4; ++m) {
;                     const int lrow0 = ai * 128 + wr * 64 + m * 16 + fq * 4, row0 = brow + lrow0 + oz;
;                     f32x2 rs[4];
;                     if (EPI == EPI_RESID && LNI >= 0) {
;                         const f32x2* st_ = (const f32x2*)((unsigned char*)p.out + OFFO_STATS) + row0;
; #pragma unroll
;                         for (int e = 0; e < 4; ++e) rs[e] = st_[e];
;                     }
;                     if (EPI == EPI_E5) {
;                         const int idx_ = ((row0 % LT) + 48) & 63; const float lgh = lg_[0][0];
; #pragma unroll
;                         for (int e = 0; e < 4; ++e) rs[e] = (f32x2){ex2(lgh * (float)(idx_ + e + 1)), 0.0625f * ex2(lgh * (float)(63 - idx_ - e))};
;                     }
; #pragma unroll
;                     for (int bj = 0; bj < 2; ++bj)
; #pragma unroll
;                         for (int n = 0; n < 2; ++n) {
;                             float v[4];
; #pragma unroll
;                             for (int e = 0; e < 4; ++e) v[e] = acc[ai][bj][m][n][e];
;                             epi_store<EPI, LNI>(p, row0, bcol + bj * 128 + wc * 32 + n * 16 + fr + oz, lrow0, v, sa, rs, lg_[bj][n], lb_[bj][n]);
	v_mov_b32_e32 v233, v141
	v_add_u32_e32 v224, v192, v179
	v_mul_hi_i32 v225, v224, s68
	v_lshrrev_b32_e32 v226, 31, v225
	v_ashrrev_i32_e32 v225, 12, v225
	v_add_u32_e32 v225, v225, v226
	v_mul_i32_i24_e32 v226, 0xffffdff0, v225
	v_add3_u32 v226, v224, v226, 48
	v_lshrrev_b32_e32 v227, 4, v226
	v_and_b32_e32 v227, 0xfffffc, v227
	v_add_lshl_u32 v228, v227, v225, 8
	v_lshlrev_b32_e32 v225, 2, v226
	v_and_b32_e32 v229, 32, v225
	v_and_b32_e32 v225, 7, v224
	v_bfe_u32 v230, v226, 4, 2
	v_lshlrev_b32_e32 v232, 1, v225
	v_lshl_add_u64 v[234:235], s[20:21], 0, v[232:233]
	v_add_u32_e32 v236, v228, v121
	v_or3_b32 v236, v236, v122, v230
	v_ashrrev_i32_e32 v237, 31, v236
	v_lshlrev_b64 v[236:237], 6, v[236:237]
	v_or3_b32 v236, v236, v229, v191
	v_lshl_add_u64 v[236:237], v[236:237], 4, v[234:235]
	global_load_dwordx2 v[220:221], v[236:237], off
	v_lshlrev_b32_e32 v41, 16, v222
	v_add_f32_e32 v38, 1.0, v38
	s_nop 0
	v_mul_f32_e32 v40, 0xbfb8aa3b, v33
	v_exp_f32_e32 v40, v40
	v_rcp_f32_e32 v39, v38
	s_nop 0
	v_mul_f32_e32 v32, v32, v39
	v_mul_f32_e32 v32, v32, v41
	v_mul_f32_e32 v32, v64, v32
	v_add_f32_e32 v38, 1.0, v40
	v_cvt_pk_bf16_f32 v32, v32, s0
	global_store_short v[48:49], v32, off offset:288
	v_and_b32_e32 v32, 0xffff0000, v222
	v_mul_f32_e32 v39, 0xbfb8aa3b, v34
	v_exp_f32_e32 v39, v39
	v_rcp_f32_e32 v36, v38
	s_nop 0
	v_mul_f32_e32 v33, v33, v36
	v_mul_f32_e32 v32, v33, v32
	v_add_f32_e32 v33, 1.0, v39
	v_mul_f32_e32 v32, v65, v32
	v_cvt_pk_bf16_f32 v32, v32, s0
	global_store_short v[52:53], v32, off offset:288
	v_mul_f32_e32 v38, 0xbfb8aa3b, v35
	v_exp_f32_e32 v38, v38
	v_lshlrev_b32_e32 v32, 16, v223
	v_rcp_f32_e32 v36, v33
	s_nop 0
	v_mul_f32_e32 v33, v34, v36
	v_mul_f32_e32 v32, v33, v32
	v_add_f32_e32 v33, 1.0, v38
	v_mul_f32_e32 v32, v66, v32
	v_cvt_pk_bf16_f32 v32, v32, s0
	global_store_short v[44:45], v32, off offset:288
	v_and_b32_e32 v32, 0xffff0000, v223
	v_rcp_f32_e32 v34, v33
	s_nop 0
	v_mul_f32_e32 v33, v35, v34
	v_mul_f32_e32 v32, v33, v32
	v_mul_f32_e32 v32, v67, v32
	v_cvt_pk_bf16_f32 v32, v32, s0
	global_store_short v[46:47], v32, off offset:288
	v_add_u32_e32 v32, v192, v179
	v_mul_hi_i32 v33, v32, s68
	v_lshrrev_b32_e32 v34, 31, v33
	v_ashrrev_i32_e32 v33, 12, v33
	v_add_u32_e32 v33, v33, v34
	v_mul_i32_i24_e32 v34, 0xffffdff0, v33
	v_add3_u32 v34, v32, v34, 48
	v_lshrrev_b32_e32 v35, 4, v34
	v_and_b32_e32 v35, 0xfffffc, v35
	v_add_lshl_u32 v47, v35, v33, 8
	v_lshlrev_b32_e32 v33, 2, v34
	v_and_b32_e32 v46, 32, v33
	v_and_b32_e32 v33, 7, v32
	v_bfe_u32 v48, v34, 4, 2
	v_lshlrev_b32_e32 v140, 1, v33
	v_add_u32_e32 v33, v47, v193
	v_or3_b32 v34, v33, v194, v48
	v_ashrrev_i32_e32 v35, 31, v34
	v_lshlrev_b64 v[34:35], 6, v[34:35]
	v_lshl_add_u64 v[40:41], s[20:21], 0, v[140:141]
	v_or3_b32 v34, v34, v46, v191
	v_lshl_add_u64 v[34:35], v[34:35], 4, v[40:41]
	v_mul_f32_e32 v33, 0xbfb8aa3b, v28
	v_exp_f32_e32 v34, v33
	v_ashrrev_i32_e32 v33, 31, v32
	v_lshlrev_b64 v[32:33], 12, v[32:33]
	v_lshl_add_u64 v[32:33], s[36:37], 0, v[32:33]
	v_add_f32_e32 v34, 1.0, v34
	v_lshl_add_u64 v[42:43], v[32:33], 0, v[146:147]
	ds_read_b128 v[36:39], v195 offset:640
	v_rcp_f32_e32 v33, v34
	s_nop 0
	v_mul_f32_e32 v28, v28, v33
	v_mul_f32_e32 v33, 0xbfb8aa3b, v29
	v_exp_f32_e32 v49, v33
	s_waitcnt vmcnt(14)
	v_add_u32_e32 v224, v47, v118
	v_or3_b32 v224, v224, v120, v48
	v_ashrrev_i32_e32 v225, 31, v224
	v_lshlrev_b64 v[224:225], 6, v[224:225]
	v_or3_b32 v224, v224, v46, v119
	v_lshl_add_u64 v[224:225], v[224:225], 4, v[40:41]
	global_load_dwordx2 v[222:223], v[224:225], off
	v_lshlrev_b32_e32 v32, 16, v216
	v_add_f32_e32 v49, 1.0, v49
	v_mul_f32_e32 v28, v28, v32
	ds_read_b128 v[32:35], v195 offset:704
	s_waitcnt lgkmcnt(1)
	v_mul_f32_e32 v28, v36, v28
	v_cvt_pk_bf16_f32 v28, v28, s0
	global_store_short v[42:43], v28, off
	v_and_b32_e32 v28, 0xffff0000, v216
	v_rcp_f32_e32 v44, v49
	s_nop 0
	v_mul_f32_e32 v29, v29, v44
	v_mul_f32_e32 v44, 0xbfb8aa3b, v30
	v_exp_f32_e32 v44, v44
	v_mul_f32_e32 v28, v29, v28
	v_mul_f32_e32 v28, v37, v28
	v_cvt_pk_bf16_f32 v49, v28, s0
	v_add_f32_e32 v44, 1.0, v44
	v_add_co_u32_e32 v28, vcc, s3, v42
	s_nop 0
	s_nop 0
	v_addc_co_u32_e32 v29, vcc, 0, v43, vcc
	v_mul_f32_e32 v51, 0xbfb8aa3b, v31
	v_exp_f32_e32 v51, v51
	global_store_short v[28:29], v49, off offset:-4096
	v_lshlrev_b32_e32 v49, 16, v217
	v_rcp_f32_e32 v50, v44
	s_nop 0
	v_mul_f32_e32 v30, v30, v50
	v_add_f32_e32 v44, 1.0, v51
	v_mul_f32_e32 v30, v30, v49
	v_mul_f32_e32 v30, v38, v30
	v_cvt_pk_bf16_f32 v30, v30, s0
	global_store_short v[28:29], v30, off
	v_and_b32_e32 v30, 0xffff0000, v217
	v_rcp_f32_e32 v45, v44
	s_nop 0
	v_mul_f32_e32 v31, v31, v45
	v_mul_f32_e32 v30, v31, v30
	v_mul_f32_e32 v30, v39, v30
	v_cvt_pk_bf16_f32 v44, v30, s0
	v_add_co_u32_e32 v30, vcc, s69, v42
	v_mul_f32_e32 v49, 0xbfb8aa3b, v24
	s_nop 0
	v_addc_co_u32_e32 v31, vcc, 0, v43, vcc
	global_store_short v[30:31], v44, off
	v_add_u32_e32 v44, v47, v126
	v_or3_b32 v44, v44, v149, v48
	v_ashrrev_i32_e32 v45, 31, v44
	v_lshlrev_b64 v[44:45], 6, v[44:45]
	v_or3_b32 v44, v44, v46, v127
	v_lshl_add_u64 v[44:45], v[44:45], 4, v[40:41]
	v_exp_f32_e32 v49, v49
	v_add_co_u32_e32 v50, vcc, s61, v42
	v_add_f32_e32 v49, 1.0, v49
	s_nop 0
	v_addc_co_u32_e32 v51, vcc, 0, v43, vcc
	v_mul_f32_e32 v53, 0xbfb8aa3b, v25
	v_exp_f32_e32 v53, v53
	v_rcp_f32_e32 v52, v49
	s_nop 0
	v_mul_f32_e32 v24, v24, v52
	v_add_f32_e32 v49, 1.0, v53
	s_waitcnt vmcnt(14)
; DI bf16_t f2bf(float x) { return (bf16_t)(cvt_pk(x, 0.f) & 0xffffu); }
; DI size_t vf_off(int item, int dvh, int j) { return ((size_t)((item * 16 + (dvh >> 5)) * 4 + (j >> 4)) * 64 + ((j >> 3) & 1) * 32 + (dvh & 31)) * 8 + (j & 7); }
;     ...
;     } else if (EPI == EPI_E5B) {
;         const u32x2 ov = *(const u32x2*)((const bf16_t*)(p.ws + OFF_VT1) + vf_off((((pos + 48) >> 6) * 4 + b) * 4 + (col >> 9), col & 511, (pos + 48) & 63));
;         bf16_t* d = (bf16_t*)(p.ws + OFF_YB) + (size_t)row0 * 2048 + col;
; #pragma unroll
;         for (int e = 0; e < 4; ++e) {
;             const unsigned ob = (e & 1) ? (ov[e >> 1] & 0xffff0000u) : (ov[e >> 1] << 16);
;             const float o = __uint_as_float(ob);
;             const float gte = v[e] / (1.f + __expf(-v[e]));
;             d[(size_t)e * 2048] = f2bf(gte * o * s_aux[lrow0 + e]);
;         }
; template <int EPI, int K, int LNI = -1>
; DI void ph_gemm(const Params& p, const bf16_t* __restrict__ A, const bf16_t* __restrict__ Bt, int N, float* s_aux) {
;     ...
; #pragma unroll
;                     for (int bj = 0; bj < 2; ++bj)
; #pragma unroll
;                         for (int n = 0; n < 2; ++n) {
;                             float v[4];
; #pragma unroll
;                             for (int e = 0; e < 4; ++e) v[e] = acc[ai][bj][m][n][e];
;                             epi_store<EPI, LNI>(p, row0, bcol + bj * 128 + wc * 32 + n * 16 + fr + oz, lrow0, v, sa, rs, lg_[bj][n], lb_[bj][n]);
	v_mov_b32_e32 v233, v141
	v_add_u32_e32 v224, v192, v180
	v_mul_hi_i32 v225, v224, s68
	v_lshrrev_b32_e32 v226, 31, v225
	v_ashrrev_i32_e32 v225, 12, v225
	v_add_u32_e32 v225, v225, v226
	v_mul_i32_i24_e32 v226, 0xffffdff0, v225
	v_add3_u32 v226, v224, v226, 48
	v_lshrrev_b32_e32 v227, 4, v226
	v_and_b32_e32 v227, 0xfffffc, v227
	v_add_lshl_u32 v228, v227, v225, 8
	v_lshlrev_b32_e32 v225, 2, v226
	v_and_b32_e32 v229, 32, v225
	v_and_b32_e32 v225, 7, v224
	v_bfe_u32 v230, v226, 4, 2
	v_lshlrev_b32_e32 v232, 1, v225
	v_add_u32_e32 v225, v228, v193
	v_or3_b32 v234, v225, v194, v230
	v_ashrrev_i32_e32 v235, 31, v234
	v_lshlrev_b64 v[234:235], 6, v[234:235]
	v_lshl_add_u64 v[226:227], s[20:21], 0, v[232:233]
	v_or3_b32 v234, v234, v229, v191
	v_lshl_add_u64 v[234:235], v[234:235], 4, v[226:227]
	global_load_dwordx2 v[216:217], v[234:235], off
	v_lshlrev_b32_e32 v54, 16, v218
	v_mul_f32_e32 v24, v24, v54
	v_mul_f32_e32 v24, v36, v24
	v_cvt_pk_bf16_f32 v24, v24, s0
	global_store_short v[42:43], v24, off offset:32
	v_and_b32_e32 v24, 0xffff0000, v218
	v_mul_f32_e32 v52, 0xbfb8aa3b, v26
	v_exp_f32_e32 v52, v52
	v_rcp_f32_e32 v44, v49
	s_nop 0
	v_mul_f32_e32 v25, v25, v44
	v_mul_f32_e32 v24, v25, v24
	v_add_f32_e32 v25, 1.0, v52
	v_mul_f32_e32 v24, v37, v24
	v_cvt_pk_bf16_f32 v24, v24, s0
	global_store_short v[50:51], v24, off offset:32
	v_mul_f32_e32 v49, 0xbfb8aa3b, v27
	v_exp_f32_e32 v49, v49
	v_lshlrev_b32_e32 v24, 16, v219
	v_rcp_f32_e32 v44, v25
	s_nop 0
	v_mul_f32_e32 v25, v26, v44
	v_mul_f32_e32 v24, v25, v24
	v_add_f32_e32 v25, 1.0, v49
	v_mul_f32_e32 v24, v38, v24
	v_cvt_pk_bf16_f32 v24, v24, s0
	global_store_short v[28:29], v24, off offset:32
	v_and_b32_e32 v24, 0xffff0000, v219
	v_rcp_f32_e32 v26, v25
	s_nop 0
	v_mul_f32_e32 v25, v27, v26
	v_mul_f32_e32 v24, v25, v24
	v_mul_f32_e32 v24, v39, v24
	v_cvt_pk_bf16_f32 v24, v24, s0
	global_store_short v[30:31], v24, off offset:32
	v_add_u32_e32 v24, v47, v121
	v_or3_b32 v24, v24, v122, v48
	v_ashrrev_i32_e32 v25, 31, v24
	v_lshlrev_b64 v[24:25], 6, v[24:25]
	v_or3_b32 v24, v24, v46, v191
	v_lshl_add_u64 v[24:25], v[24:25], 4, v[40:41]
	v_mul_f32_e32 v26, 0xbfb8aa3b, v20
	v_exp_f32_e32 v26, v26
	s_waitcnt vmcnt(14)
	v_mov_b32_e32 v233, v141
	v_add_u32_e32 v224, v192, v180
	v_mul_hi_i32 v225, v224, s68
	v_lshrrev_b32_e32 v226, 31, v225
	v_ashrrev_i32_e32 v225, 12, v225
	v_add_u32_e32 v225, v225, v226
	v_mul_i32_i24_e32 v226, 0xffffdff0, v225
	v_add3_u32 v226, v224, v226, 48
	v_lshrrev_b32_e32 v227, 4, v226
	v_and_b32_e32 v227, 0xfffffc, v227
	v_add_lshl_u32 v228, v227, v225, 8
	v_lshlrev_b32_e32 v225, 2, v226
	v_and_b32_e32 v229, 32, v225
	v_and_b32_e32 v225, 7, v224
	v_bfe_u32 v230, v226, 4, 2
	v_lshlrev_b32_e32 v232, 1, v225
	v_lshl_add_u64 v[226:227], s[20:21], 0, v[232:233]
	v_add_u32_e32 v234, v228, v126
	v_or3_b32 v234, v234, v149, v230
	v_ashrrev_i32_e32 v235, 31, v234
	v_lshlrev_b64 v[234:235], 6, v[234:235]
	v_or3_b32 v234, v234, v229, v127
	v_lshl_add_u64 v[234:235], v[234:235], 4, v[226:227]
	global_load_dwordx2 v[218:219], v[234:235], off
	v_lshlrev_b32_e32 v45, 16, v220
	v_add_f32_e32 v26, 1.0, v26
	s_nop 0
	v_mul_f32_e32 v44, 0xbfb8aa3b, v21
	v_exp_f32_e32 v44, v44
	v_rcp_f32_e32 v27, v26
	s_nop 0
	v_mul_f32_e32 v20, v20, v27
	v_mul_f32_e32 v20, v20, v45
	v_mul_f32_e32 v20, v36, v20
	v_add_f32_e32 v26, 1.0, v44
	v_cvt_pk_bf16_f32 v20, v20, s0
	global_store_short v[42:43], v20, off offset:256
	v_and_b32_e32 v20, 0xffff0000, v220
	v_mul_f32_e32 v27, 0xbfb8aa3b, v22
	v_exp_f32_e32 v27, v27
	v_rcp_f32_e32 v24, v26
	s_nop 0
	v_mul_f32_e32 v21, v21, v24
	v_mul_f32_e32 v20, v21, v20
	v_add_f32_e32 v21, 1.0, v27
	v_mul_f32_e32 v20, v37, v20
	v_cvt_pk_bf16_f32 v20, v20, s0
	global_store_short v[50:51], v20, off offset:256
	v_mul_f32_e32 v26, 0xbfb8aa3b, v23
	v_exp_f32_e32 v26, v26
	v_lshlrev_b32_e32 v20, 16, v221
	v_rcp_f32_e32 v24, v21
	s_nop 0
	v_mul_f32_e32 v21, v22, v24
	v_mul_f32_e32 v20, v21, v20
	v_add_f32_e32 v21, 1.0, v26
	v_mul_f32_e32 v20, v38, v20
	v_cvt_pk_bf16_f32 v20, v20, s0
	global_store_short v[28:29], v20, off offset:256
	v_and_b32_e32 v20, 0xffff0000, v221
	v_rcp_f32_e32 v22, v21
	s_nop 0
	v_mul_f32_e32 v21, v23, v22
	v_mul_f32_e32 v20, v21, v20
	v_mul_f32_e32 v20, v39, v20
	v_cvt_pk_bf16_f32 v20, v20, s0
	global_store_short v[30:31], v20, off offset:256
	v_add_u32_e32 v20, v47, v118
	v_or3_b32 v20, v20, v120, v48
	v_ashrrev_i32_e32 v21, 31, v20
	v_lshlrev_b64 v[20:21], 6, v[20:21]
	v_or3_b32 v20, v20, v46, v119
	v_lshl_add_u64 v[20:21], v[20:21], 4, v[40:41]
	v_mul_f32_e32 v22, 0xbfb8aa3b, v16
	v_exp_f32_e32 v22, v22
	s_waitcnt vmcnt(14)
; DI bf16_t f2bf(float x) { return (bf16_t)(cvt_pk(x, 0.f) & 0xffffu); }
; DI float ex2(float x) { return __builtin_amdgcn_exp2f(x); }
; DI size_t vf_off(int item, int dvh, int j) { return ((size_t)((item * 16 + (dvh >> 5)) * 4 + (j >> 4)) * 64 + ((j >> 3) & 1) * 32 + (dvh & 31)) * 8 + (j & 7); }
;     ...
;     } else if (EPI == EPI_E5B) {
;         const u32x2 ov = *(const u32x2*)((const bf16_t*)(p.ws + OFF_VT1) + vf_off((((pos + 48) >> 6) * 4 + b) * 4 + (col >> 9), col & 511, (pos + 48) & 63));
;         bf16_t* d = (bf16_t*)(p.ws + OFF_YB) + (size_t)row0 * 2048 + col;
; #pragma unroll
;         for (int e = 0; e < 4; ++e) {
;             const unsigned ob = (e & 1) ? (ov[e >> 1] & 0xffff0000u) : (ov[e >> 1] << 16);
;             const float o = __uint_as_float(ob);
;             const float gte = v[e] / (1.f + __expf(-v[e]));
;             d[(size_t)e * 2048] = f2bf(gte * o * s_aux[lrow0 + e]);
;         }
; template <int EPI, int K, int LNI = -1>
; DI void ph_gemm(const Params& p, const bf16_t* __restrict__ A, const bf16_t* __restrict__ Bt, int N, float* s_aux) {
;     ...
;             for (int ai = 0; ai < 2; ++ai)
; #pragma unroll
;                 for (int m = 0; m < 4; ++m) {
;                     const int lrow0 = ai * 128 + wr * 64 + m * 16 + fq * 4, row0 = brow + lrow0 + oz;
;                     f32x2 rs[4];
;                     if (EPI == EPI_RESID && LNI >= 0) {
;                         const f32x2* st_ = (const f32x2*)((unsigned char*)p.out + OFFO_STATS) + row0;
; #pragma unroll
;                         for (int e = 0; e < 4; ++e) rs[e] = st_[e];
;                     }
;                     if (EPI == EPI_E5) {
;                         const int idx_ = ((row0 % LT) + 48) & 63; const float lgh = lg_[0][0];
; #pragma unroll
;                         for (int e = 0; e < 4; ++e) rs[e] = (f32x2){ex2(lgh * (float)(idx_ + e + 1)), 0.0625f * ex2(lgh * (float)(63 - idx_ - e))};
;                     }
; #pragma unroll
;                     for (int bj = 0; bj < 2; ++bj)
; #pragma unroll
;                         for (int n = 0; n < 2; ++n) {
;                             float v[4];
; #pragma unroll
;                             for (int e = 0; e < 4; ++e) v[e] = acc[ai][bj][m][n][e];
;                             epi_store<EPI, LNI>(p, row0, bcol + bj * 128 + wc * 32 + n * 16 + fr + oz, lrow0, v, sa, rs, lg_[bj][n], lb_[bj][n]);
;                         }
	v_mov_b32_e32 v233, v141
	v_add_u32_e32 v224, v192, v180
	v_mul_hi_i32 v225, v224, s68
	v_lshrrev_b32_e32 v226, 31, v225
	v_ashrrev_i32_e32 v225, 12, v225
	v_add_u32_e32 v225, v225, v226
	v_mul_i32_i24_e32 v226, 0xffffdff0, v225
	v_add3_u32 v226, v224, v226, 48
	v_lshrrev_b32_e32 v227, 4, v226
	v_and_b32_e32 v227, 0xfffffc, v227
	v_add_lshl_u32 v228, v227, v225, 8
	v_lshlrev_b32_e32 v225, 2, v226
	v_and_b32_e32 v229, 32, v225
	v_and_b32_e32 v225, 7, v224
	v_bfe_u32 v230, v226, 4, 2
	v_lshlrev_b32_e32 v232, 1, v225
	v_lshl_add_u64 v[226:227], s[20:21], 0, v[232:233]
	v_add_u32_e32 v234, v228, v121
	v_or3_b32 v234, v234, v122, v230
	v_ashrrev_i32_e32 v235, 31, v234
	v_lshlrev_b64 v[234:235], 6, v[234:235]
	v_or3_b32 v234, v234, v229, v191
	v_lshl_add_u64 v[234:235], v[234:235], 4, v[226:227]
	global_load_dwordx2 v[220:221], v[234:235], off
	v_lshlrev_b32_e32 v25, 16, v222
	v_add_f32_e32 v22, 1.0, v22
	s_nop 0
	v_mul_f32_e32 v24, 0xbfb8aa3b, v17
	v_exp_f32_e32 v24, v24
	v_rcp_f32_e32 v23, v22
	s_nop 0
	v_mul_f32_e32 v16, v16, v23
	v_mul_f32_e32 v16, v16, v25
	v_mul_f32_e32 v16, v36, v16
	v_add_f32_e32 v22, 1.0, v24
	v_cvt_pk_bf16_f32 v16, v16, s0
	global_store_short v[42:43], v16, off offset:288
	v_and_b32_e32 v16, 0xffff0000, v222
	v_mul_f32_e32 v23, 0xbfb8aa3b, v18
	v_exp_f32_e32 v23, v23
	v_rcp_f32_e32 v20, v22
	s_nop 0
	v_mul_f32_e32 v17, v17, v20
	v_mul_f32_e32 v16, v17, v16
	v_add_f32_e32 v17, 1.0, v23
	v_mul_f32_e32 v16, v37, v16
	v_cvt_pk_bf16_f32 v16, v16, s0
	global_store_short v[50:51], v16, off offset:288
	v_mul_f32_e32 v22, 0xbfb8aa3b, v19
	v_exp_f32_e32 v22, v22
	v_lshlrev_b32_e32 v16, 16, v223
	v_rcp_f32_e32 v20, v17
	s_nop 0
	v_mul_f32_e32 v17, v18, v20
	v_mul_f32_e32 v16, v17, v16
	v_add_f32_e32 v17, 1.0, v22
	v_mul_f32_e32 v16, v38, v16
	v_cvt_pk_bf16_f32 v16, v16, s0
	global_store_short v[28:29], v16, off offset:288
	v_and_b32_e32 v16, 0xffff0000, v223
	v_rcp_f32_e32 v18, v17
	s_nop 0
	v_mul_f32_e32 v17, v19, v18
	v_mul_f32_e32 v16, v17, v16
	v_mul_f32_e32 v16, v39, v16
	v_cvt_pk_bf16_f32 v16, v16, s0
	global_store_short v[30:31], v16, off offset:288
	v_add_u32_e32 v16, v192, v180
	v_mul_hi_i32 v17, v16, s68
	v_lshrrev_b32_e32 v18, 31, v17
	v_ashrrev_i32_e32 v17, 12, v17
	v_add_u32_e32 v17, v17, v18
	v_mul_i32_i24_e32 v18, 0xffffdff0, v17
	v_add3_u32 v18, v16, v18, 48
	v_lshrrev_b32_e32 v19, 4, v18
	v_and_b32_e32 v19, 0xfffffc, v19
	v_add_lshl_u32 v24, v19, v17, 8
	v_lshlrev_b32_e32 v17, 2, v18
	v_and_b32_e32 v26, 32, v17
	v_and_b32_e32 v17, 7, v16
	v_bfe_u32 v25, v18, 4, 2
	v_lshlrev_b32_e32 v140, 1, v17
	v_add_u32_e32 v17, v24, v193
	v_or3_b32 v20, v17, v194, v25
	v_ashrrev_i32_e32 v21, 31, v20
	v_lshlrev_b64 v[20:21], 6, v[20:21]
	v_lshl_add_u64 v[18:19], s[20:21], 0, v[140:141]
	v_or3_b32 v20, v20, v26, v191
	v_lshl_add_u64 v[20:21], v[20:21], 4, v[18:19]
	v_mul_f32_e32 v17, 0xbfb8aa3b, v12
	v_exp_f32_e32 v22, v17
	v_ashrrev_i32_e32 v17, 31, v16
	v_lshlrev_b64 v[16:17], 12, v[16:17]
	v_lshl_add_u64 v[16:17], s[36:37], 0, v[16:17]
	v_add_f32_e32 v22, 1.0, v22
	v_lshl_add_u64 v[16:17], v[16:17], 0, v[146:147]
	v_mul_f32_e32 v27, 0xbfb8aa3b, v13
	v_exp_f32_e32 v27, v27
	v_rcp_f32_e32 v23, v22
	s_nop 0
	v_mul_f32_e32 v12, v12, v23
	v_add_f32_e32 v22, 1.0, v27
	s_waitcnt vmcnt(14)
	v_add_u32_e32 v224, v24, v118
	v_or3_b32 v224, v224, v120, v25
	v_ashrrev_i32_e32 v225, 31, v224
	v_lshlrev_b64 v[224:225], 6, v[224:225]
	v_or3_b32 v224, v224, v26, v119
	v_lshl_add_u64 v[224:225], v[224:225], 4, v[18:19]
	global_load_dwordx2 v[222:223], v[224:225], off
	v_lshlrev_b32_e32 v28, 16, v216
	v_mul_f32_e32 v12, v12, v28
	s_waitcnt lgkmcnt(0)
	v_mul_f32_e32 v12, v32, v12
	v_cvt_pk_bf16_f32 v12, v12, s0
	global_store_short v[16:17], v12, off
	v_and_b32_e32 v12, 0xffff0000, v216
	v_rcp_f32_e32 v20, v22
	s_nop 0
	v_mul_f32_e32 v13, v13, v20
	v_mul_f32_e32 v20, 0xbfb8aa3b, v14
	v_exp_f32_e32 v20, v20
	v_mul_f32_e32 v12, v13, v12
	v_mul_f32_e32 v12, v33, v12
	v_cvt_pk_bf16_f32 v22, v12, s0
	v_add_f32_e32 v20, 1.0, v20
	v_add_co_u32_e32 v12, vcc, s3, v16
	s_nop 0
	s_nop 0
	v_addc_co_u32_e32 v13, vcc, 0, v17, vcc
	v_mul_f32_e32 v27, 0xbfb8aa3b, v15
	v_exp_f32_e32 v27, v27
	global_store_short v[12:13], v22, off offset:-4096
	v_lshlrev_b32_e32 v22, 16, v217
	v_rcp_f32_e32 v23, v20
	s_nop 0
	v_mul_f32_e32 v14, v14, v23
	v_add_f32_e32 v20, 1.0, v27
	v_mul_f32_e32 v14, v14, v22
	v_mul_f32_e32 v14, v34, v14
	v_cvt_pk_bf16_f32 v14, v14, s0
	global_store_short v[12:13], v14, off
	v_and_b32_e32 v14, 0xffff0000, v217
	v_rcp_f32_e32 v21, v20
	s_nop 0
	v_mul_f32_e32 v15, v15, v21
	v_mul_f32_e32 v14, v15, v14
	v_mul_f32_e32 v14, v35, v14
	v_cvt_pk_bf16_f32 v20, v14, s0
	v_add_co_u32_e32 v14, vcc, s69, v16
	s_nop 1
	v_addc_co_u32_e32 v15, vcc, 0, v17, vcc
	global_store_short v[14:15], v20, off
	v_add_u32_e32 v20, v24, v126
	v_or3_b32 v20, v20, v149, v25
	v_ashrrev_i32_e32 v21, 31, v20
	v_lshlrev_b64 v[20:21], 6, v[20:21]
	v_or3_b32 v20, v20, v26, v127
	v_lshl_add_u64 v[20:21], v[20:21], 4, v[18:19]
	v_mul_f32_e32 v20, 0xbfb8aa3b, v8
	v_exp_f32_e32 v20, v20
	s_waitcnt vmcnt(14)
; #define BAR __builtin_amdgcn_s_barrier()
;     ...
;     } else if (EPI == EPI_E5B) {
;         const u32x2 ov = *(const u32x2*)((const bf16_t*)(p.ws + OFF_VT1) + vf_off((((pos + 48) >> 6) * 4 + b) * 4 + (col >> 9), col & 511, (pos + 48) & 63));
;         bf16_t* d = (bf16_t*)(p.ws + OFF_YB) + (size_t)row0 * 2048 + col;
; #pragma unroll
;         for (int e = 0; e < 4; ++e) {
;             const unsigned ob = (e & 1) ? (ov[e >> 1] & 0xffff0000u) : (ov[e >> 1] << 16);
; template <int EPI, int K, int LNI = -1>
; DI void ph_gemm(const Params& p, const bf16_t* __restrict__ A, const bf16_t* __restrict__ Bt, int N, float* s_aux) {
;     ...
;             for (int ai = 0; ai < 2; ++ai)
; #pragma unroll
;                 for (int m = 0; m < 4; ++m) {
;                     const int lrow0 = ai * 128 + wr * 64 + m * 16 + fq * 4, row0 = brow + lrow0 + oz;
;                     f32x2 rs[4];
;                     if (EPI == EPI_RESID && LNI >= 0) {
;                         const f32x2* st_ = (const f32x2*)((unsigned char*)p.out + OFFO_STATS) + row0;
; #pragma unroll
;                         for (int e = 0; e < 4; ++e) rs[e] = st_[e];
;                     }
;                     if (EPI == EPI_E5) {
;                         const int idx_ = ((row0 % LT) + 48) & 63; const float lgh = lg_[0][0];
; #pragma unroll
;                         for (int e = 0; e < 4; ++e) rs[e] = (f32x2){ex2(lgh * (float)(idx_ + e + 1)), 0.0625f * ex2(lgh * (float)(63 - idx_ - e))};
;                     }
; #pragma unroll
;                     for (int bj = 0; bj < 2; ++bj)
; #pragma unroll
;                         for (int n = 0; n < 2; ++n) {
;                             float v[4];
; #pragma unroll
;                             for (int e = 0; e < 4; ++e) v[e] = acc[ai][bj][m][n][e];
;                             epi_store<EPI, LNI>(p, row0, bcol + bj * 128 + wc * 32 + n * 16 + fr + oz, lrow0, v, sa, rs, lg_[bj][n], lb_[bj][n]);
;                         }
;                 }
;         }
;         if (!has_next) break;
; #pragma unroll
;         for (int a = 0; a < 2; ++a)
; #pragma unroll
;             for (int b = 0; b < 2; ++b)
; #pragma unroll
;                 for (int m = 0; m < 4; ++m)
; #pragma unroll
;                     for (int n = 0; n < 2; ++n) acc[a][b][m][n] = (f32x4){0.f, 0.f, 0.f, 0.f};
;         pm = npm; pn = npn; cA = nA; cB = nB; it = itn; ++cnt;
;         if (wr == 1) BAR;
;     }
	v_lshlrev_b32_e32 v30, 16, v218
	v_add_f32_e32 v27, 1.0, v20
	v_add_co_u32_e32 v20, vcc, s61, v16
	s_nop 0
	s_nop 0
	v_addc_co_u32_e32 v21, vcc, 0, v17, vcc
	v_mul_f32_e32 v29, 0xbfb8aa3b, v9
	v_exp_f32_e32 v29, v29
	v_rcp_f32_e32 v28, v27
	s_nop 0
	v_mul_f32_e32 v8, v8, v28
	v_mul_f32_e32 v8, v8, v30
	v_mul_f32_e32 v8, v32, v8
	v_add_f32_e32 v27, 1.0, v29
	v_cvt_pk_bf16_f32 v8, v8, s0
	global_store_short v[16:17], v8, off offset:32
	v_and_b32_e32 v8, 0xffff0000, v218
	v_mul_f32_e32 v28, 0xbfb8aa3b, v10
	v_exp_f32_e32 v28, v28
	v_rcp_f32_e32 v22, v27
	s_nop 0
	v_mul_f32_e32 v9, v9, v22
	v_mul_f32_e32 v8, v9, v8
	v_add_f32_e32 v9, 1.0, v28
	v_mul_f32_e32 v8, v33, v8
	v_cvt_pk_bf16_f32 v8, v8, s0
	global_store_short v[20:21], v8, off offset:32
	v_mul_f32_e32 v27, 0xbfb8aa3b, v11
	v_exp_f32_e32 v27, v27
	v_lshlrev_b32_e32 v8, 16, v219
	v_rcp_f32_e32 v22, v9
	s_nop 0
	v_mul_f32_e32 v9, v10, v22
	v_mul_f32_e32 v8, v9, v8
	v_add_f32_e32 v9, 1.0, v27
	v_mul_f32_e32 v8, v34, v8
	v_cvt_pk_bf16_f32 v8, v8, s0
	global_store_short v[12:13], v8, off offset:32
	v_and_b32_e32 v8, 0xffff0000, v219
	v_rcp_f32_e32 v10, v9
	s_nop 0
	v_mul_f32_e32 v9, v11, v10
	v_mul_f32_e32 v8, v9, v8
	v_mul_f32_e32 v8, v35, v8
	v_cvt_pk_bf16_f32 v8, v8, s0
	global_store_short v[14:15], v8, off offset:32
	v_add_u32_e32 v8, v24, v121
	v_or3_b32 v8, v8, v122, v25
	v_ashrrev_i32_e32 v9, 31, v8
	v_lshlrev_b64 v[8:9], 6, v[8:9]
	v_or3_b32 v8, v8, v26, v191
	v_lshl_add_u64 v[8:9], v[8:9], 4, v[18:19]
	v_mul_f32_e32 v10, 0xbfb8aa3b, v4
	v_exp_f32_e32 v10, v10
	s_waitcnt vmcnt(13)
	v_lshlrev_b32_e32 v23, 16, v220
	v_add_f32_e32 v10, 1.0, v10
	s_nop 0
	v_mul_f32_e32 v22, 0xbfb8aa3b, v5
	v_exp_f32_e32 v22, v22
	v_rcp_f32_e32 v11, v10
	s_nop 0
	v_mul_f32_e32 v4, v4, v11
	v_mul_f32_e32 v4, v4, v23
	v_mul_f32_e32 v4, v32, v4
	v_add_f32_e32 v10, 1.0, v22
	v_cvt_pk_bf16_f32 v4, v4, s0
	global_store_short v[16:17], v4, off offset:256
	v_and_b32_e32 v4, 0xffff0000, v220
	v_mul_f32_e32 v11, 0xbfb8aa3b, v6
	v_exp_f32_e32 v11, v11
	v_rcp_f32_e32 v8, v10
	s_nop 0
	v_mul_f32_e32 v5, v5, v8
	v_mul_f32_e32 v4, v5, v4
	v_add_f32_e32 v5, 1.0, v11
	v_mul_f32_e32 v4, v33, v4
	v_cvt_pk_bf16_f32 v4, v4, s0
	global_store_short v[20:21], v4, off offset:256
	v_mul_f32_e32 v10, 0xbfb8aa3b, v7
	v_exp_f32_e32 v10, v10
	v_lshlrev_b32_e32 v4, 16, v221
	v_rcp_f32_e32 v8, v5
	s_nop 0
	v_mul_f32_e32 v5, v6, v8
	v_mul_f32_e32 v4, v5, v4
	v_add_f32_e32 v5, 1.0, v10
	v_mul_f32_e32 v4, v34, v4
	v_cvt_pk_bf16_f32 v4, v4, s0
	global_store_short v[12:13], v4, off offset:256
	v_and_b32_e32 v4, 0xffff0000, v221
	v_rcp_f32_e32 v6, v5
	s_nop 0
	v_mul_f32_e32 v5, v7, v6
	v_mul_f32_e32 v4, v5, v4
	v_mul_f32_e32 v4, v35, v4
	v_cvt_pk_bf16_f32 v4, v4, s0
	global_store_short v[14:15], v4, off offset:256
	v_add_u32_e32 v4, v24, v118
	v_or3_b32 v4, v4, v120, v25
	v_ashrrev_i32_e32 v5, 31, v4
	v_lshlrev_b64 v[4:5], 6, v[4:5]
	v_or3_b32 v4, v4, v26, v119
	v_lshl_add_u64 v[4:5], v[4:5], 4, v[18:19]
	v_mul_f32_e32 v6, 0xbfb8aa3b, v0
	v_exp_f32_e32 v6, v6
	s_waitcnt vmcnt(12)
	v_lshlrev_b32_e32 v9, 16, v222
	v_add_f32_e32 v6, 1.0, v6
	s_nop 0
	v_mul_f32_e32 v8, 0xbfb8aa3b, v1
	v_exp_f32_e32 v8, v8
	v_rcp_f32_e32 v7, v6
	s_nop 0
	v_mul_f32_e32 v0, v0, v7
	v_mul_f32_e32 v0, v0, v9
	v_mul_f32_e32 v0, v32, v0
	v_add_f32_e32 v6, 1.0, v8
	v_cvt_pk_bf16_f32 v0, v0, s0
	global_store_short v[16:17], v0, off offset:288
	v_and_b32_e32 v0, 0xffff0000, v222
	v_mul_f32_e32 v7, 0xbfb8aa3b, v2
	v_exp_f32_e32 v7, v7
	v_rcp_f32_e32 v4, v6
	s_nop 0
	v_mul_f32_e32 v1, v1, v4
	v_mul_f32_e32 v0, v1, v0
	v_add_f32_e32 v1, 1.0, v7
	v_mul_f32_e32 v0, v33, v0
	v_cvt_pk_bf16_f32 v0, v0, s0
	global_store_short v[20:21], v0, off offset:288
	v_mul_f32_e32 v6, 0xbfb8aa3b, v3
	v_exp_f32_e32 v6, v6
	v_lshlrev_b32_e32 v0, 16, v223
	v_rcp_f32_e32 v4, v1
	s_nop 0
	v_mul_f32_e32 v1, v2, v4
	v_mul_f32_e32 v0, v1, v0
	v_add_f32_e32 v1, 1.0, v6
	v_mul_f32_e32 v0, v34, v0
	v_cvt_pk_bf16_f32 v0, v0, s0
	global_store_short v[12:13], v0, off offset:288
	v_and_b32_e32 v0, 0xffff0000, v223
	v_rcp_f32_e32 v2, v1
	s_nop 0
	v_mul_f32_e32 v1, v3, v2
	v_mul_f32_e32 v0, v1, v0
	v_mul_f32_e32 v0, v35, v0
	v_cvt_pk_bf16_f32 v0, v0, s0
	s_andn2_b64 vcc, exec, s[28:29]
	s_mov_b64 s[10:11], -1
	global_store_short v[14:15], v0, off offset:288
	s_cbranch_vccnz .LBB0_1626
	s_and_saveexec_b64 s[10:11], s[6:7]
	s_xor_b64 s[10:11], exec, s[10:11]
	s_cbranch_execz .LBB0_1625
	s_barrier
	s_branch .LBB0_1625

; DI f32x16 mfma32(bf16x8 a, bf16x8 b, f32x16 c) { return __builtin_amdgcn_mfma_f32_32x32x16_bf16(a, b, c, 0, 0, 0); }
; DI f32x16 zero16() { f32x16 z; for (int i = 0; i < 16; ++i) z[i] = 0.f; return z; }
; template <int EPI, int K, int LNI>
; DI void gemm_tail_unit(const Params& p, const bf16_t* __restrict__ A, const bf16_t* __restrict__ Bt, const int un, float* s_aux) {
;     ...
;     f32x16 acc[2][2];
;     acc[0][0] = zero16(); acc[0][1] = zero16(); acc[1][0] = zero16(); acc[1][1] = zero16();
;     const bf16_t* ap = A + (size_t)(ROW0 + r) * K + w * KS + h * 8;
;     const bf16_t* bp = Bt + (size_t)(col0 + r) * K + w * KS + h * 8;
; #pragma unroll 8
;     for (int s = 0; s < KS / 16; ++s) {
;         const bf16x8 a0 = *(const bf16x8*)(ap + s * 16), a1 = *(const bf16x8*)(ap + (size_t)32 * K + s * 16);
;         const bf16x8 b0 = *(const bf16x8*)(bp + s * 16), b1 = *(const bf16x8*)(bp + (size_t)32 * K + s * 16);
;         acc[0][0] = mfma32(a0, b0, acc[0][0]); acc[0][1] = mfma32(a0, b1, acc[0][1]);
;         acc[1][0] = mfma32(a1, b0, acc[1][0]); acc[1][1] = mfma32(a1, b1, acc[1][1]);
;     }
;     float* red = (float*)dsm;
; #pragma unroll
;     for (int i = 0; i < 2; ++i)
; #pragma unroll
;         for (int j = 0; j < 2; ++j)
; #pragma unroll
;             for (int reg = 0; reg < 16; ++reg) red[((w * 4 + i * 2 + j) * 16 + reg) * 64 + lane] = acc[i][j][reg];
.LBB0_1644:
	s_or_b64 exec, exec, s[10:11]
	v_ashrrev_i32_e32 v117, 6, v66
	v_and_b32_e32 v67, 31, v66
	v_lshlrev_b32_e32 v2, 7, v117
	v_lshlrev_b32_e32 v64, 11, v67
	v_ashrrev_i32_e32 v3, 31, v2
	v_bfe_u32 v116, v66, 5, 1
	v_lshl_add_u64 v[0:1], s[40:41], 0, v[64:65]
	v_lshlrev_b64 v[4:5], 1, v[2:3]
	v_lshl_add_u64 v[0:1], v[0:1], 0, v[4:5]
	v_lshlrev_b32_e32 v6, 4, v116
	v_mov_b32_e32 v7, v65
	v_add_u32_e32 v106, s3, v67
	v_lshl_add_u64 v[12:13], v[0:1], 0, v[6:7]
	v_ashrrev_i32_e32 v107, 31, v106
	v_lshlrev_b64 v[8:9], 11, v[106:107]
	v_add_co_u32_e32 v0, vcc, s15, v12
	v_lshl_add_u64 v[8:9], s[22:23], 0, v[8:9]
	s_nop 0
	v_addc_co_u32_e32 v1, vcc, 0, v13, vcc
	global_load_dwordx4 v[0:3], v[0:1], off
	v_lshl_add_u64 v[4:5], v[8:9], 0, v[4:5]
	v_lshl_add_u64 v[108:109], v[4:5], 0, v[6:7]
	v_add_co_u32_e32 v112, vcc, s27, v108
	v_lshl_add_u64 v[110:111], v[12:13], 0, s[8:9]
	s_nop 0
	v_addc_co_u32_e32 v113, vcc, 0, v109, vcc
	global_load_dwordx4 v[4:7], v[108:109], off
	global_load_dwordx4 v[70:73], v[110:111], off offset:224
	global_load_dwordx4 v[74:77], v[108:109], off offset:224
	global_load_dwordx4 v[8:11], v[112:113], off
	global_load_dwordx4 v[78:81], v[112:113], off offset:32
	v_add_co_u32_e32 v114, vcc, s26, v12
	v_lshlrev_b32_e32 v64, 3, v116
	s_nop 0
	v_addc_co_u32_e32 v115, vcc, 0, v13, vcc
	s_add_i32 s45, s45, s58
	s_add_i32 s44, s44, s34
	s_waitcnt vmcnt(4)
	v_mfma_f32_32x32x16_bf16 v[48:63], v[0:3], v[4:7], 0
	s_waitcnt vmcnt(1)
	v_mfma_f32_32x32x16_bf16 v[32:47], v[0:3], v[8:11], 0
	global_load_dwordx4 v[0:3], v[114:115], off
	global_load_dwordx4 v[82:85], v[110:111], off offset:32
	global_load_dwordx4 v[86:89], v[114:115], off offset:32
	global_load_dwordx4 v[90:93], v[108:109], off offset:32
	global_load_dwordx4 v[94:97], v[110:111], off offset:64
	global_load_dwordx4 v[98:101], v[108:109], off offset:64
	s_waitcnt vmcnt(5)
	v_mfma_f32_32x32x16_bf16 v[16:31], v[0:3], v[4:7], 0
	v_mfma_f32_32x32x16_bf16 v[0:15], v[0:3], v[8:11], 0
	s_waitcnt vmcnt(2)
	v_mfma_f32_32x32x16_bf16 v[48:63], v[82:85], v[90:93], v[48:63]
	v_mfma_f32_32x32x16_bf16 v[32:47], v[82:85], v[78:81], v[32:47]
	v_mfma_f32_32x32x16_bf16 v[0:15], v[86:89], v[78:81], v[0:15]
	global_load_dwordx4 v[78:81], v[112:113], off offset:64
	global_load_dwordx4 v[82:85], v[112:113], off offset:96
	v_mfma_f32_32x32x16_bf16 v[16:31], v[86:89], v[90:93], v[16:31]
	s_waitcnt vmcnt(2)
	v_mfma_f32_32x32x16_bf16 v[48:63], v[94:97], v[98:101], v[48:63]
	s_waitcnt vmcnt(1)
	v_mfma_f32_32x32x16_bf16 v[32:47], v[94:97], v[78:81], v[32:47]
	global_load_dwordx4 v[86:89], v[114:115], off offset:64
	global_load_dwordx4 v[90:93], v[110:111], off offset:96
	global_load_dwordx4 v[94:97], v[114:115], off offset:96
	s_waitcnt vmcnt(2)
	v_mfma_f32_32x32x16_bf16 v[16:31], v[86:89], v[98:101], v[16:31]
	global_load_dwordx4 v[98:101], v[108:109], off offset:96
	global_load_dwordx4 v[102:105], v[110:111], off offset:128
	v_mfma_f32_32x32x16_bf16 v[0:15], v[86:89], v[78:81], v[0:15]
	global_load_dwordx4 v[78:81], v[108:109], off offset:128
	s_waitcnt vmcnt(4)
	v_mfma_f32_32x32x16_bf16 v[32:47], v[90:93], v[82:85], v[32:47]
	s_waitcnt vmcnt(3)
	v_mfma_f32_32x32x16_bf16 v[0:15], v[94:97], v[82:85], v[0:15]
	global_load_dwordx4 v[82:85], v[112:113], off offset:128
	global_load_dwordx4 v[86:89], v[112:113], off offset:160
	s_waitcnt vmcnt(4)
	v_mfma_f32_32x32x16_bf16 v[48:63], v[90:93], v[98:101], v[48:63]
	v_mfma_f32_32x32x16_bf16 v[16:31], v[94:97], v[98:101], v[16:31]
	global_load_dwordx4 v[90:93], v[114:115], off offset:128
	global_load_dwordx4 v[94:97], v[110:111], off offset:160
	global_load_dwordx4 v[98:101], v[114:115], off offset:160
	s_waitcnt vmcnt(5)
	v_mfma_f32_32x32x16_bf16 v[48:63], v[102:105], v[78:81], v[48:63]
	s_waitcnt vmcnt(4)
	v_mfma_f32_32x32x16_bf16 v[32:47], v[102:105], v[82:85], v[32:47]
	s_waitcnt vmcnt(2)
	v_mfma_f32_32x32x16_bf16 v[16:31], v[90:93], v[78:81], v[16:31]
	global_load_dwordx4 v[78:81], v[108:109], off offset:160
	v_mfma_f32_32x32x16_bf16 v[0:15], v[90:93], v[82:85], v[0:15]
	global_load_dwordx4 v[82:85], v[110:111], off offset:192
	global_load_dwordx4 v[90:93], v[108:109], off offset:192
	s_waitcnt vmcnt(4)
	v_mfma_f32_32x32x16_bf16 v[32:47], v[94:97], v[86:89], v[32:47]
	s_waitcnt vmcnt(2)
	v_mfma_f32_32x32x16_bf16 v[48:63], v[94:97], v[78:81], v[48:63]
	v_mfma_f32_32x32x16_bf16 v[16:31], v[98:101], v[78:81], v[16:31]
	global_load_dwordx4 v[78:81], v[112:113], off offset:192
	v_mfma_f32_32x32x16_bf16 v[0:15], v[98:101], v[86:89], v[0:15]
	global_load_dwordx4 v[86:89], v[114:115], off offset:192
	global_load_dwordx4 v[94:97], v[112:113], off offset:224
	s_waitcnt vmcnt(3)
	v_mfma_f32_32x32x16_bf16 v[48:63], v[82:85], v[90:93], v[48:63]
	s_waitcnt vmcnt(2)
	v_mfma_f32_32x32x16_bf16 v[32:47], v[82:85], v[78:81], v[32:47]
	global_load_dwordx4 v[82:85], v[114:115], off offset:224
	s_waitcnt vmcnt(2)
	v_mfma_f32_32x32x16_bf16 v[16:31], v[86:89], v[90:93], v[16:31]
	v_and_b32_e32 v90, 63, v66
	v_lshl_add_u32 v90, v90, 2, 0
	v_lshl_add_u32 v91, v117, 14, v90
	v_mfma_f32_32x32x16_bf16 v[0:15], v[86:89], v[78:81], v[0:15]
	v_mfma_f32_32x32x16_bf16 v[48:63], v[70:73], v[74:77], v[48:63]
	s_nop 11
	ds_write2st64_b32 v91, v48, v49 offset1:1
	ds_write2st64_b32 v91, v50, v51 offset0:2 offset1:3
	ds_write2st64_b32 v91, v52, v53 offset0:4 offset1:5
	s_waitcnt vmcnt(1)
	v_mfma_f32_32x32x16_bf16 v[32:47], v[70:73], v[94:97], v[32:47]
	ds_write2st64_b32 v91, v54, v55 offset0:6 offset1:7
	ds_write2st64_b32 v91, v56, v57 offset0:8 offset1:9
	ds_write2st64_b32 v91, v58, v59 offset0:10 offset1:11
	ds_write2st64_b32 v91, v60, v61 offset0:12 offset1:13
	ds_write2st64_b32 v91, v62, v63 offset0:14 offset1:15
	s_nop 6
	ds_write2st64_b32 v91, v32, v33 offset0:16 offset1:17
	ds_write2st64_b32 v91, v34, v35 offset0:18 offset1:19
	v_add_u32_e32 v32, 0x1c000, v90
	s_waitcnt vmcnt(0)
; DI bf16_t f2bf(float x) { return (bf16_t)(cvt_pk(x, 0.f) & 0xffffu); }
; DI size_t vf_off(int item, int dvh, int j) { return ((size_t)((item * 16 + (dvh >> 5)) * 4 + (j >> 4)) * 64 + ((j >> 3) & 1) * 32 + (dvh & 31)) * 8 + (j & 7); }
;     ...
;         const u32x2 ov = *(const u32x2*)((const bf16_t*)(p.ws + OFF_VT1) + vf_off((((pos + 48) >> 6) * 4 + b) * 4 + (col >> 9), col & 511, (pos + 48) & 63));
;         bf16_t* d = (bf16_t*)(p.ws + OFF_YB) + (size_t)row0 * 2048 + col;
; #pragma unroll
;         for (int e = 0; e < 4; ++e) {
;             const unsigned ob = (e & 1) ? (ov[e >> 1] & 0xffff0000u) : (ov[e >> 1] << 16);
;             const float o = __uint_as_float(ob);
;             const float gte = v[e] / (1.f + __expf(-v[e]));
;             d[(size_t)e * 2048] = f2bf(gte * o * s_aux[lrow0 + e]);
; template <int EPI, int K, int LNI>
; DI void gemm_tail_unit(const Params& p, const bf16_t* __restrict__ A, const bf16_t* __restrict__ Bt, const int un, float* s_aux) {
;     ...
;     __syncthreads();
;     {
;         const int tile = w >> 1, i = tile >> 1, j = tile & 1;
; #pragma unroll
;         for (int gg = 0; gg < 2; ++gg) {
;             const int g = 2 * (w & 1) + gg;
;             float v[4];
; #pragma unroll
;             for (int e = 0; e < 4; ++e) {
;                 float sacc = 0.f;
; #pragma unroll
;                 for (int wv = 0; wv < 8; ++wv) sacc += red[((wv * 4 + tile) * 16 + 4 * g + e) * 64 + lane];
;                 v[e] = sacc;
;             }
;             const int lrow0 = i * 32 + 8 * g + 4 * h;
	v_mfma_f32_32x32x16_bf16 v[16:31], v[82:85], v[74:77], v[16:31]
	ds_write2st64_b32 v91, v36, v37 offset0:20 offset1:21
	ds_write2st64_b32 v91, v38, v39 offset0:22 offset1:23
	ds_write2st64_b32 v91, v40, v41 offset0:24 offset1:25
	ds_write2st64_b32 v91, v42, v43 offset0:26 offset1:27
	ds_write2st64_b32 v91, v44, v45 offset0:28 offset1:29
	ds_write2st64_b32 v91, v46, v47 offset0:30 offset1:31
	s_nop 5
	ds_write2st64_b32 v91, v16, v17 offset0:32 offset1:33
	ds_write2st64_b32 v91, v18, v19 offset0:34 offset1:35
	ds_write2st64_b32 v91, v20, v21 offset0:36 offset1:37
	ds_write2st64_b32 v91, v22, v23 offset0:38 offset1:39
	ds_write2st64_b32 v91, v24, v25 offset0:40 offset1:41
	ds_write2st64_b32 v91, v26, v27 offset0:42 offset1:43
	ds_write2st64_b32 v91, v28, v29 offset0:44 offset1:45
	ds_write2st64_b32 v91, v30, v31 offset0:46 offset1:47
	v_mfma_f32_32x32x16_bf16 v[0:15], v[82:85], v[94:97], v[0:15]
	s_nop 11
	ds_write2st64_b32 v91, v0, v1 offset0:48 offset1:49
	ds_write2st64_b32 v91, v2, v3 offset0:50 offset1:51
	ds_write2st64_b32 v91, v4, v5 offset0:52 offset1:53
	ds_write2st64_b32 v91, v6, v7 offset0:54 offset1:55
	ds_write2st64_b32 v91, v8, v9 offset0:56 offset1:57
	ds_write2st64_b32 v91, v10, v11 offset0:58 offset1:59
	ds_write2st64_b32 v91, v12, v13 offset0:60 offset1:61
	ds_write2st64_b32 v91, v14, v15 offset0:62 offset1:63
	v_ashrrev_i32_e32 v0, 7, v66
	v_lshlrev_b32_e32 v1, 1, v117
	v_and_b32_e32 v22, 2, v1
	v_lshlrev_b32_e32 v23, 12, v0
	v_lshl_or_b32 v26, v22, 10, v23
	v_add_u32_e32 v20, v90, v26
	s_waitcnt lgkmcnt(0)
	s_barrier
	ds_read2st64_b32 v[4:5], v20 offset1:1
	ds_read2st64_b32 v[6:7], v20 offset0:64 offset1:65
	v_ashrrev_i32_e32 v1, 3, v66
	v_and_b32_e32 v1, 0xffffffe0, v1
	v_lshl_or_b32 v24, v116, 2, v1
	s_waitcnt lgkmcnt(1)
	v_add_f32_e32 v4, 0, v4
	v_lshl_or_b32 v27, v22, 3, v24
	s_waitcnt lgkmcnt(0)
	v_add_f32_e32 v6, v4, v6
	v_add_u32_e32 v4, 0x8000, v27
	v_mul_hi_i32 v16, v4, s28
	v_lshrrev_b32_e32 v17, 31, v16
	v_ashrrev_i32_e32 v16, 12, v16
	v_add_u32_e32 v16, v16, v17
	v_lshlrev_b32_e32 v0, 5, v0
	v_mul_i32_i24_e32 v17, 0xffffdff0, v16
	v_and_b32_e32 v0, 32, v0
	v_add3_u32 v18, v27, v17, s29
	v_add_u32_e32 v1, s3, v0
	v_lshrrev_b32_e32 v17, 4, v18
	v_lshrrev_b32_e32 v1, 3, v1
	v_and_b32_e32 v19, 0xfffffc, v17
	v_and_or_b32 v25, v1, 60, v69
	v_add_u32_e32 v16, v19, v16
	v_lshl_add_u32 v16, v16, 8, v25
	v_and_or_b32 v16, v17, 3, v16
	v_ashrrev_i32_e32 v17, 31, v16
	v_lshlrev_b32_e32 v18, 2, v18
	v_lshlrev_b64 v[16:17], 6, v[16:17]
	v_and_b32_e32 v18, 32, v18
	v_lshl_add_u64 v[2:3], s[20:21], 0, v[64:65]
	v_or3_b32 v16, v16, v18, v67
	v_lshl_add_u64 v[16:17], v[16:17], 4, v[2:3]
	ds_read2st64_b32 v[8:9], v20 offset0:66 offset1:67
	ds_read2st64_b32 v[10:11], v20 offset0:2 offset1:3
	ds_read2st64_b32 v[12:13], v20 offset0:128 offset1:129
	ds_read2st64_b32 v[14:15], v20 offset0:192 offset1:193
	global_load_dwordx2 v[16:17], v[16:17], off
	v_add_u32_e32 v28, 0x10000, v90
	v_add_u32_e32 v29, 0x14000, v90
	s_waitcnt lgkmcnt(1)
	v_add_f32_e32 v6, v6, v12
	v_add_u32_e32 v30, 0x18000, v90
	v_or_b32_e32 v34, 0x100, v26
	v_add_f32_e32 v5, 0, v5
	s_waitcnt lgkmcnt(0)
	v_add_f32_e32 v6, v6, v14
	v_add_u32_e32 v12, v28, v26
	v_add_u32_e32 v14, v29, v26
	v_add_u32_e32 v31, v30, v26
	v_add_u32_e32 v33, v32, v26
	v_add_u32_e32 v35, v28, v34
	v_add_u32_e32 v36, v29, v34
	v_add_u32_e32 v37, v30, v34
	v_add_u32_e32 v34, v32, v34
	v_add_f32_e32 v5, v5, v7
	ds_read2st64_b32 v[18:19], v20 offset0:194 offset1:195
	ds_read2st64_b32 v[20:21], v20 offset0:130 offset1:131
	ds_read_b32 v12, v12
	ds_read_b32 v14, v14
	ds_read_b32 v31, v31
	ds_read_b32 v33, v33
	ds_read_b32 v35, v35
	ds_read_b32 v36, v36
	ds_read_b32 v37, v37
	ds_read_b32 v34, v34
	s_waitcnt lgkmcnt(7)
	v_add_f32_e32 v6, v6, v12
	v_add_f32_e32 v5, v5, v13
	s_waitcnt lgkmcnt(6)
	v_add_f32_e32 v6, v6, v14
	v_add_f32_e32 v5, v5, v15
	s_waitcnt lgkmcnt(5)
	v_add_f32_e32 v6, v6, v31
	s_waitcnt lgkmcnt(3)
	v_add_f32_e32 v5, v5, v35
	v_add_f32_e32 v12, v6, v33
	s_waitcnt lgkmcnt(2)
	v_add_f32_e32 v5, v5, v36
	v_add_f32_e32 v6, 0, v10
	s_waitcnt lgkmcnt(1)
	v_add_f32_e32 v5, v5, v37
	v_add_f32_e32 v6, v6, v8
	s_waitcnt lgkmcnt(0)
	v_add_f32_e32 v13, v5, v34
	v_or_b32_e32 v5, 0x200, v26
	v_add_f32_e32 v6, v6, v20
	v_or_b32_e32 v14, 0x300, v26
	v_add_f32_e32 v6, v6, v18
	v_add_u32_e32 v7, v28, v5
	v_add_u32_e32 v8, v29, v5
	v_add_u32_e32 v10, v30, v5
	v_add_u32_e32 v5, v32, v5
	v_add_u32_e32 v15, v28, v14
	v_add_u32_e32 v18, v29, v14
	v_add_u32_e32 v20, v30, v14
	v_add_u32_e32 v14, v32, v14
	ds_read_b32 v7, v7
	ds_read_b32 v8, v8
	ds_read_b32 v10, v10
	ds_read_b32 v5, v5
	ds_read_b32 v15, v15
	ds_read_b32 v18, v18
	ds_read_b32 v20, v20
	ds_read_b32 v14, v14
	s_waitcnt lgkmcnt(7)
	v_add_f32_e32 v6, v6, v7
	s_waitcnt lgkmcnt(6)
	v_add_f32_e32 v6, v6, v8
	s_waitcnt lgkmcnt(5)
	v_add_f32_e32 v6, v6, v10
	s_waitcnt lgkmcnt(4)
	v_add_f32_e32 v10, v6, v5
	v_add_f32_e32 v5, 0, v11
	v_add_f32_e32 v5, v5, v9
	v_add_f32_e32 v5, v5, v21
	v_mul_f32_e32 v6, 0xbfb8aa3b, v12
	v_add_f32_e32 v5, v5, v19
	v_exp_f32_e32 v6, v6
	s_waitcnt lgkmcnt(3)
	v_add_f32_e32 v5, v5, v15
	s_waitcnt lgkmcnt(2)
	v_add_f32_e32 v5, v5, v18
	s_waitcnt lgkmcnt(1)
	v_add_f32_e32 v5, v5, v20
	s_waitcnt lgkmcnt(0)
	v_add_f32_e32 v11, v5, v14
	v_add_f32_e32 v14, 1.0, v6
	v_add_u32_e32 v0, v106, v0
	v_ashrrev_i32_e32 v1, 31, v0
	v_ashrrev_i32_e32 v5, 31, v4
	v_lshl_add_u64 v[0:1], v[0:1], 1, s[36:37]
	v_lshlrev_b64 v[4:5], 12, v[4:5]
	v_lshl_add_u64 v[8:9], v[0:1], 0, v[4:5]
	v_lshl_add_u32 v4, v27, 2, s35
	ds_read_b128 v[4:7], v4
	v_mul_f32_e32 v19, 0xbfb8aa3b, v13
	v_exp_f32_e32 v19, v19
	s_waitcnt vmcnt(0)
; DI bf16_t f2bf(float x) { return (bf16_t)(cvt_pk(x, 0.f) & 0xffffu); }
; DI float ex2(float x) { return __builtin_amdgcn_exp2f(x); }
;     ...
;     } else if (EPI == EPI_E5B) {
;         const u32x2 ov = *(const u32x2*)((const bf16_t*)(p.ws + OFF_VT1) + vf_off((((pos + 48) >> 6) * 4 + b) * 4 + (col >> 9), col & 511, (pos + 48) & 63));
;         bf16_t* d = (bf16_t*)(p.ws + OFF_YB) + (size_t)row0 * 2048 + col;
; #pragma unroll
;         for (int e = 0; e < 4; ++e) {
;             const unsigned ob = (e & 1) ? (ov[e >> 1] & 0xffff0000u) : (ov[e >> 1] << 16);
;             const float o = __uint_as_float(ob);
;             const float gte = v[e] / (1.f + __expf(-v[e]));
;             d[(size_t)e * 2048] = f2bf(gte * o * s_aux[lrow0 + e]);
;         }
; template <int EPI, int K, int LNI>
; DI void gemm_tail_unit(const Params& p, const bf16_t* __restrict__ A, const bf16_t* __restrict__ Bt, const int un, float* s_aux) {
;     ...
; #pragma unroll
;         for (int gg = 0; gg < 2; ++gg) {
;             const int g = 2 * (w & 1) + gg;
;             float v[4];
; #pragma unroll
;             for (int e = 0; e < 4; ++e) {
;                 float sacc = 0.f;
; #pragma unroll
;                 for (int wv = 0; wv < 8; ++wv) sacc += red[((wv * 4 + tile) * 16 + 4 * g + e) * 64 + lane];
;                 v[e] = sacc;
;             }
;             const int lrow0 = i * 32 + 8 * g + 4 * h;
;             f32x2 rs[4]; float lng = 1.f, lnb = 0.f;
;             if (EPI == EPI_E5) {
;                 lng = log2f(1.f - ex2(-5.f - (float)((col0 >> 8) & 3)));
;                 const int idx_ = (((ROW0 + lrow0) % LT) + 48) & 63;
; #pragma unroll
;                 for (int e = 0; e < 4; ++e) rs[e] = (f32x2){ex2(lng * (float)(idx_ + e + 1)), 0.0625f * ex2(lng * (float)(63 - idx_ - e))};
;             }
;             if (EPI == EPI_RESID && LNI >= 0) {
;                 const f32x2* st_ = (const f32x2*)((unsigned char*)p.out + OFFO_STATS) + ROW0 + lrow0;
; #pragma unroll
;                 for (int e = 0; e < 4; ++e) rs[e] = st_[e];
;                 lng = p.ln_g[(LNI < 0 ? 0 : LNI) * 1024 + col0 + j * 32 + r]; lnb = p.ln_b[(LNI < 0 ? 0 : LNI) * 1024 + col0 + j * 32 + r];
;             }
;             epi_store<EPI, LNI>(p, ROW0 + lrow0, col0 + j * 32 + r, lrow0, v, s_aux, rs, lng, lnb);
;         }
	v_lshlrev_b32_e32 v15, 16, v16
	v_rcp_f32_e32 v18, v14
	s_nop 0
	v_mul_f32_e32 v12, v12, v18
	v_mul_f32_e32 v12, v12, v15
	s_waitcnt lgkmcnt(0)
	v_mul_f32_e32 v4, v4, v12
	v_add_f32_e32 v12, 1.0, v19
	v_cvt_pk_bf16_f32 v4, v4, s0
	global_store_short v[8:9], v4, off
	v_and_b32_e32 v4, 0xffff0000, v16
	v_rcp_f32_e32 v14, v12
	s_nop 0
	v_mul_f32_e32 v12, v13, v14
	v_mul_f32_e32 v13, 0xbfb8aa3b, v10
	v_exp_f32_e32 v13, v13
	v_mul_f32_e32 v4, v12, v4
	v_mul_f32_e32 v4, v5, v4
	v_cvt_pk_bf16_f32 v12, v4, s0
	v_add_f32_e32 v13, 1.0, v13
	v_add_co_u32_e32 v4, vcc, s42, v8
	s_add_i32 s3, s3, s14
	s_nop 0
	v_addc_co_u32_e32 v5, vcc, 0, v9, vcc
	v_mul_f32_e32 v15, 0xbfb8aa3b, v11
	v_exp_f32_e32 v15, v15
	global_store_short v[4:5], v12, off offset:-4096
	v_lshlrev_b32_e32 v12, 16, v17
	v_rcp_f32_e32 v14, v13
	s_nop 0
	v_mul_f32_e32 v10, v10, v14
	v_mul_f32_e32 v10, v10, v12
	v_mul_f32_e32 v6, v10, v6
	v_add_f32_e32 v10, 1.0, v15
	v_cvt_pk_bf16_f32 v6, v6, s0
	global_store_short v[4:5], v6, off
	v_and_b32_e32 v4, 0xffff0000, v17
	v_or_b32_e32 v12, 1, v22
	v_rcp_f32_e32 v5, v10
	s_nop 0
	v_mul_f32_e32 v5, v11, v5
	v_lshl_or_b32 v20, v12, 10, v23
	v_mul_f32_e32 v4, v5, v4
	v_add_u32_e32 v18, v90, v20
	v_mul_f32_e32 v4, v4, v7
	ds_read2st64_b32 v[6:7], v18 offset1:1
	v_lshl_or_b32 v21, v12, 3, v24
	v_cvt_pk_bf16_f32 v10, v4, s0
	v_add_co_u32_e32 v4, vcc, s43, v8
	s_waitcnt lgkmcnt(0)
	v_add_f32_e32 v16, 0, v6
	v_add_u32_e32 v6, 0x8000, v21
	v_mul_hi_i32 v12, v6, s28
	v_lshrrev_b32_e32 v13, 31, v12
	v_ashrrev_i32_e32 v12, 12, v12
	v_add_u32_e32 v12, v12, v13
	v_mul_i32_i24_e32 v13, 0xffffdff0, v12
	v_add3_u32 v14, v21, v13, s29
	v_lshrrev_b32_e32 v13, 4, v14
	v_and_b32_e32 v15, 0xfffffc, v13
	v_add_u32_e32 v12, v15, v12
	v_lshl_add_u32 v12, v12, 8, v25
	v_and_or_b32 v12, v13, 3, v12
	v_ashrrev_i32_e32 v13, 31, v12
	v_lshlrev_b32_e32 v14, 2, v14
	v_lshlrev_b64 v[12:13], 6, v[12:13]
	v_and_b32_e32 v14, 32, v14
	v_addc_co_u32_e32 v5, vcc, 0, v9, vcc
	v_or3_b32 v12, v12, v14, v67
	global_store_short v[4:5], v10, off
	v_lshl_add_u64 v[2:3], v[12:13], 4, v[2:3]
	ds_read2st64_b32 v[4:5], v18 offset0:64 offset1:65
	ds_read2st64_b32 v[8:9], v18 offset0:66 offset1:67
	ds_read2st64_b32 v[10:11], v18 offset0:2 offset1:3
	global_load_dwordx2 v[12:13], v[2:3], off
	ds_read2st64_b32 v[2:3], v18 offset0:128 offset1:129
	ds_read2st64_b32 v[14:15], v18 offset0:192 offset1:193
	s_waitcnt lgkmcnt(4)
	v_add_f32_e32 v4, v16, v4
	v_or_b32_e32 v24, 0x100, v20
	v_add_u32_e32 v22, v30, v20
	s_waitcnt lgkmcnt(1)
	v_add_f32_e32 v2, v4, v2
	s_waitcnt lgkmcnt(0)
	v_add_f32_e32 v2, v2, v14
	v_add_u32_e32 v4, v28, v20
	v_add_u32_e32 v14, v29, v20
	v_add_u32_e32 v23, v32, v20
	v_add_u32_e32 v25, v28, v24
	v_add_u32_e32 v26, v29, v24
	v_add_u32_e32 v27, v30, v24
	v_add_u32_e32 v24, v32, v24
	ds_read2st64_b32 v[16:17], v18 offset0:194 offset1:195
	ds_read2st64_b32 v[18:19], v18 offset0:130 offset1:131
	ds_read_b32 v4, v4
	ds_read_b32 v14, v14
	ds_read_b32 v22, v22
	ds_read_b32 v23, v23
	ds_read_b32 v25, v25
	ds_read_b32 v26, v26
	ds_read_b32 v27, v27
	ds_read_b32 v24, v24
	s_waitcnt lgkmcnt(7)
	v_add_f32_e32 v2, v2, v4
	s_waitcnt lgkmcnt(6)
	v_add_f32_e32 v2, v2, v14
	s_waitcnt lgkmcnt(5)
	v_add_f32_e32 v2, v2, v22
	s_waitcnt lgkmcnt(4)
	v_add_f32_e32 v14, v2, v23
	v_add_f32_e32 v2, 0, v7
	v_add_f32_e32 v2, v2, v5
	v_add_f32_e32 v2, v2, v3
	v_add_f32_e32 v2, v2, v15
	s_waitcnt lgkmcnt(3)
	v_add_f32_e32 v2, v2, v25
	s_waitcnt lgkmcnt(2)
	v_add_f32_e32 v2, v2, v26
	v_add_f32_e32 v3, 0, v10
	s_waitcnt lgkmcnt(1)
	v_add_f32_e32 v2, v2, v27
	v_add_f32_e32 v3, v3, v8
	s_waitcnt lgkmcnt(0)
	v_add_f32_e32 v15, v2, v24
	v_or_b32_e32 v2, 0x200, v20
	v_add_f32_e32 v3, v3, v18
	v_or_b32_e32 v8, 0x300, v20
	v_add_f32_e32 v3, v3, v16
	v_add_u32_e32 v4, v28, v2
	v_add_u32_e32 v5, v29, v2
	v_add_u32_e32 v7, v30, v2
	v_add_u32_e32 v2, v32, v2
	v_add_u32_e32 v10, v28, v8
	v_add_u32_e32 v16, v29, v8
	v_add_u32_e32 v18, v30, v8
	v_add_u32_e32 v8, v32, v8
	ds_read_b32 v4, v4
	ds_read_b32 v5, v5
	ds_read_b32 v7, v7
	ds_read_b32 v2, v2
	ds_read_b32 v10, v10
	ds_read_b32 v16, v16
	ds_read_b32 v18, v18
	ds_read_b32 v8, v8
	s_waitcnt lgkmcnt(7)
	v_add_f32_e32 v3, v3, v4
	s_waitcnt lgkmcnt(6)
	v_add_f32_e32 v3, v3, v5
	s_waitcnt lgkmcnt(5)
	v_add_f32_e32 v3, v3, v7
	s_waitcnt lgkmcnt(4)
	v_add_f32_e32 v20, v3, v2
	v_mul_f32_e32 v3, 0xbfb8aa3b, v14
	v_exp_f32_e32 v3, v3
	v_add_f32_e32 v2, 0, v11
	v_add_f32_e32 v2, v2, v9
	v_add_f32_e32 v2, v2, v19
	v_add_f32_e32 v2, v2, v17
	v_add_f32_e32 v9, 1.0, v3
	s_waitcnt lgkmcnt(3)
	v_add_f32_e32 v2, v2, v10
	s_waitcnt lgkmcnt(2)
	v_add_f32_e32 v2, v2, v16
	s_waitcnt lgkmcnt(1)
	v_add_f32_e32 v2, v2, v18
	v_ashrrev_i32_e32 v7, 31, v6
	s_waitcnt lgkmcnt(0)
	v_add_f32_e32 v8, v2, v8
	v_lshlrev_b64 v[2:3], 12, v[6:7]
	v_lshl_add_u64 v[4:5], v[0:1], 0, v[2:3]
	v_lshl_add_u32 v0, v21, 2, s35
	ds_read_b128 v[0:3], v0
	v_mul_f32_e32 v10, 0xbfb8aa3b, v15
	v_exp_f32_e32 v10, v10
	v_rcp_f32_e32 v7, v9
	s_nop 0
	v_mul_f32_e32 v7, v14, v7
	s_cmp_lt_i32 s45, 32
	s_waitcnt vmcnt(0)
	v_lshlrev_b32_e32 v6, 16, v12
	v_mul_f32_e32 v6, v7, v6
	s_waitcnt lgkmcnt(0)
	v_mul_f32_e32 v0, v0, v6
	v_add_f32_e32 v6, 1.0, v10
	v_cvt_pk_bf16_f32 v0, v0, s0
	global_store_short v[4:5], v0, off
	v_and_b32_e32 v0, 0xffff0000, v12
	v_rcp_f32_e32 v7, v6
	s_nop 0
	v_mul_f32_e32 v6, v15, v7
	v_mul_f32_e32 v7, 0xbfb8aa3b, v20
	v_exp_f32_e32 v7, v7
	v_mul_f32_e32 v0, v6, v0
	v_mul_f32_e32 v0, v1, v0
	v_cvt_pk_bf16_f32 v6, v0, s0
	v_add_f32_e32 v7, 1.0, v7
	v_add_co_u32_e32 v0, vcc, s42, v4
	s_nop 0
	s_nop 0
	v_addc_co_u32_e32 v1, vcc, 0, v5, vcc
	v_mul_f32_e32 v10, 0xbfb8aa3b, v8
	v_exp_f32_e32 v10, v10
	global_store_short v[0:1], v6, off offset:-4096
	v_lshlrev_b32_e32 v6, 16, v13
	v_rcp_f32_e32 v9, v7
	s_nop 0
	v_mul_f32_e32 v7, v20, v9
	v_mul_f32_e32 v6, v7, v6
	v_mul_f32_e32 v2, v6, v2
	v_add_f32_e32 v6, 1.0, v10
	v_cvt_pk_bf16_f32 v2, v2, s0
	global_store_short v[0:1], v2, off
	v_and_b32_e32 v0, 0xffff0000, v13
	v_rcp_f32_e32 v1, v6
	s_nop 0
	v_mul_f32_e32 v1, v8, v1
	v_mul_f32_e32 v0, v1, v0
	v_mul_f32_e32 v0, v0, v3
	v_cvt_pk_bf16_f32 v2, v0, s0
	v_add_co_u32_e32 v0, vcc, 0x3000, v4
	s_nop 1
	v_addc_co_u32_e32 v1, vcc, 0, v5, vcc
	global_store_short v[0:1], v2, off
	s_barrier
	s_cbranch_scc0 .LBB0_1649
